# UP epilogue: per-row sum-of-squares loads issued before the final MFMAs / accumulator->LDS writes (epilogue de-serialisation)
# baseline (speedup 1.0000x reference)
.LBB0_338:
	s_lshr_b32 s8, s13, 2
	s_and_b32 s10, s16, 56
	s_and_b32 s8, s8, 0x1ffffc0
	s_or_b32 s10, s10, s3
	s_or_b32 s8, s10, s8
	s_lshl_b32 s8, s8, 7
	s_lshl_b64 s[24:25], s[8:9], 11
	v_lshl_add_u64 v[78:79], v[68:69], 0, s[24:25]
	v_add_co_u32_e32 v80, vcc, s18, v78
	s_and_b32 s10, s14, 0xf80
	s_nop 0
	v_addc_co_u32_e32 v81, vcc, 0, v79, vcc
	s_lshl_b32 s26, s10, 11
	s_mov_b32 s27, s9
	v_add_co_u32_e32 v82, vcc, s19, v78
	v_lshl_add_u64 v[76:77], v[70:71], 0, s[26:27]
	s_nop 0
	v_addc_co_u32_e32 v83, vcc, 0, v79, vcc
	v_add_co_u32_e32 v84, vcc, s18, v76
	global_load_dwordx4 v[2:5], v[78:79], off
	global_load_dwordx4 v[6:9], v[80:81], off
	v_addc_co_u32_e32 v85, vcc, 0, v77, vcc
	v_add_co_u32_e32 v86, vcc, s19, v76
	global_load_dwordx4 v[10:13], v[82:83], off
	global_load_dwordx4 v[14:17], v[76:77], off
	v_addc_co_u32_e32 v87, vcc, 0, v77, vcc
	global_load_dwordx4 v[18:21], v[84:85], off
	global_load_dwordx4 v[22:25], v[86:87], off
	v_add_co_u32_e32 v88, vcc, s20, v76
	s_nop 1
	v_addc_co_u32_e32 v89, vcc, 0, v77, vcc
	global_load_dwordx4 v[26:29], v[88:89], off
	v_add_co_u32_e32 v90, vcc, s20, v78
	s_nop 1
	v_addc_co_u32_e32 v91, vcc, 0, v79, vcc
	global_load_dwordx4 v[30:33], v[90:91], off
	global_load_dwordx4 v[148:151], v[76:77], off offset:128
	global_load_dwordx4 v[152:155], v[84:85], off offset:128
	global_load_dwordx4 v[156:159], v[86:87], off offset:128
	global_load_dwordx4 v[160:163], v[88:89], off offset:128
	global_load_dwordx4 v[164:167], v[78:79], off offset:128
	global_load_dwordx4 v[168:171], v[80:81], off offset:128
	global_load_dwordx4 v[172:175], v[82:83], off offset:128
	global_load_dwordx4 v[176:179], v[90:91], off offset:128
	s_waitcnt vmcnt(12)
	ds_write_b128 v1, v[14:17] offset:36864
	s_waitcnt vmcnt(11)
	ds_write_b128 v1, v[18:21] offset:41472
	s_waitcnt vmcnt(10)
	ds_write_b128 v1, v[22:25] offset:46080
	s_waitcnt vmcnt(9)
	ds_write_b128 v1, v[26:29] offset:50688
	ds_write_b128 v1, v[2:5]
	ds_write_b128 v1, v[6:9] offset:4608
	ds_write_b128 v1, v[10:13] offset:9216
	s_waitcnt vmcnt(8)
	ds_write_b128 v1, v[30:33] offset:13824
	s_waitcnt lgkmcnt(0)
	s_barrier
	global_load_dwordx4 v[180:183], v[80:81], off offset:256
	global_load_dwordx4 v[184:187], v[82:83], off offset:256
	global_load_dwordx4 v[188:191], v[78:79], off offset:256
	global_load_dwordx4 v[192:195], v[76:77], off offset:256
	global_load_dwordx4 v[196:199], v[90:91], off offset:256
	global_load_dwordx4 v[200:203], v[84:85], off offset:256
	global_load_dwordx4 v[204:207], v[86:87], off offset:256
	global_load_dwordx4 v[208:211], v[88:89], off offset:256
	ds_read_b128 v[18:21], v72
	ds_read_b128 v[34:37], v73 offset:36864
	ds_read_b128 v[212:215], v72 offset:32
	ds_read_b128 v[216:219], v73 offset:36896
	ds_read_b128 v[50:53], v73 offset:41472
	ds_read_b128 v[220:223], v73 offset:41504
	ds_read_b128 v[54:57], v72 offset:4608
	ds_read_b128 v[224:227], v72 offset:4640
	s_waitcnt lgkmcnt(6)
	v_mfma_f32_32x32x16_bf16 v[2:17], v[18:21], v[34:37], 0
	s_waitcnt lgkmcnt(3)
	v_mfma_f32_32x32x16_bf16 v[18:33], v[18:21], v[50:53], 0
	s_waitcnt lgkmcnt(1)
	v_mfma_f32_32x32x16_bf16 v[34:49], v[54:57], v[34:37], 0
	v_mfma_f32_32x32x16_bf16 v[50:65], v[54:57], v[50:53], 0
	v_mfma_f32_32x32x16_bf16 v[2:17], v[212:215], v[216:219], v[2:17]
	v_mfma_f32_32x32x16_bf16 v[18:33], v[212:215], v[220:223], v[18:33]
	s_waitcnt lgkmcnt(0)
	v_mfma_f32_32x32x16_bf16 v[34:49], v[224:227], v[216:219], v[34:49]
	v_mfma_f32_32x32x16_bf16 v[50:65], v[224:227], v[220:223], v[50:65]
	ds_read_b128 v[212:215], v72 offset:64
	ds_read_b128 v[216:219], v73 offset:36928
	ds_read_b128 v[220:223], v72 offset:96
	ds_read_b128 v[224:227], v73 offset:36960
	ds_read_b128 v[228:231], v73 offset:41536
	ds_read_b128 v[232:235], v73 offset:41568
	s_waitcnt lgkmcnt(4)
	v_mfma_f32_32x32x16_bf16 v[2:17], v[212:215], v[216:219], v[2:17]
	s_waitcnt lgkmcnt(1)
	v_mfma_f32_32x32x16_bf16 v[18:33], v[212:215], v[228:231], v[18:33]
	ds_read_b128 v[212:215], v72 offset:4672
	ds_read_b128 v[236:239], v72 offset:4704
	s_waitcnt vmcnt(11)
	ds_write_b128 v1, v[164:167] offset:18432
	s_waitcnt vmcnt(10)
	ds_write_b128 v1, v[168:171] offset:23040
	s_waitcnt vmcnt(9)
	ds_write_b128 v1, v[172:175] offset:27648
	s_waitcnt vmcnt(8)
	ds_write_b128 v1, v[176:179] offset:32256
	ds_write_b128 v1, v[148:151] offset:55296
	ds_write_b128 v1, v[152:155] offset:59904
	ds_write_b128 v1, v[156:159] offset:64512
	ds_write_b128 v92, v[160:163] offset:32256
	global_load_dwordx4 v[148:151], v[80:81], off offset:384
	global_load_dwordx4 v[152:155], v[82:83], off offset:384
	global_load_dwordx4 v[156:159], v[78:79], off offset:384
	global_load_dwordx4 v[160:163], v[76:77], off offset:384
	global_load_dwordx4 v[164:167], v[90:91], off offset:384
	global_load_dwordx4 v[168:171], v[84:85], off offset:384
	global_load_dwordx4 v[172:175], v[86:87], off offset:384
	global_load_dwordx4 v[176:179], v[88:89], off offset:384
	s_waitcnt lgkmcnt(0)
	s_barrier
	v_mfma_f32_32x32x16_bf16 v[34:49], v[212:215], v[216:219], v[34:49]
	v_mfma_f32_32x32x16_bf16 v[50:65], v[212:215], v[228:231], v[50:65]
	v_mfma_f32_32x32x16_bf16 v[2:17], v[220:223], v[224:227], v[2:17]
	v_mfma_f32_32x32x16_bf16 v[18:33], v[220:223], v[232:235], v[18:33]
	v_mfma_f32_32x32x16_bf16 v[34:49], v[236:239], v[224:227], v[34:49]
	v_mfma_f32_32x32x16_bf16 v[50:65], v[236:239], v[232:235], v[50:65]
	ds_read_b128 v[212:215], v72 offset:18432
	ds_read_b128 v[216:219], v73 offset:55296
	ds_read_b128 v[220:223], v72 offset:18464
	ds_read_b128 v[224:227], v73 offset:55328
	ds_read_b128 v[228:231], v73 offset:59904
	ds_read_b128 v[232:235], v73 offset:59936
	s_waitcnt lgkmcnt(4)
	v_mfma_f32_32x32x16_bf16 v[2:17], v[212:215], v[216:219], v[2:17]
	s_waitcnt lgkmcnt(1)
	v_mfma_f32_32x32x16_bf16 v[18:33], v[212:215], v[228:231], v[18:33]
	ds_read_b128 v[212:215], v72 offset:23040
	ds_read_b128 v[236:239], v72 offset:23072
	s_waitcnt lgkmcnt(1)
	v_mfma_f32_32x32x16_bf16 v[34:49], v[212:215], v[216:219], v[34:49]
	v_mfma_f32_32x32x16_bf16 v[50:65], v[212:215], v[228:231], v[50:65]
	v_mfma_f32_32x32x16_bf16 v[2:17], v[220:223], v[224:227], v[2:17]
	v_mfma_f32_32x32x16_bf16 v[18:33], v[220:223], v[232:235], v[18:33]
	s_waitcnt lgkmcnt(0)
	v_mfma_f32_32x32x16_bf16 v[34:49], v[236:239], v[224:227], v[34:49]
	ds_read_b128 v[212:215], v72 offset:18496
	ds_read_b128 v[216:219], v73 offset:55360
	ds_read_b128 v[220:223], v72 offset:18528
	ds_read_b128 v[224:227], v73 offset:55392
	v_mfma_f32_32x32x16_bf16 v[50:65], v[236:239], v[232:235], v[50:65]
	ds_read_b128 v[228:231], v73 offset:59968
	ds_read_b128 v[232:235], v73 offset:60000
	s_waitcnt lgkmcnt(4)
	v_mfma_f32_32x32x16_bf16 v[2:17], v[212:215], v[216:219], v[2:17]
	s_waitcnt lgkmcnt(1)
	v_mfma_f32_32x32x16_bf16 v[18:33], v[212:215], v[228:231], v[18:33]
	ds_read_b128 v[212:215], v72 offset:23104
	ds_read_b128 v[236:239], v72 offset:23136
	s_waitcnt vmcnt(13)
	ds_write_b128 v1, v[188:191]
	ds_write_b128 v1, v[180:183] offset:4608
	ds_write_b128 v1, v[184:187] offset:9216
	s_waitcnt vmcnt(11)
	ds_write_b128 v1, v[196:199] offset:13824
	ds_write_b128 v1, v[192:195] offset:36864
	s_waitcnt vmcnt(10)
	ds_write_b128 v1, v[200:203] offset:41472
	s_waitcnt vmcnt(9)
	ds_write_b128 v1, v[204:207] offset:46080
	s_waitcnt vmcnt(8)
	ds_write_b128 v1, v[208:211] offset:50688
	global_load_dwordx4 v[180:183], v[80:81], off offset:512
	global_load_dwordx4 v[184:187], v[82:83], off offset:512
	global_load_dwordx4 v[188:191], v[78:79], off offset:512
	global_load_dwordx4 v[192:195], v[76:77], off offset:512
	global_load_dwordx4 v[196:199], v[90:91], off offset:512
	global_load_dwordx4 v[200:203], v[84:85], off offset:512
	global_load_dwordx4 v[204:207], v[86:87], off offset:512
	global_load_dwordx4 v[208:211], v[88:89], off offset:512
	s_waitcnt lgkmcnt(0)
	s_barrier
	v_mfma_f32_32x32x16_bf16 v[34:49], v[212:215], v[216:219], v[34:49]
	v_mfma_f32_32x32x16_bf16 v[50:65], v[212:215], v[228:231], v[50:65]
	v_mfma_f32_32x32x16_bf16 v[2:17], v[220:223], v[224:227], v[2:17]
	v_mfma_f32_32x32x16_bf16 v[18:33], v[220:223], v[232:235], v[18:33]
	v_mfma_f32_32x32x16_bf16 v[34:49], v[236:239], v[224:227], v[34:49]
	v_mfma_f32_32x32x16_bf16 v[50:65], v[236:239], v[232:235], v[50:65]
	ds_read_b128 v[212:215], v72
	ds_read_b128 v[216:219], v73 offset:36864
	ds_read_b128 v[220:223], v72 offset:32
	ds_read_b128 v[224:227], v73 offset:36896
	ds_read_b128 v[228:231], v73 offset:41472
	ds_read_b128 v[232:235], v73 offset:41504
	s_waitcnt lgkmcnt(4)
	v_mfma_f32_32x32x16_bf16 v[2:17], v[212:215], v[216:219], v[2:17]
	s_waitcnt lgkmcnt(1)
	v_mfma_f32_32x32x16_bf16 v[18:33], v[212:215], v[228:231], v[18:33]
	ds_read_b128 v[212:215], v72 offset:4608
	ds_read_b128 v[236:239], v72 offset:4640
	s_waitcnt lgkmcnt(1)
	v_mfma_f32_32x32x16_bf16 v[34:49], v[212:215], v[216:219], v[34:49]
	v_mfma_f32_32x32x16_bf16 v[50:65], v[212:215], v[228:231], v[50:65]
	v_mfma_f32_32x32x16_bf16 v[2:17], v[220:223], v[224:227], v[2:17]
	v_mfma_f32_32x32x16_bf16 v[18:33], v[220:223], v[232:235], v[18:33]
	s_waitcnt lgkmcnt(0)
	v_mfma_f32_32x32x16_bf16 v[34:49], v[236:239], v[224:227], v[34:49]
	ds_read_b128 v[212:215], v72 offset:64
	ds_read_b128 v[216:219], v73 offset:36928
	ds_read_b128 v[220:223], v72 offset:96
	ds_read_b128 v[224:227], v73 offset:36960
	v_mfma_f32_32x32x16_bf16 v[50:65], v[236:239], v[232:235], v[50:65]
	ds_read_b128 v[228:231], v73 offset:41536
	ds_read_b128 v[232:235], v73 offset:41568
	s_waitcnt lgkmcnt(4)
	v_mfma_f32_32x32x16_bf16 v[2:17], v[212:215], v[216:219], v[2:17]
	s_waitcnt lgkmcnt(1)
	v_mfma_f32_32x32x16_bf16 v[18:33], v[212:215], v[228:231], v[18:33]
	ds_read_b128 v[212:215], v72 offset:4672
	ds_read_b128 v[236:239], v72 offset:4704
	s_waitcnt vmcnt(13)
	ds_write_b128 v1, v[156:159] offset:18432
	ds_write_b128 v1, v[148:151] offset:23040
	ds_write_b128 v1, v[152:155] offset:27648
	s_waitcnt vmcnt(11)
	ds_write_b128 v1, v[164:167] offset:32256
	ds_write_b128 v1, v[160:163] offset:55296
	s_waitcnt vmcnt(10)
	ds_write_b128 v1, v[168:171] offset:59904
	s_waitcnt vmcnt(9)
	ds_write_b128 v1, v[172:175] offset:64512
	s_waitcnt vmcnt(8)
	ds_write_b128 v92, v[176:179] offset:32256
	global_load_dwordx4 v[148:151], v[80:81], off offset:640
	global_load_dwordx4 v[152:155], v[82:83], off offset:640
	global_load_dwordx4 v[156:159], v[78:79], off offset:640
	global_load_dwordx4 v[160:163], v[76:77], off offset:640
	global_load_dwordx4 v[164:167], v[90:91], off offset:640
	global_load_dwordx4 v[168:171], v[84:85], off offset:640
	global_load_dwordx4 v[172:175], v[86:87], off offset:640
	global_load_dwordx4 v[176:179], v[88:89], off offset:640
	s_waitcnt lgkmcnt(0)
	s_barrier
	v_mfma_f32_32x32x16_bf16 v[34:49], v[212:215], v[216:219], v[34:49]
	v_mfma_f32_32x32x16_bf16 v[50:65], v[212:215], v[228:231], v[50:65]
	v_mfma_f32_32x32x16_bf16 v[2:17], v[220:223], v[224:227], v[2:17]
	v_mfma_f32_32x32x16_bf16 v[18:33], v[220:223], v[232:235], v[18:33]
	v_mfma_f32_32x32x16_bf16 v[34:49], v[236:239], v[224:227], v[34:49]
	v_mfma_f32_32x32x16_bf16 v[50:65], v[236:239], v[232:235], v[50:65]
	ds_read_b128 v[212:215], v72 offset:18432
	ds_read_b128 v[216:219], v73 offset:55296
	ds_read_b128 v[220:223], v72 offset:18464
	ds_read_b128 v[224:227], v73 offset:55328
	ds_read_b128 v[228:231], v73 offset:59904
	ds_read_b128 v[232:235], v73 offset:59936
	s_waitcnt lgkmcnt(4)
	v_mfma_f32_32x32x16_bf16 v[2:17], v[212:215], v[216:219], v[2:17]
	s_waitcnt lgkmcnt(1)
	v_mfma_f32_32x32x16_bf16 v[18:33], v[212:215], v[228:231], v[18:33]
	ds_read_b128 v[212:215], v72 offset:23040
	ds_read_b128 v[236:239], v72 offset:23072
	s_waitcnt lgkmcnt(1)
	v_mfma_f32_32x32x16_bf16 v[34:49], v[212:215], v[216:219], v[34:49]
	v_mfma_f32_32x32x16_bf16 v[50:65], v[212:215], v[228:231], v[50:65]
	v_mfma_f32_32x32x16_bf16 v[2:17], v[220:223], v[224:227], v[2:17]
	v_mfma_f32_32x32x16_bf16 v[18:33], v[220:223], v[232:235], v[18:33]
	s_waitcnt lgkmcnt(0)
	v_mfma_f32_32x32x16_bf16 v[34:49], v[236:239], v[224:227], v[34:49]
	ds_read_b128 v[212:215], v72 offset:18496
	ds_read_b128 v[216:219], v73 offset:55360
	ds_read_b128 v[220:223], v72 offset:18528
	ds_read_b128 v[224:227], v73 offset:55392
	v_mfma_f32_32x32x16_bf16 v[50:65], v[236:239], v[232:235], v[50:65]
	ds_read_b128 v[228:231], v73 offset:59968
	ds_read_b128 v[232:235], v73 offset:60000
	s_waitcnt lgkmcnt(4)
	v_mfma_f32_32x32x16_bf16 v[2:17], v[212:215], v[216:219], v[2:17]
	s_waitcnt lgkmcnt(1)
	v_mfma_f32_32x32x16_bf16 v[18:33], v[212:215], v[228:231], v[18:33]
	ds_read_b128 v[212:215], v72 offset:23104
	ds_read_b128 v[236:239], v72 offset:23136
	s_waitcnt vmcnt(13)
	ds_write_b128 v1, v[188:191]
	ds_write_b128 v1, v[180:183] offset:4608
	ds_write_b128 v1, v[184:187] offset:9216
	s_waitcnt vmcnt(11)
	ds_write_b128 v1, v[196:199] offset:13824
	ds_write_b128 v1, v[192:195] offset:36864
	s_waitcnt vmcnt(10)
	ds_write_b128 v1, v[200:203] offset:41472
	s_waitcnt vmcnt(9)
	ds_write_b128 v1, v[204:207] offset:46080
	s_waitcnt vmcnt(8)
	ds_write_b128 v1, v[208:211] offset:50688
	global_load_dwordx4 v[180:183], v[80:81], off offset:768
	global_load_dwordx4 v[184:187], v[82:83], off offset:768
	global_load_dwordx4 v[188:191], v[78:79], off offset:768
	global_load_dwordx4 v[192:195], v[76:77], off offset:768
	global_load_dwordx4 v[196:199], v[90:91], off offset:768
	global_load_dwordx4 v[200:203], v[84:85], off offset:768
	global_load_dwordx4 v[204:207], v[86:87], off offset:768
	global_load_dwordx4 v[208:211], v[88:89], off offset:768
	s_waitcnt lgkmcnt(0)
	s_barrier
	v_mfma_f32_32x32x16_bf16 v[34:49], v[212:215], v[216:219], v[34:49]
	v_mfma_f32_32x32x16_bf16 v[50:65], v[212:215], v[228:231], v[50:65]
	v_mfma_f32_32x32x16_bf16 v[2:17], v[220:223], v[224:227], v[2:17]
	v_mfma_f32_32x32x16_bf16 v[18:33], v[220:223], v[232:235], v[18:33]
	v_mfma_f32_32x32x16_bf16 v[34:49], v[236:239], v[224:227], v[34:49]
	v_mfma_f32_32x32x16_bf16 v[50:65], v[236:239], v[232:235], v[50:65]
	ds_read_b128 v[212:215], v72
	ds_read_b128 v[216:219], v73 offset:36864
	ds_read_b128 v[220:223], v72 offset:32
	ds_read_b128 v[224:227], v73 offset:36896
	ds_read_b128 v[228:231], v73 offset:41472
	ds_read_b128 v[232:235], v73 offset:41504
	s_waitcnt lgkmcnt(4)
	v_mfma_f32_32x32x16_bf16 v[2:17], v[212:215], v[216:219], v[2:17]
	s_waitcnt lgkmcnt(1)
	v_mfma_f32_32x32x16_bf16 v[18:33], v[212:215], v[228:231], v[18:33]
	ds_read_b128 v[212:215], v72 offset:4608
	ds_read_b128 v[236:239], v72 offset:4640
	s_waitcnt lgkmcnt(1)
	v_mfma_f32_32x32x16_bf16 v[34:49], v[212:215], v[216:219], v[34:49]
	v_mfma_f32_32x32x16_bf16 v[50:65], v[212:215], v[228:231], v[50:65]
	v_mfma_f32_32x32x16_bf16 v[2:17], v[220:223], v[224:227], v[2:17]
	v_mfma_f32_32x32x16_bf16 v[18:33], v[220:223], v[232:235], v[18:33]
	s_waitcnt lgkmcnt(0)
	v_mfma_f32_32x32x16_bf16 v[34:49], v[236:239], v[224:227], v[34:49]
	ds_read_b128 v[212:215], v72 offset:64
	ds_read_b128 v[216:219], v73 offset:36928
	ds_read_b128 v[220:223], v72 offset:96
	ds_read_b128 v[224:227], v73 offset:36960
	v_mfma_f32_32x32x16_bf16 v[50:65], v[236:239], v[232:235], v[50:65]
	ds_read_b128 v[228:231], v73 offset:41536
	ds_read_b128 v[232:235], v73 offset:41568
	s_waitcnt lgkmcnt(4)
	v_mfma_f32_32x32x16_bf16 v[2:17], v[212:215], v[216:219], v[2:17]
	s_waitcnt lgkmcnt(1)
	v_mfma_f32_32x32x16_bf16 v[18:33], v[212:215], v[228:231], v[18:33]
	ds_read_b128 v[212:215], v72 offset:4672
	ds_read_b128 v[236:239], v72 offset:4704
	s_waitcnt vmcnt(13)
	ds_write_b128 v1, v[156:159] offset:18432
	ds_write_b128 v1, v[148:151] offset:23040
	ds_write_b128 v1, v[152:155] offset:27648
	s_waitcnt vmcnt(11)
	ds_write_b128 v1, v[164:167] offset:32256
	ds_write_b128 v1, v[160:163] offset:55296
	s_waitcnt vmcnt(10)
	ds_write_b128 v1, v[168:171] offset:59904
	s_waitcnt vmcnt(9)
	ds_write_b128 v1, v[172:175] offset:64512
	s_waitcnt vmcnt(8)
	ds_write_b128 v92, v[176:179] offset:32256
	global_load_dwordx4 v[148:151], v[80:81], off offset:896
	global_load_dwordx4 v[152:155], v[82:83], off offset:896
	global_load_dwordx4 v[156:159], v[78:79], off offset:896
	global_load_dwordx4 v[160:163], v[76:77], off offset:896
	global_load_dwordx4 v[164:167], v[90:91], off offset:896
	global_load_dwordx4 v[168:171], v[84:85], off offset:896
	global_load_dwordx4 v[172:175], v[86:87], off offset:896
	global_load_dwordx4 v[176:179], v[88:89], off offset:896
	s_waitcnt lgkmcnt(0)
	s_barrier
	v_mfma_f32_32x32x16_bf16 v[34:49], v[212:215], v[216:219], v[34:49]
	v_mfma_f32_32x32x16_bf16 v[50:65], v[212:215], v[228:231], v[50:65]
	v_mfma_f32_32x32x16_bf16 v[2:17], v[220:223], v[224:227], v[2:17]
	v_mfma_f32_32x32x16_bf16 v[18:33], v[220:223], v[232:235], v[18:33]
	v_mfma_f32_32x32x16_bf16 v[34:49], v[236:239], v[224:227], v[34:49]
	v_mfma_f32_32x32x16_bf16 v[50:65], v[236:239], v[232:235], v[50:65]
	ds_read_b128 v[212:215], v72 offset:18432
	ds_read_b128 v[216:219], v73 offset:55296
	ds_read_b128 v[220:223], v72 offset:18464
	ds_read_b128 v[224:227], v73 offset:55328
	ds_read_b128 v[228:231], v73 offset:59904
	ds_read_b128 v[232:235], v73 offset:59936
	s_waitcnt lgkmcnt(4)
	v_mfma_f32_32x32x16_bf16 v[2:17], v[212:215], v[216:219], v[2:17]
	s_waitcnt lgkmcnt(1)
	v_mfma_f32_32x32x16_bf16 v[18:33], v[212:215], v[228:231], v[18:33]
	ds_read_b128 v[212:215], v72 offset:23040
	ds_read_b128 v[236:239], v72 offset:23072
	s_waitcnt lgkmcnt(1)
	v_mfma_f32_32x32x16_bf16 v[34:49], v[212:215], v[216:219], v[34:49]
	v_mfma_f32_32x32x16_bf16 v[50:65], v[212:215], v[228:231], v[50:65]
	v_mfma_f32_32x32x16_bf16 v[2:17], v[220:223], v[224:227], v[2:17]
	v_mfma_f32_32x32x16_bf16 v[18:33], v[220:223], v[232:235], v[18:33]
	s_waitcnt lgkmcnt(0)
	v_mfma_f32_32x32x16_bf16 v[34:49], v[236:239], v[224:227], v[34:49]
	ds_read_b128 v[212:215], v72 offset:18496
	ds_read_b128 v[216:219], v73 offset:55360
	ds_read_b128 v[220:223], v72 offset:18528
	ds_read_b128 v[224:227], v73 offset:55392
	v_mfma_f32_32x32x16_bf16 v[50:65], v[236:239], v[232:235], v[50:65]
	ds_read_b128 v[228:231], v73 offset:59968
	ds_read_b128 v[232:235], v73 offset:60000
	s_waitcnt lgkmcnt(4)
	v_mfma_f32_32x32x16_bf16 v[2:17], v[212:215], v[216:219], v[2:17]
	s_waitcnt lgkmcnt(1)
	v_mfma_f32_32x32x16_bf16 v[18:33], v[212:215], v[228:231], v[18:33]
	ds_read_b128 v[212:215], v72 offset:23104
	ds_read_b128 v[236:239], v72 offset:23136
	s_waitcnt vmcnt(13)
	ds_write_b128 v1, v[188:191]
	ds_write_b128 v1, v[180:183] offset:4608
	ds_write_b128 v1, v[184:187] offset:9216
	s_waitcnt vmcnt(11)
	ds_write_b128 v1, v[196:199] offset:13824
	ds_write_b128 v1, v[192:195] offset:36864
	s_waitcnt vmcnt(10)
	ds_write_b128 v1, v[200:203] offset:41472
	s_waitcnt vmcnt(9)
	ds_write_b128 v1, v[204:207] offset:46080
	s_waitcnt vmcnt(8)
	ds_write_b128 v1, v[208:211] offset:50688
	global_load_dwordx4 v[180:183], v[80:81], off offset:1024
	global_load_dwordx4 v[184:187], v[82:83], off offset:1024
	global_load_dwordx4 v[188:191], v[78:79], off offset:1024
	global_load_dwordx4 v[192:195], v[76:77], off offset:1024
	global_load_dwordx4 v[196:199], v[90:91], off offset:1024
	global_load_dwordx4 v[200:203], v[84:85], off offset:1024
	global_load_dwordx4 v[204:207], v[86:87], off offset:1024
	global_load_dwordx4 v[208:211], v[88:89], off offset:1024
	s_waitcnt lgkmcnt(0)
	s_barrier
	v_mfma_f32_32x32x16_bf16 v[34:49], v[212:215], v[216:219], v[34:49]
	v_mfma_f32_32x32x16_bf16 v[50:65], v[212:215], v[228:231], v[50:65]
	v_mfma_f32_32x32x16_bf16 v[2:17], v[220:223], v[224:227], v[2:17]
	v_mfma_f32_32x32x16_bf16 v[18:33], v[220:223], v[232:235], v[18:33]
	v_mfma_f32_32x32x16_bf16 v[34:49], v[236:239], v[224:227], v[34:49]
	v_mfma_f32_32x32x16_bf16 v[50:65], v[236:239], v[232:235], v[50:65]
	ds_read_b128 v[212:215], v72
	ds_read_b128 v[216:219], v73 offset:36864
	ds_read_b128 v[220:223], v72 offset:32
	ds_read_b128 v[224:227], v73 offset:36896
	ds_read_b128 v[228:231], v73 offset:41472
	ds_read_b128 v[232:235], v73 offset:41504
	s_waitcnt lgkmcnt(4)
	v_mfma_f32_32x32x16_bf16 v[2:17], v[212:215], v[216:219], v[2:17]
	s_waitcnt lgkmcnt(1)
	v_mfma_f32_32x32x16_bf16 v[18:33], v[212:215], v[228:231], v[18:33]
	ds_read_b128 v[212:215], v72 offset:4608
	ds_read_b128 v[236:239], v72 offset:4640
	s_waitcnt lgkmcnt(1)
	v_mfma_f32_32x32x16_bf16 v[34:49], v[212:215], v[216:219], v[34:49]
	v_mfma_f32_32x32x16_bf16 v[50:65], v[212:215], v[228:231], v[50:65]
	v_mfma_f32_32x32x16_bf16 v[2:17], v[220:223], v[224:227], v[2:17]
	v_mfma_f32_32x32x16_bf16 v[18:33], v[220:223], v[232:235], v[18:33]
	s_waitcnt lgkmcnt(0)
	v_mfma_f32_32x32x16_bf16 v[34:49], v[236:239], v[224:227], v[34:49]
	ds_read_b128 v[212:215], v72 offset:64
	ds_read_b128 v[216:219], v73 offset:36928
	ds_read_b128 v[220:223], v72 offset:96
	ds_read_b128 v[224:227], v73 offset:36960
	v_mfma_f32_32x32x16_bf16 v[50:65], v[236:239], v[232:235], v[50:65]
	ds_read_b128 v[228:231], v73 offset:41536
	ds_read_b128 v[232:235], v73 offset:41568
	s_waitcnt lgkmcnt(4)
	v_mfma_f32_32x32x16_bf16 v[2:17], v[212:215], v[216:219], v[2:17]
	s_waitcnt lgkmcnt(1)
	v_mfma_f32_32x32x16_bf16 v[18:33], v[212:215], v[228:231], v[18:33]
	ds_read_b128 v[212:215], v72 offset:4672
	ds_read_b128 v[236:239], v72 offset:4704
	s_waitcnt vmcnt(13)
	ds_write_b128 v1, v[156:159] offset:18432
	ds_write_b128 v1, v[148:151] offset:23040
	ds_write_b128 v1, v[152:155] offset:27648
	s_waitcnt vmcnt(11)
	ds_write_b128 v1, v[164:167] offset:32256
	ds_write_b128 v1, v[160:163] offset:55296
	s_waitcnt vmcnt(10)
	ds_write_b128 v1, v[168:171] offset:59904
	s_waitcnt vmcnt(9)
	ds_write_b128 v1, v[172:175] offset:64512
	s_waitcnt vmcnt(8)
	ds_write_b128 v92, v[176:179] offset:32256
	global_load_dwordx4 v[148:151], v[80:81], off offset:1152
	global_load_dwordx4 v[152:155], v[82:83], off offset:1152
	global_load_dwordx4 v[156:159], v[78:79], off offset:1152
	global_load_dwordx4 v[160:163], v[76:77], off offset:1152
	global_load_dwordx4 v[164:167], v[90:91], off offset:1152
	global_load_dwordx4 v[168:171], v[84:85], off offset:1152
	global_load_dwordx4 v[172:175], v[86:87], off offset:1152
	global_load_dwordx4 v[176:179], v[88:89], off offset:1152
	s_waitcnt lgkmcnt(0)
	s_barrier
	v_mfma_f32_32x32x16_bf16 v[34:49], v[212:215], v[216:219], v[34:49]
	v_mfma_f32_32x32x16_bf16 v[50:65], v[212:215], v[228:231], v[50:65]
	v_mfma_f32_32x32x16_bf16 v[2:17], v[220:223], v[224:227], v[2:17]
	v_mfma_f32_32x32x16_bf16 v[18:33], v[220:223], v[232:235], v[18:33]
	v_mfma_f32_32x32x16_bf16 v[34:49], v[236:239], v[224:227], v[34:49]
	v_mfma_f32_32x32x16_bf16 v[50:65], v[236:239], v[232:235], v[50:65]
	ds_read_b128 v[212:215], v72 offset:18432
	ds_read_b128 v[216:219], v73 offset:55296
	ds_read_b128 v[220:223], v72 offset:18464
	ds_read_b128 v[224:227], v73 offset:55328
	ds_read_b128 v[228:231], v73 offset:59904
	ds_read_b128 v[232:235], v73 offset:59936
	s_waitcnt lgkmcnt(4)
	v_mfma_f32_32x32x16_bf16 v[2:17], v[212:215], v[216:219], v[2:17]
	s_waitcnt lgkmcnt(1)
	v_mfma_f32_32x32x16_bf16 v[18:33], v[212:215], v[228:231], v[18:33]
	ds_read_b128 v[212:215], v72 offset:23040
	ds_read_b128 v[236:239], v72 offset:23072
	s_waitcnt lgkmcnt(1)
	v_mfma_f32_32x32x16_bf16 v[34:49], v[212:215], v[216:219], v[34:49]
	v_mfma_f32_32x32x16_bf16 v[50:65], v[212:215], v[228:231], v[50:65]
	v_mfma_f32_32x32x16_bf16 v[2:17], v[220:223], v[224:227], v[2:17]
	v_mfma_f32_32x32x16_bf16 v[18:33], v[220:223], v[232:235], v[18:33]
	s_waitcnt lgkmcnt(0)
	v_mfma_f32_32x32x16_bf16 v[34:49], v[236:239], v[224:227], v[34:49]
	ds_read_b128 v[212:215], v72 offset:18496
	ds_read_b128 v[216:219], v73 offset:55360
	ds_read_b128 v[220:223], v72 offset:18528
	ds_read_b128 v[224:227], v73 offset:55392
	v_mfma_f32_32x32x16_bf16 v[50:65], v[236:239], v[232:235], v[50:65]
	ds_read_b128 v[228:231], v73 offset:59968
	ds_read_b128 v[232:235], v73 offset:60000
	s_waitcnt lgkmcnt(4)
	v_mfma_f32_32x32x16_bf16 v[2:17], v[212:215], v[216:219], v[2:17]
	s_waitcnt lgkmcnt(1)
	v_mfma_f32_32x32x16_bf16 v[18:33], v[212:215], v[228:231], v[18:33]
	ds_read_b128 v[212:215], v72 offset:23104
	ds_read_b128 v[236:239], v72 offset:23136
	s_waitcnt vmcnt(13)
	ds_write_b128 v1, v[188:191]
	ds_write_b128 v1, v[180:183] offset:4608
	ds_write_b128 v1, v[184:187] offset:9216
	s_waitcnt vmcnt(11)
	ds_write_b128 v1, v[196:199] offset:13824
	ds_write_b128 v1, v[192:195] offset:36864
	s_waitcnt vmcnt(10)
	ds_write_b128 v1, v[200:203] offset:41472
	s_waitcnt vmcnt(9)
	ds_write_b128 v1, v[204:207] offset:46080
	s_waitcnt vmcnt(8)
	ds_write_b128 v1, v[208:211] offset:50688
	global_load_dwordx4 v[180:183], v[80:81], off offset:1280
	global_load_dwordx4 v[184:187], v[82:83], off offset:1280
	global_load_dwordx4 v[188:191], v[78:79], off offset:1280
	global_load_dwordx4 v[192:195], v[76:77], off offset:1280
	global_load_dwordx4 v[196:199], v[90:91], off offset:1280
	global_load_dwordx4 v[200:203], v[84:85], off offset:1280
	global_load_dwordx4 v[204:207], v[86:87], off offset:1280
	global_load_dwordx4 v[208:211], v[88:89], off offset:1280
	s_waitcnt lgkmcnt(0)
	s_barrier
	v_mfma_f32_32x32x16_bf16 v[34:49], v[212:215], v[216:219], v[34:49]
	v_mfma_f32_32x32x16_bf16 v[50:65], v[212:215], v[228:231], v[50:65]
	v_mfma_f32_32x32x16_bf16 v[2:17], v[220:223], v[224:227], v[2:17]
	v_mfma_f32_32x32x16_bf16 v[18:33], v[220:223], v[232:235], v[18:33]
	v_mfma_f32_32x32x16_bf16 v[34:49], v[236:239], v[224:227], v[34:49]
	v_mfma_f32_32x32x16_bf16 v[50:65], v[236:239], v[232:235], v[50:65]
	ds_read_b128 v[212:215], v72
	ds_read_b128 v[216:219], v73 offset:36864
	ds_read_b128 v[220:223], v72 offset:32
	ds_read_b128 v[224:227], v73 offset:36896
	ds_read_b128 v[228:231], v73 offset:41472
	ds_read_b128 v[232:235], v73 offset:41504
	s_waitcnt lgkmcnt(4)
	v_mfma_f32_32x32x16_bf16 v[2:17], v[212:215], v[216:219], v[2:17]
	s_waitcnt lgkmcnt(1)
	v_mfma_f32_32x32x16_bf16 v[18:33], v[212:215], v[228:231], v[18:33]
	ds_read_b128 v[212:215], v72 offset:4608
	ds_read_b128 v[236:239], v72 offset:4640
	s_waitcnt lgkmcnt(1)
	v_mfma_f32_32x32x16_bf16 v[34:49], v[212:215], v[216:219], v[34:49]
	v_mfma_f32_32x32x16_bf16 v[50:65], v[212:215], v[228:231], v[50:65]
	v_mfma_f32_32x32x16_bf16 v[2:17], v[220:223], v[224:227], v[2:17]
	v_mfma_f32_32x32x16_bf16 v[18:33], v[220:223], v[232:235], v[18:33]
	s_waitcnt lgkmcnt(0)
	v_mfma_f32_32x32x16_bf16 v[34:49], v[236:239], v[224:227], v[34:49]
	ds_read_b128 v[212:215], v72 offset:64
	ds_read_b128 v[216:219], v73 offset:36928
	ds_read_b128 v[220:223], v72 offset:96
	ds_read_b128 v[224:227], v73 offset:36960
	v_mfma_f32_32x32x16_bf16 v[50:65], v[236:239], v[232:235], v[50:65]
	ds_read_b128 v[228:231], v73 offset:41536
	ds_read_b128 v[232:235], v73 offset:41568
	s_waitcnt lgkmcnt(4)
	v_mfma_f32_32x32x16_bf16 v[2:17], v[212:215], v[216:219], v[2:17]
	s_waitcnt lgkmcnt(1)
	v_mfma_f32_32x32x16_bf16 v[18:33], v[212:215], v[228:231], v[18:33]
	ds_read_b128 v[212:215], v72 offset:4672
	ds_read_b128 v[236:239], v72 offset:4704
	s_waitcnt vmcnt(13)
	ds_write_b128 v1, v[156:159] offset:18432
	ds_write_b128 v1, v[148:151] offset:23040
	ds_write_b128 v1, v[152:155] offset:27648
	s_waitcnt vmcnt(11)
	ds_write_b128 v1, v[164:167] offset:32256
	ds_write_b128 v1, v[160:163] offset:55296
	s_waitcnt vmcnt(10)
	ds_write_b128 v1, v[168:171] offset:59904
	s_waitcnt vmcnt(9)
	ds_write_b128 v1, v[172:175] offset:64512
	s_waitcnt vmcnt(8)
	ds_write_b128 v92, v[176:179] offset:32256
	global_load_dwordx4 v[148:151], v[80:81], off offset:1408
	global_load_dwordx4 v[152:155], v[82:83], off offset:1408
	global_load_dwordx4 v[156:159], v[78:79], off offset:1408
	global_load_dwordx4 v[160:163], v[76:77], off offset:1408
	global_load_dwordx4 v[164:167], v[90:91], off offset:1408
	global_load_dwordx4 v[168:171], v[84:85], off offset:1408
	global_load_dwordx4 v[172:175], v[86:87], off offset:1408
	global_load_dwordx4 v[176:179], v[88:89], off offset:1408
	s_waitcnt lgkmcnt(0)
	s_barrier
	v_mfma_f32_32x32x16_bf16 v[34:49], v[212:215], v[216:219], v[34:49]
	v_mfma_f32_32x32x16_bf16 v[50:65], v[212:215], v[228:231], v[50:65]
	v_mfma_f32_32x32x16_bf16 v[2:17], v[220:223], v[224:227], v[2:17]
	v_mfma_f32_32x32x16_bf16 v[18:33], v[220:223], v[232:235], v[18:33]
	v_mfma_f32_32x32x16_bf16 v[34:49], v[236:239], v[224:227], v[34:49]
	v_mfma_f32_32x32x16_bf16 v[50:65], v[236:239], v[232:235], v[50:65]
	ds_read_b128 v[212:215], v72 offset:18432
	ds_read_b128 v[216:219], v73 offset:55296
	ds_read_b128 v[220:223], v72 offset:18464
	ds_read_b128 v[224:227], v73 offset:55328
	ds_read_b128 v[228:231], v73 offset:59904
	ds_read_b128 v[232:235], v73 offset:59936
	s_waitcnt lgkmcnt(4)
	v_mfma_f32_32x32x16_bf16 v[2:17], v[212:215], v[216:219], v[2:17]
	s_waitcnt lgkmcnt(1)
	v_mfma_f32_32x32x16_bf16 v[18:33], v[212:215], v[228:231], v[18:33]
	ds_read_b128 v[212:215], v72 offset:23040
	ds_read_b128 v[236:239], v72 offset:23072
	s_waitcnt lgkmcnt(1)
	v_mfma_f32_32x32x16_bf16 v[34:49], v[212:215], v[216:219], v[34:49]
	v_mfma_f32_32x32x16_bf16 v[50:65], v[212:215], v[228:231], v[50:65]
	v_mfma_f32_32x32x16_bf16 v[2:17], v[220:223], v[224:227], v[2:17]
	v_mfma_f32_32x32x16_bf16 v[18:33], v[220:223], v[232:235], v[18:33]
	s_waitcnt lgkmcnt(0)
	v_mfma_f32_32x32x16_bf16 v[34:49], v[236:239], v[224:227], v[34:49]
	ds_read_b128 v[212:215], v72 offset:18496
	ds_read_b128 v[216:219], v73 offset:55360
	ds_read_b128 v[220:223], v72 offset:18528
	ds_read_b128 v[224:227], v73 offset:55392
	v_mfma_f32_32x32x16_bf16 v[50:65], v[236:239], v[232:235], v[50:65]
	ds_read_b128 v[228:231], v73 offset:59968
	ds_read_b128 v[232:235], v73 offset:60000
	s_waitcnt lgkmcnt(4)
	v_mfma_f32_32x32x16_bf16 v[2:17], v[212:215], v[216:219], v[2:17]
	s_waitcnt lgkmcnt(1)
	v_mfma_f32_32x32x16_bf16 v[18:33], v[212:215], v[228:231], v[18:33]
	ds_read_b128 v[212:215], v72 offset:23104
	ds_read_b128 v[236:239], v72 offset:23136
	s_waitcnt vmcnt(13)
	ds_write_b128 v1, v[188:191]
	ds_write_b128 v1, v[180:183] offset:4608
	ds_write_b128 v1, v[184:187] offset:9216
	s_waitcnt vmcnt(11)
	ds_write_b128 v1, v[196:199] offset:13824
	ds_write_b128 v1, v[192:195] offset:36864
	s_waitcnt vmcnt(10)
	ds_write_b128 v1, v[200:203] offset:41472
	s_waitcnt vmcnt(9)
	ds_write_b128 v1, v[204:207] offset:46080
	s_waitcnt vmcnt(8)
	ds_write_b128 v1, v[208:211] offset:50688
	global_load_dwordx4 v[180:183], v[80:81], off offset:1536
	global_load_dwordx4 v[184:187], v[82:83], off offset:1536
	global_load_dwordx4 v[188:191], v[78:79], off offset:1536
	global_load_dwordx4 v[192:195], v[76:77], off offset:1536
	global_load_dwordx4 v[196:199], v[90:91], off offset:1536
	global_load_dwordx4 v[200:203], v[84:85], off offset:1536
	global_load_dwordx4 v[204:207], v[86:87], off offset:1536
	global_load_dwordx4 v[208:211], v[88:89], off offset:1536
	s_waitcnt lgkmcnt(0)
	s_barrier
	v_mfma_f32_32x32x16_bf16 v[34:49], v[212:215], v[216:219], v[34:49]
	v_mfma_f32_32x32x16_bf16 v[50:65], v[212:215], v[228:231], v[50:65]
	v_mfma_f32_32x32x16_bf16 v[2:17], v[220:223], v[224:227], v[2:17]
	v_mfma_f32_32x32x16_bf16 v[18:33], v[220:223], v[232:235], v[18:33]
	v_mfma_f32_32x32x16_bf16 v[34:49], v[236:239], v[224:227], v[34:49]
	v_mfma_f32_32x32x16_bf16 v[50:65], v[236:239], v[232:235], v[50:65]
	ds_read_b128 v[212:215], v72
	ds_read_b128 v[216:219], v73 offset:36864
	ds_read_b128 v[220:223], v72 offset:32
	ds_read_b128 v[224:227], v73 offset:36896
	ds_read_b128 v[228:231], v73 offset:41472
	ds_read_b128 v[232:235], v73 offset:41504
	s_waitcnt lgkmcnt(4)
	v_mfma_f32_32x32x16_bf16 v[2:17], v[212:215], v[216:219], v[2:17]
	s_waitcnt lgkmcnt(1)
	v_mfma_f32_32x32x16_bf16 v[18:33], v[212:215], v[228:231], v[18:33]
	ds_read_b128 v[212:215], v72 offset:4608
	ds_read_b128 v[236:239], v72 offset:4640
	s_waitcnt lgkmcnt(1)
	v_mfma_f32_32x32x16_bf16 v[34:49], v[212:215], v[216:219], v[34:49]
	v_mfma_f32_32x32x16_bf16 v[50:65], v[212:215], v[228:231], v[50:65]
	v_mfma_f32_32x32x16_bf16 v[2:17], v[220:223], v[224:227], v[2:17]
	v_mfma_f32_32x32x16_bf16 v[18:33], v[220:223], v[232:235], v[18:33]
	s_waitcnt lgkmcnt(0)
	v_mfma_f32_32x32x16_bf16 v[34:49], v[236:239], v[224:227], v[34:49]
	ds_read_b128 v[212:215], v72 offset:64
	ds_read_b128 v[216:219], v73 offset:36928
	ds_read_b128 v[220:223], v72 offset:96
	ds_read_b128 v[224:227], v73 offset:36960
	v_mfma_f32_32x32x16_bf16 v[50:65], v[236:239], v[232:235], v[50:65]
	ds_read_b128 v[228:231], v73 offset:41536
	ds_read_b128 v[232:235], v73 offset:41568
	s_waitcnt lgkmcnt(4)
	v_mfma_f32_32x32x16_bf16 v[2:17], v[212:215], v[216:219], v[2:17]
	s_waitcnt lgkmcnt(1)
	v_mfma_f32_32x32x16_bf16 v[18:33], v[212:215], v[228:231], v[18:33]
	ds_read_b128 v[212:215], v72 offset:4672
	ds_read_b128 v[236:239], v72 offset:4704
	s_waitcnt vmcnt(13)
	ds_write_b128 v1, v[156:159] offset:18432
	ds_write_b128 v1, v[148:151] offset:23040
	ds_write_b128 v1, v[152:155] offset:27648
	s_waitcnt vmcnt(11)
	ds_write_b128 v1, v[164:167] offset:32256
	ds_write_b128 v1, v[160:163] offset:55296
	s_waitcnt vmcnt(10)
	ds_write_b128 v1, v[168:171] offset:59904
	s_waitcnt vmcnt(9)
	ds_write_b128 v1, v[172:175] offset:64512
	s_waitcnt vmcnt(8)
	ds_write_b128 v92, v[176:179] offset:32256
	global_load_dwordx4 v[148:151], v[80:81], off offset:1664
	global_load_dwordx4 v[152:155], v[82:83], off offset:1664
	global_load_dwordx4 v[156:159], v[78:79], off offset:1664
	global_load_dwordx4 v[160:163], v[76:77], off offset:1664
	global_load_dwordx4 v[164:167], v[90:91], off offset:1664
	global_load_dwordx4 v[168:171], v[84:85], off offset:1664
	global_load_dwordx4 v[172:175], v[86:87], off offset:1664
	global_load_dwordx4 v[176:179], v[88:89], off offset:1664
	s_waitcnt lgkmcnt(0)
	s_barrier
	v_mfma_f32_32x32x16_bf16 v[34:49], v[212:215], v[216:219], v[34:49]
	v_mfma_f32_32x32x16_bf16 v[50:65], v[212:215], v[228:231], v[50:65]
	v_mfma_f32_32x32x16_bf16 v[2:17], v[220:223], v[224:227], v[2:17]
	v_mfma_f32_32x32x16_bf16 v[18:33], v[220:223], v[232:235], v[18:33]
	v_mfma_f32_32x32x16_bf16 v[34:49], v[236:239], v[224:227], v[34:49]
	v_mfma_f32_32x32x16_bf16 v[50:65], v[236:239], v[232:235], v[50:65]
	ds_read_b128 v[212:215], v72 offset:18432
	ds_read_b128 v[216:219], v73 offset:55296
	ds_read_b128 v[220:223], v72 offset:18464
	ds_read_b128 v[224:227], v73 offset:55328
	ds_read_b128 v[228:231], v73 offset:59904
	ds_read_b128 v[232:235], v73 offset:59936
	s_waitcnt lgkmcnt(4)
	v_mfma_f32_32x32x16_bf16 v[2:17], v[212:215], v[216:219], v[2:17]
	s_waitcnt lgkmcnt(1)
	v_mfma_f32_32x32x16_bf16 v[18:33], v[212:215], v[228:231], v[18:33]
	ds_read_b128 v[212:215], v72 offset:23040
	ds_read_b128 v[236:239], v72 offset:23072
	s_waitcnt lgkmcnt(1)
	v_mfma_f32_32x32x16_bf16 v[34:49], v[212:215], v[216:219], v[34:49]
	v_mfma_f32_32x32x16_bf16 v[50:65], v[212:215], v[228:231], v[50:65]
	v_mfma_f32_32x32x16_bf16 v[2:17], v[220:223], v[224:227], v[2:17]
	v_mfma_f32_32x32x16_bf16 v[18:33], v[220:223], v[232:235], v[18:33]
	s_waitcnt lgkmcnt(0)
	v_mfma_f32_32x32x16_bf16 v[34:49], v[236:239], v[224:227], v[34:49]
	ds_read_b128 v[212:215], v72 offset:18496
	ds_read_b128 v[216:219], v73 offset:55360
	ds_read_b128 v[220:223], v72 offset:18528
	ds_read_b128 v[224:227], v73 offset:55392
	v_mfma_f32_32x32x16_bf16 v[50:65], v[236:239], v[232:235], v[50:65]
	ds_read_b128 v[228:231], v73 offset:59968
	ds_read_b128 v[232:235], v73 offset:60000
	s_waitcnt lgkmcnt(4)
	v_mfma_f32_32x32x16_bf16 v[2:17], v[212:215], v[216:219], v[2:17]
	s_waitcnt lgkmcnt(1)
	v_mfma_f32_32x32x16_bf16 v[18:33], v[212:215], v[228:231], v[18:33]
	ds_read_b128 v[212:215], v72 offset:23104
	ds_read_b128 v[236:239], v72 offset:23136
	s_waitcnt vmcnt(13)
	ds_write_b128 v1, v[188:191]
	ds_write_b128 v1, v[180:183] offset:4608
	ds_write_b128 v1, v[184:187] offset:9216
	s_waitcnt vmcnt(11)
	ds_write_b128 v1, v[196:199] offset:13824
	ds_write_b128 v1, v[192:195] offset:36864
	s_waitcnt vmcnt(10)
	ds_write_b128 v1, v[200:203] offset:41472
	s_waitcnt vmcnt(9)
	ds_write_b128 v1, v[204:207] offset:46080
	s_waitcnt vmcnt(8)
	ds_write_b128 v1, v[208:211] offset:50688
	global_load_dwordx4 v[180:183], v[80:81], off offset:1792
	global_load_dwordx4 v[184:187], v[82:83], off offset:1792
	global_load_dwordx4 v[188:191], v[78:79], off offset:1792
	global_load_dwordx4 v[192:195], v[76:77], off offset:1792
	global_load_dwordx4 v[196:199], v[90:91], off offset:1792
	global_load_dwordx4 v[200:203], v[84:85], off offset:1792
	global_load_dwordx4 v[204:207], v[86:87], off offset:1792
	global_load_dwordx4 v[208:211], v[88:89], off offset:1792
	s_waitcnt lgkmcnt(0)
	s_barrier
	v_mfma_f32_32x32x16_bf16 v[34:49], v[212:215], v[216:219], v[34:49]
	v_mfma_f32_32x32x16_bf16 v[50:65], v[212:215], v[228:231], v[50:65]
	v_mfma_f32_32x32x16_bf16 v[2:17], v[220:223], v[224:227], v[2:17]
	v_mfma_f32_32x32x16_bf16 v[18:33], v[220:223], v[232:235], v[18:33]
	v_mfma_f32_32x32x16_bf16 v[34:49], v[236:239], v[224:227], v[34:49]
	v_mfma_f32_32x32x16_bf16 v[50:65], v[236:239], v[232:235], v[50:65]
	ds_read_b128 v[212:215], v72
	ds_read_b128 v[216:219], v73 offset:36864
	ds_read_b128 v[220:223], v72 offset:32
	ds_read_b128 v[224:227], v73 offset:36896
	ds_read_b128 v[228:231], v73 offset:41472
	ds_read_b128 v[232:235], v73 offset:41504
	s_waitcnt lgkmcnt(4)
	v_mfma_f32_32x32x16_bf16 v[2:17], v[212:215], v[216:219], v[2:17]
	s_waitcnt lgkmcnt(1)
	v_mfma_f32_32x32x16_bf16 v[18:33], v[212:215], v[228:231], v[18:33]
	ds_read_b128 v[212:215], v72 offset:4608
	ds_read_b128 v[236:239], v72 offset:4640
	s_waitcnt lgkmcnt(1)
	v_mfma_f32_32x32x16_bf16 v[34:49], v[212:215], v[216:219], v[34:49]
	v_mfma_f32_32x32x16_bf16 v[50:65], v[212:215], v[228:231], v[50:65]
	v_mfma_f32_32x32x16_bf16 v[2:17], v[220:223], v[224:227], v[2:17]
	v_mfma_f32_32x32x16_bf16 v[18:33], v[220:223], v[232:235], v[18:33]
	s_waitcnt lgkmcnt(0)
	v_mfma_f32_32x32x16_bf16 v[34:49], v[236:239], v[224:227], v[34:49]
	ds_read_b128 v[212:215], v72 offset:64
	ds_read_b128 v[216:219], v73 offset:36928
	ds_read_b128 v[220:223], v72 offset:96
	ds_read_b128 v[224:227], v73 offset:36960
	v_mfma_f32_32x32x16_bf16 v[50:65], v[236:239], v[232:235], v[50:65]
	ds_read_b128 v[228:231], v73 offset:41536
	ds_read_b128 v[232:235], v73 offset:41568
	s_waitcnt lgkmcnt(4)
	v_mfma_f32_32x32x16_bf16 v[2:17], v[212:215], v[216:219], v[2:17]
	s_waitcnt lgkmcnt(1)
	v_mfma_f32_32x32x16_bf16 v[18:33], v[212:215], v[228:231], v[18:33]
	ds_read_b128 v[212:215], v72 offset:4672
	ds_read_b128 v[236:239], v72 offset:4704
	s_waitcnt vmcnt(13)
	ds_write_b128 v1, v[156:159] offset:18432
	ds_write_b128 v1, v[148:151] offset:23040
	ds_write_b128 v1, v[152:155] offset:27648
	s_waitcnt vmcnt(11)
	ds_write_b128 v1, v[164:167] offset:32256
	ds_write_b128 v1, v[160:163] offset:55296
	s_waitcnt vmcnt(10)
	ds_write_b128 v1, v[168:171] offset:59904
	s_waitcnt vmcnt(9)
	ds_write_b128 v1, v[172:175] offset:64512
	s_waitcnt vmcnt(8)
	ds_write_b128 v92, v[176:179] offset:32256
	s_waitcnt lgkmcnt(0)
	s_barrier
	global_load_dwordx4 v[148:151], v[80:81], off offset:1920
	s_nop 0
	global_load_dwordx4 v[80:83], v[82:83], off offset:1920
	s_nop 0
	global_load_dwordx4 v[152:155], v[78:79], off offset:1920
	s_nop 0
	global_load_dwordx4 v[76:79], v[76:77], off offset:1920
	s_nop 0
	global_load_dwordx4 v[156:159], v[90:91], off offset:1920
	global_load_dwordx4 v[160:163], v[84:85], off offset:1920
	s_nop 0
	global_load_dwordx4 v[84:87], v[86:87], off offset:1920
	s_nop 0
	global_load_dwordx4 v[88:91], v[88:89], off offset:1920
	v_mfma_f32_32x32x16_bf16 v[34:49], v[212:215], v[216:219], v[34:49]
	v_mfma_f32_32x32x16_bf16 v[50:65], v[212:215], v[228:231], v[50:65]
	v_mfma_f32_32x32x16_bf16 v[2:17], v[220:223], v[224:227], v[2:17]
	v_mfma_f32_32x32x16_bf16 v[18:33], v[220:223], v[232:235], v[18:33]
	v_mfma_f32_32x32x16_bf16 v[34:49], v[236:239], v[224:227], v[34:49]
	v_mfma_f32_32x32x16_bf16 v[50:65], v[236:239], v[232:235], v[50:65]
	ds_read_b128 v[164:167], v72 offset:18432
	ds_read_b128 v[168:171], v73 offset:55296
	ds_read_b128 v[172:175], v72 offset:18464
	ds_read_b128 v[176:179], v73 offset:55328
	ds_read_b128 v[212:215], v73 offset:59904
	ds_read_b128 v[216:219], v73 offset:59936
	s_waitcnt lgkmcnt(4)
	v_mfma_f32_32x32x16_bf16 v[2:17], v[164:167], v[168:171], v[2:17]
	s_waitcnt lgkmcnt(1)
	v_mfma_f32_32x32x16_bf16 v[18:33], v[164:167], v[212:215], v[18:33]
	ds_read_b128 v[164:167], v72 offset:23040
	ds_read_b128 v[220:223], v72 offset:23072
	s_waitcnt lgkmcnt(1)
	v_mfma_f32_32x32x16_bf16 v[34:49], v[164:167], v[168:171], v[34:49]
	v_mfma_f32_32x32x16_bf16 v[50:65], v[164:167], v[212:215], v[50:65]
	v_mfma_f32_32x32x16_bf16 v[2:17], v[172:175], v[176:179], v[2:17]
	v_mfma_f32_32x32x16_bf16 v[18:33], v[172:175], v[216:219], v[18:33]
	s_waitcnt lgkmcnt(0)
	v_mfma_f32_32x32x16_bf16 v[34:49], v[220:223], v[176:179], v[34:49]
	ds_read_b128 v[164:167], v72 offset:18496
	ds_read_b128 v[168:171], v73 offset:55360
	ds_read_b128 v[172:175], v72 offset:18528
	ds_read_b128 v[176:179], v73 offset:55392
	v_mfma_f32_32x32x16_bf16 v[50:65], v[220:223], v[216:219], v[50:65]
	ds_read_b128 v[212:215], v73 offset:59968
	ds_read_b128 v[216:219], v73 offset:60000
	s_waitcnt lgkmcnt(4)
	v_mfma_f32_32x32x16_bf16 v[2:17], v[164:167], v[168:171], v[2:17]
	s_waitcnt lgkmcnt(1)
	v_mfma_f32_32x32x16_bf16 v[18:33], v[164:167], v[212:215], v[18:33]
	ds_read_b128 v[164:167], v72 offset:23104
	ds_read_b128 v[220:223], v72 offset:23136
	s_waitcnt vmcnt(13)
	ds_write_b128 v1, v[188:191]
	ds_write_b128 v1, v[180:183] offset:4608
	ds_write_b128 v1, v[184:187] offset:9216
	s_waitcnt vmcnt(11)
	ds_write_b128 v1, v[196:199] offset:13824
	ds_write_b128 v1, v[192:195] offset:36864
	s_waitcnt vmcnt(10)
	ds_write_b128 v1, v[200:203] offset:41472
	s_waitcnt vmcnt(9)
	ds_write_b128 v1, v[204:207] offset:46080
	s_waitcnt vmcnt(8)
	ds_write_b128 v1, v[208:211] offset:50688
	s_waitcnt lgkmcnt(0)
	s_barrier
	v_mfma_f32_32x32x16_bf16 v[34:49], v[164:167], v[168:171], v[34:49]
	v_mfma_f32_32x32x16_bf16 v[50:65], v[164:167], v[212:215], v[50:65]
	v_mfma_f32_32x32x16_bf16 v[2:17], v[172:175], v[176:179], v[2:17]
	v_mfma_f32_32x32x16_bf16 v[18:33], v[172:175], v[216:219], v[18:33]
	v_mfma_f32_32x32x16_bf16 v[34:49], v[220:223], v[176:179], v[34:49]
	v_mfma_f32_32x32x16_bf16 v[50:65], v[220:223], v[216:219], v[50:65]
	ds_read_b128 v[164:167], v72
	ds_read_b128 v[168:171], v73 offset:36864
	ds_read_b128 v[172:175], v72 offset:32
	ds_read_b128 v[176:179], v73 offset:36896
	ds_read_b128 v[180:183], v73 offset:41472
	ds_read_b128 v[184:187], v73 offset:41504
	s_waitcnt lgkmcnt(4)
	v_mfma_f32_32x32x16_bf16 v[2:17], v[164:167], v[168:171], v[2:17]
	s_waitcnt lgkmcnt(1)
	v_mfma_f32_32x32x16_bf16 v[18:33], v[164:167], v[180:183], v[18:33]
	ds_read_b128 v[164:167], v72 offset:4608
	ds_read_b128 v[188:191], v72 offset:4640
	s_waitcnt lgkmcnt(1)
	v_mfma_f32_32x32x16_bf16 v[34:49], v[164:167], v[168:171], v[34:49]
	v_mfma_f32_32x32x16_bf16 v[50:65], v[164:167], v[180:183], v[50:65]
	v_mfma_f32_32x32x16_bf16 v[2:17], v[172:175], v[176:179], v[2:17]
	v_mfma_f32_32x32x16_bf16 v[18:33], v[172:175], v[184:187], v[18:33]
	s_waitcnt lgkmcnt(0)
	v_mfma_f32_32x32x16_bf16 v[34:49], v[188:191], v[176:179], v[34:49]
	ds_read_b128 v[164:167], v72 offset:64
	ds_read_b128 v[168:171], v73 offset:36928
	ds_read_b128 v[172:175], v72 offset:96
	ds_read_b128 v[176:179], v73 offset:36960
	v_mfma_f32_32x32x16_bf16 v[50:65], v[188:191], v[184:187], v[50:65]
	ds_read_b128 v[180:183], v73 offset:41536
	ds_read_b128 v[184:187], v73 offset:41568
	s_waitcnt lgkmcnt(4)
	v_mfma_f32_32x32x16_bf16 v[2:17], v[164:167], v[168:171], v[2:17]
	s_waitcnt lgkmcnt(1)
	v_mfma_f32_32x32x16_bf16 v[18:33], v[164:167], v[180:183], v[18:33]
	ds_read_b128 v[164:167], v72 offset:4672
	ds_read_b128 v[188:191], v72 offset:4704
	s_waitcnt vmcnt(5)
	ds_write_b128 v1, v[152:155] offset:18432
	ds_write_b128 v1, v[148:151] offset:23040
	ds_write_b128 v1, v[80:83] offset:27648
	s_waitcnt vmcnt(3)
	ds_write_b128 v1, v[156:159] offset:32256
	ds_write_b128 v1, v[76:79] offset:55296
	s_waitcnt vmcnt(2)
	ds_write_b128 v1, v[160:163] offset:59904
	s_waitcnt vmcnt(1)
	ds_write_b128 v1, v[84:87] offset:64512
	s_waitcnt vmcnt(0)
	ds_write_b128 v92, v[88:91] offset:32256
	s_waitcnt lgkmcnt(0)
	s_barrier
	v_mfma_f32_32x32x16_bf16 v[34:49], v[164:167], v[168:171], v[34:49]
	v_mfma_f32_32x32x16_bf16 v[50:65], v[164:167], v[180:183], v[50:65]
	v_mfma_f32_32x32x16_bf16 v[2:17], v[172:175], v[176:179], v[2:17]
	v_mfma_f32_32x32x16_bf16 v[18:33], v[172:175], v[184:187], v[18:33]
	v_mfma_f32_32x32x16_bf16 v[34:49], v[188:191], v[176:179], v[34:49]
	v_mfma_f32_32x32x16_bf16 v[50:65], v[188:191], v[184:187], v[50:65]
	ds_read_b128 v[76:79], v72 offset:18432
	ds_read_b128 v[80:83], v73 offset:55296
	ds_read_b128 v[84:87], v72 offset:18464
	ds_read_b128 v[88:91], v73 offset:55328
	ds_read_b128 v[148:151], v73 offset:59904
	ds_read_b128 v[152:155], v73 offset:59936
	v_or_b32_e32 v66, s8, v93
	s_waitcnt lgkmcnt(4)
	v_mfma_f32_32x32x16_bf16 v[2:17], v[76:79], v[80:83], v[2:17]
	s_lshl_b32 s10, s10, 1
	s_mov_b32 s11, s9
	s_add_i32 s13, s13, s12
	s_add_i32 s14, s14, s15
	s_add_i32 s16, s16, s17
	s_cmpk_lt_u32 s13, 0x400
	s_waitcnt lgkmcnt(1)
	v_mfma_f32_32x32x16_bf16 v[18:33], v[76:79], v[148:151], v[18:33]
	ds_read_b128 v[76:79], v72 offset:23040
	ds_read_b128 v[156:159], v72 offset:23072
	s_waitcnt lgkmcnt(1)
	v_mfma_f32_32x32x16_bf16 v[34:49], v[76:79], v[80:83], v[34:49]
	v_mfma_f32_32x32x16_bf16 v[50:65], v[76:79], v[148:151], v[50:65]
	v_mfma_f32_32x32x16_bf16 v[2:17], v[84:87], v[88:91], v[2:17]
	v_mfma_f32_32x32x16_bf16 v[18:33], v[84:87], v[152:155], v[18:33]
	s_waitcnt lgkmcnt(0)
	v_mfma_f32_32x32x16_bf16 v[34:49], v[156:159], v[88:91], v[34:49]
	ds_read_b128 v[76:79], v72 offset:18496
	ds_read_b128 v[80:83], v73 offset:55360
	ds_read_b128 v[84:87], v72 offset:18528
	ds_read_b128 v[88:91], v73 offset:55392
	v_mfma_f32_32x32x16_bf16 v[50:65], v[156:159], v[152:155], v[50:65]
	ds_read_b128 v[148:151], v73 offset:59968
	ds_read_b128 v[152:155], v73 offset:60000
	s_waitcnt lgkmcnt(4)
	v_mfma_f32_32x32x16_bf16 v[2:17], v[76:79], v[80:83], v[2:17]
	s_waitcnt lgkmcnt(1)
	v_mfma_f32_32x32x16_bf16 v[18:33], v[76:79], v[148:151], v[18:33]
	ds_read_b128 v[76:79], v72 offset:23104
	ds_read_b128 v[156:159], v72 offset:23136
	s_waitcnt lgkmcnt(0)
	s_barrier
	v_lshlrev_b32_e32 v168, 2, v66
	global_load_dword v160, v168, s[6:7]
	global_load_dword v161, v168, s[6:7] offset:64
	global_load_dword v162, v168, s[6:7] offset:128
	global_load_dword v163, v168, s[6:7] offset:192
	global_load_dword v164, v168, s[6:7] offset:256
	global_load_dword v165, v168, s[6:7] offset:320
	global_load_dword v166, v168, s[6:7] offset:384
	global_load_dword v167, v168, s[6:7] offset:448
	v_mfma_f32_32x32x16_bf16 v[34:49], v[76:79], v[80:83], v[34:49]
	v_mfma_f32_32x32x16_bf16 v[50:65], v[76:79], v[148:151], v[50:65]
	v_mfma_f32_32x32x16_bf16 v[2:17], v[84:87], v[88:91], v[2:17]
	v_mfma_f32_32x32x16_bf16 v[18:33], v[84:87], v[152:155], v[18:33]
	v_mfma_f32_32x32x16_bf16 v[34:49], v[156:159], v[88:91], v[34:49]
	s_nop 10
	ds_write2_b32 v101, v2, v18 offset1:32
	v_mfma_f32_32x32x16_bf16 v[50:65], v[156:159], v[152:155], v[50:65]
	s_nop 11
	ds_write2_b32 v132, v34, v50 offset0:32 offset1:64
	ds_write2_b32 v101, v3, v19 offset0:129 offset1:161
	ds_write2_b32 v132, v35, v51 offset0:161 offset1:193
	ds_write2_b32 v133, v4, v20 offset0:2 offset1:34
	ds_write2_b32 v134, v36, v52 offset0:34 offset1:66
	ds_write2_b32 v133, v5, v21 offset0:131 offset1:163
	ds_write2_b32 v134, v37, v53 offset0:163 offset1:195
	ds_write2_b32 v135, v6, v22 offset0:8 offset1:40
	ds_write2_b32 v136, v38, v54 offset0:40 offset1:72
	ds_write2_b32 v135, v7, v23 offset0:137 offset1:169
	ds_write2_b32 v136, v39, v55 offset0:169 offset1:201
	ds_write2_b32 v137, v8, v24 offset0:10 offset1:42
	ds_write2_b32 v138, v40, v56 offset0:42 offset1:74
	ds_write2_b32 v137, v9, v25 offset0:139 offset1:171
	ds_write2_b32 v138, v41, v57 offset0:171 offset1:203
	ds_write2_b32 v139, v10, v26 offset0:16 offset1:48
	ds_write2_b32 v140, v42, v58 offset0:48 offset1:80
	ds_write2_b32 v139, v11, v27 offset0:145 offset1:177
	ds_write2_b32 v140, v43, v59 offset0:177 offset1:209
	ds_write2_b32 v141, v12, v28 offset0:18 offset1:50
	ds_write2_b32 v142, v44, v60 offset0:50 offset1:82
	ds_write2_b32 v141, v13, v29 offset0:147 offset1:179
	ds_write2_b32 v142, v45, v61 offset0:179 offset1:211
	ds_write2_b32 v143, v14, v30 offset0:24 offset1:56
	ds_write2_b32 v144, v46, v62 offset0:56 offset1:88
	ds_write2_b32 v143, v15, v31 offset0:153 offset1:185
	ds_write2_b32 v144, v47, v63 offset0:185 offset1:217
	ds_write2_b32 v145, v16, v32 offset0:26 offset1:58
	ds_write2_b32 v146, v48, v64 offset0:58 offset1:90
	ds_write2_b32 v145, v17, v33 offset0:155 offset1:187
	ds_write2_b32 v146, v49, v65 offset0:187 offset1:219
	v_lshl_add_u64 v[2:3], v[66:67], 2, s[6:7]
	s_waitcnt lgkmcnt(0)
	s_barrier
	v_mov_b32_e32 v2, v66
	v_lshlrev_b32_e32 v3, 2, v2
	v_lshlrev_b32_e32 v4, 13, v2
	v_add3_u32 v4, v4, v74, s10
	s_movk_i32 s24, 0x7fff
	v_mov_b32_e32 v59, 1
	v_mov_b32_e32 v13, 0x358637bd
	ds_read2_b32 v[14:15], v103 offset0:0 offset1:1
	ds_read2_b32 v[16:17], v103 offset0:2 offset1:3
	ds_read2_b32 v[18:19], v103 offset0:4 offset1:5
	ds_read2_b32 v[20:21], v103 offset0:6 offset1:7
	v_add_u32_e32 v56, 0x2040, v103
	ds_read2_b32 v[22:23], v56 offset0:0 offset1:1
	ds_read2_b32 v[24:25], v56 offset0:2 offset1:3
	ds_read2_b32 v[26:27], v56 offset0:4 offset1:5
	ds_read2_b32 v[28:29], v56 offset0:6 offset1:7
	s_waitcnt vmcnt(7) lgkmcnt(4)
	v_fmamk_f32 v54, v160, 0x3a800000, v13
	v_rsq_f32_e32 v54, v54
	s_nop 0
	v_mul_f32_e32 v14, v14, v54
	v_mul_f32_e32 v15, v15, v54
	v_mul_f32_e32 v16, v16, v54
	v_mul_f32_e32 v17, v17, v54
	v_mul_f32_e32 v18, v18, v54
	v_mul_f32_e32 v19, v19, v54
	v_mul_f32_e32 v20, v20, v54
	v_mul_f32_e32 v21, v21, v54
	v_max_f32_e32 v14, 0, v14
	v_max_f32_e32 v15, 0, v15
	v_max_f32_e32 v16, 0, v16
	v_max_f32_e32 v17, 0, v17
	v_max_f32_e32 v18, 0, v18
	v_max_f32_e32 v19, 0, v19
	v_max_f32_e32 v20, 0, v20
	v_max_f32_e32 v21, 0, v21
	v_pk_mul_f32 v[14:15], v[14:15], v[14:15]
	v_pk_mul_f32 v[16:17], v[16:17], v[16:17]
	v_pk_mul_f32 v[18:19], v[18:19], v[18:19]
	v_pk_mul_f32 v[20:21], v[20:21], v[20:21]
	v_and_b32_sdwa v46, v14, v59 dst_sel:DWORD dst_unused:UNUSED_PAD src0_sel:WORD_1 src1_sel:DWORD
	v_and_b32_sdwa v47, v15, v59 dst_sel:DWORD dst_unused:UNUSED_PAD src0_sel:WORD_1 src1_sel:DWORD
	v_and_b32_sdwa v48, v16, v59 dst_sel:DWORD dst_unused:UNUSED_PAD src0_sel:WORD_1 src1_sel:DWORD
	v_and_b32_sdwa v49, v17, v59 dst_sel:DWORD dst_unused:UNUSED_PAD src0_sel:WORD_1 src1_sel:DWORD
	v_and_b32_sdwa v50, v18, v59 dst_sel:DWORD dst_unused:UNUSED_PAD src0_sel:WORD_1 src1_sel:DWORD
	v_and_b32_sdwa v51, v19, v59 dst_sel:DWORD dst_unused:UNUSED_PAD src0_sel:WORD_1 src1_sel:DWORD
	v_and_b32_sdwa v52, v20, v59 dst_sel:DWORD dst_unused:UNUSED_PAD src0_sel:WORD_1 src1_sel:DWORD
	v_and_b32_sdwa v53, v21, v59 dst_sel:DWORD dst_unused:UNUSED_PAD src0_sel:WORD_1 src1_sel:DWORD
	v_add3_u32 v14, v14, v46, s24
	v_add3_u32 v15, v15, v47, s24
	v_add3_u32 v16, v16, v48, s24
	v_add3_u32 v17, v17, v49, s24
	v_add3_u32 v18, v18, v50, s24
	v_add3_u32 v19, v19, v51, s24
	v_add3_u32 v20, v20, v52, s24
	v_add3_u32 v21, v21, v53, s24
	v_and_b32_e32 v15, 0xffff0000, v15
	v_and_b32_e32 v17, 0xffff0000, v17
	v_and_b32_e32 v19, 0xffff0000, v19
	v_and_b32_e32 v21, 0xffff0000, v21
	v_or_b32_sdwa v60, v15, v14 dst_sel:DWORD dst_unused:UNUSED_PAD src0_sel:DWORD src1_sel:WORD_1
	v_or_b32_sdwa v61, v17, v16 dst_sel:DWORD dst_unused:UNUSED_PAD src0_sel:DWORD src1_sel:WORD_1
	v_or_b32_sdwa v62, v19, v18 dst_sel:DWORD dst_unused:UNUSED_PAD src0_sel:DWORD src1_sel:WORD_1
	v_or_b32_sdwa v63, v21, v20 dst_sel:DWORD dst_unused:UNUSED_PAD src0_sel:DWORD src1_sel:WORD_1
	global_store_dwordx4 v4, v[60:63], s[56:57]
	v_add_u32_e32 v55, 0x4080, v103
	ds_read2_b32 v[30:31], v55 offset0:0 offset1:1
	ds_read2_b32 v[32:33], v55 offset0:2 offset1:3
	ds_read2_b32 v[34:35], v55 offset0:4 offset1:5
	ds_read2_b32 v[36:37], v55 offset0:6 offset1:7
	v_add_u32_e32 v56, 0x60c0, v103
	ds_read2_b32 v[38:39], v56 offset0:0 offset1:1
	ds_read2_b32 v[40:41], v56 offset0:2 offset1:3
	ds_read2_b32 v[42:43], v56 offset0:4 offset1:5
	ds_read2_b32 v[44:45], v56 offset0:6 offset1:7
	s_waitcnt vmcnt(7) lgkmcnt(8)
	v_fmamk_f32 v54, v161, 0x3a800000, v13
	v_rsq_f32_e32 v54, v54
	v_add_u32_e32 v58, 0x20000, v4
	v_mul_f32_e32 v22, v22, v54
	v_mul_f32_e32 v23, v23, v54
	v_mul_f32_e32 v24, v24, v54
	v_mul_f32_e32 v25, v25, v54
	v_mul_f32_e32 v26, v26, v54
	v_mul_f32_e32 v27, v27, v54
	v_mul_f32_e32 v28, v28, v54
	v_mul_f32_e32 v29, v29, v54
	v_max_f32_e32 v22, 0, v22
	v_max_f32_e32 v23, 0, v23
	v_max_f32_e32 v24, 0, v24
	v_max_f32_e32 v25, 0, v25
	v_max_f32_e32 v26, 0, v26
	v_max_f32_e32 v27, 0, v27
	v_max_f32_e32 v28, 0, v28
	v_max_f32_e32 v29, 0, v29
	v_pk_mul_f32 v[22:23], v[22:23], v[22:23]
	v_pk_mul_f32 v[24:25], v[24:25], v[24:25]
	v_pk_mul_f32 v[26:27], v[26:27], v[26:27]
	v_pk_mul_f32 v[28:29], v[28:29], v[28:29]
	v_and_b32_sdwa v46, v22, v59 dst_sel:DWORD dst_unused:UNUSED_PAD src0_sel:WORD_1 src1_sel:DWORD
	v_and_b32_sdwa v47, v23, v59 dst_sel:DWORD dst_unused:UNUSED_PAD src0_sel:WORD_1 src1_sel:DWORD
	v_and_b32_sdwa v48, v24, v59 dst_sel:DWORD dst_unused:UNUSED_PAD src0_sel:WORD_1 src1_sel:DWORD
	v_and_b32_sdwa v49, v25, v59 dst_sel:DWORD dst_unused:UNUSED_PAD src0_sel:WORD_1 src1_sel:DWORD
	v_and_b32_sdwa v50, v26, v59 dst_sel:DWORD dst_unused:UNUSED_PAD src0_sel:WORD_1 src1_sel:DWORD
	v_and_b32_sdwa v51, v27, v59 dst_sel:DWORD dst_unused:UNUSED_PAD src0_sel:WORD_1 src1_sel:DWORD
	v_and_b32_sdwa v52, v28, v59 dst_sel:DWORD dst_unused:UNUSED_PAD src0_sel:WORD_1 src1_sel:DWORD
	v_and_b32_sdwa v53, v29, v59 dst_sel:DWORD dst_unused:UNUSED_PAD src0_sel:WORD_1 src1_sel:DWORD
	v_add3_u32 v22, v22, v46, s24
	v_add3_u32 v23, v23, v47, s24
	v_add3_u32 v24, v24, v48, s24
	v_add3_u32 v25, v25, v49, s24
	v_add3_u32 v26, v26, v50, s24
	v_add3_u32 v27, v27, v51, s24
	v_add3_u32 v28, v28, v52, s24
	v_add3_u32 v29, v29, v53, s24
	v_and_b32_e32 v23, 0xffff0000, v23
	v_and_b32_e32 v25, 0xffff0000, v25
	v_and_b32_e32 v27, 0xffff0000, v27
	v_and_b32_e32 v29, 0xffff0000, v29
	v_or_b32_sdwa v76, v23, v22 dst_sel:DWORD dst_unused:UNUSED_PAD src0_sel:DWORD src1_sel:WORD_1
	v_or_b32_sdwa v77, v25, v24 dst_sel:DWORD dst_unused:UNUSED_PAD src0_sel:DWORD src1_sel:WORD_1
	v_or_b32_sdwa v78, v27, v26 dst_sel:DWORD dst_unused:UNUSED_PAD src0_sel:DWORD src1_sel:WORD_1
	v_or_b32_sdwa v79, v29, v28 dst_sel:DWORD dst_unused:UNUSED_PAD src0_sel:DWORD src1_sel:WORD_1
	global_store_dwordx4 v58, v[76:79], s[56:57]
	s_waitcnt vmcnt(7) lgkmcnt(4)
	v_fmamk_f32 v54, v162, 0x3a800000, v13
	v_rsq_f32_e32 v54, v54
	v_add_u32_e32 v57, 0x40000, v4
	v_mul_f32_e32 v30, v30, v54
	v_mul_f32_e32 v31, v31, v54
	v_mul_f32_e32 v32, v32, v54
	v_mul_f32_e32 v33, v33, v54
	v_mul_f32_e32 v34, v34, v54
	v_mul_f32_e32 v35, v35, v54
	v_mul_f32_e32 v36, v36, v54
	v_mul_f32_e32 v37, v37, v54
	v_max_f32_e32 v30, 0, v30
	v_max_f32_e32 v31, 0, v31
	v_max_f32_e32 v32, 0, v32
	v_max_f32_e32 v33, 0, v33
	v_max_f32_e32 v34, 0, v34
	v_max_f32_e32 v35, 0, v35
	v_max_f32_e32 v36, 0, v36
	v_max_f32_e32 v37, 0, v37
	v_pk_mul_f32 v[30:31], v[30:31], v[30:31]
	v_pk_mul_f32 v[32:33], v[32:33], v[32:33]
	v_pk_mul_f32 v[34:35], v[34:35], v[34:35]
	v_pk_mul_f32 v[36:37], v[36:37], v[36:37]
	v_and_b32_sdwa v46, v30, v59 dst_sel:DWORD dst_unused:UNUSED_PAD src0_sel:WORD_1 src1_sel:DWORD
	v_and_b32_sdwa v47, v31, v59 dst_sel:DWORD dst_unused:UNUSED_PAD src0_sel:WORD_1 src1_sel:DWORD
	v_and_b32_sdwa v48, v32, v59 dst_sel:DWORD dst_unused:UNUSED_PAD src0_sel:WORD_1 src1_sel:DWORD
	v_and_b32_sdwa v49, v33, v59 dst_sel:DWORD dst_unused:UNUSED_PAD src0_sel:WORD_1 src1_sel:DWORD
	v_and_b32_sdwa v50, v34, v59 dst_sel:DWORD dst_unused:UNUSED_PAD src0_sel:WORD_1 src1_sel:DWORD
	v_and_b32_sdwa v51, v35, v59 dst_sel:DWORD dst_unused:UNUSED_PAD src0_sel:WORD_1 src1_sel:DWORD
	v_and_b32_sdwa v52, v36, v59 dst_sel:DWORD dst_unused:UNUSED_PAD src0_sel:WORD_1 src1_sel:DWORD
	v_and_b32_sdwa v53, v37, v59 dst_sel:DWORD dst_unused:UNUSED_PAD src0_sel:WORD_1 src1_sel:DWORD
	v_add3_u32 v30, v30, v46, s24
	v_add3_u32 v31, v31, v47, s24
	v_add3_u32 v32, v32, v48, s24
	v_add3_u32 v33, v33, v49, s24
	v_add3_u32 v34, v34, v50, s24
	v_add3_u32 v35, v35, v51, s24
	v_add3_u32 v36, v36, v52, s24
	v_add3_u32 v37, v37, v53, s24
	v_and_b32_e32 v31, 0xffff0000, v31
	v_and_b32_e32 v33, 0xffff0000, v33
	v_and_b32_e32 v35, 0xffff0000, v35
	v_and_b32_e32 v37, 0xffff0000, v37
	v_or_b32_sdwa v60, v31, v30 dst_sel:DWORD dst_unused:UNUSED_PAD src0_sel:DWORD src1_sel:WORD_1
	v_or_b32_sdwa v61, v33, v32 dst_sel:DWORD dst_unused:UNUSED_PAD src0_sel:DWORD src1_sel:WORD_1
	v_or_b32_sdwa v62, v35, v34 dst_sel:DWORD dst_unused:UNUSED_PAD src0_sel:DWORD src1_sel:WORD_1
	v_or_b32_sdwa v63, v37, v36 dst_sel:DWORD dst_unused:UNUSED_PAD src0_sel:DWORD src1_sel:WORD_1
	global_store_dwordx4 v57, v[60:63], s[56:57]
	v_add_u32_e32 v55, 0x8100, v103
	ds_read2_b32 v[14:15], v55 offset0:0 offset1:1
	ds_read2_b32 v[16:17], v55 offset0:2 offset1:3
	ds_read2_b32 v[18:19], v55 offset0:4 offset1:5
	ds_read2_b32 v[20:21], v55 offset0:6 offset1:7
	v_add_u32_e32 v56, 0xa140, v103
	ds_read2_b32 v[22:23], v56 offset0:0 offset1:1
	ds_read2_b32 v[24:25], v56 offset0:2 offset1:3
	ds_read2_b32 v[26:27], v56 offset0:4 offset1:5
	ds_read2_b32 v[28:29], v56 offset0:6 offset1:7
	s_waitcnt vmcnt(7) lgkmcnt(8)
	v_fmamk_f32 v54, v163, 0x3a800000, v13
	v_rsq_f32_e32 v54, v54
	v_add_u32_e32 v58, 0x60000, v4
	v_mul_f32_e32 v38, v38, v54
	v_mul_f32_e32 v39, v39, v54
	v_mul_f32_e32 v40, v40, v54
	v_mul_f32_e32 v41, v41, v54
	v_mul_f32_e32 v42, v42, v54
	v_mul_f32_e32 v43, v43, v54
	v_mul_f32_e32 v44, v44, v54
	v_mul_f32_e32 v45, v45, v54
	v_max_f32_e32 v38, 0, v38
	v_max_f32_e32 v39, 0, v39
	v_max_f32_e32 v40, 0, v40
	v_max_f32_e32 v41, 0, v41
	v_max_f32_e32 v42, 0, v42
	v_max_f32_e32 v43, 0, v43
	v_max_f32_e32 v44, 0, v44
	v_max_f32_e32 v45, 0, v45
	v_pk_mul_f32 v[38:39], v[38:39], v[38:39]
	v_pk_mul_f32 v[40:41], v[40:41], v[40:41]
	v_pk_mul_f32 v[42:43], v[42:43], v[42:43]
	v_pk_mul_f32 v[44:45], v[44:45], v[44:45]
	v_and_b32_sdwa v46, v38, v59 dst_sel:DWORD dst_unused:UNUSED_PAD src0_sel:WORD_1 src1_sel:DWORD
	v_and_b32_sdwa v47, v39, v59 dst_sel:DWORD dst_unused:UNUSED_PAD src0_sel:WORD_1 src1_sel:DWORD
	v_and_b32_sdwa v48, v40, v59 dst_sel:DWORD dst_unused:UNUSED_PAD src0_sel:WORD_1 src1_sel:DWORD
	v_and_b32_sdwa v49, v41, v59 dst_sel:DWORD dst_unused:UNUSED_PAD src0_sel:WORD_1 src1_sel:DWORD
	v_and_b32_sdwa v50, v42, v59 dst_sel:DWORD dst_unused:UNUSED_PAD src0_sel:WORD_1 src1_sel:DWORD
	v_and_b32_sdwa v51, v43, v59 dst_sel:DWORD dst_unused:UNUSED_PAD src0_sel:WORD_1 src1_sel:DWORD
	v_and_b32_sdwa v52, v44, v59 dst_sel:DWORD dst_unused:UNUSED_PAD src0_sel:WORD_1 src1_sel:DWORD
	v_and_b32_sdwa v53, v45, v59 dst_sel:DWORD dst_unused:UNUSED_PAD src0_sel:WORD_1 src1_sel:DWORD
	v_add3_u32 v38, v38, v46, s24
	v_add3_u32 v39, v39, v47, s24
	v_add3_u32 v40, v40, v48, s24
	v_add3_u32 v41, v41, v49, s24
	v_add3_u32 v42, v42, v50, s24
	v_add3_u32 v43, v43, v51, s24
	v_add3_u32 v44, v44, v52, s24
	v_add3_u32 v45, v45, v53, s24
	v_and_b32_e32 v39, 0xffff0000, v39
	v_and_b32_e32 v41, 0xffff0000, v41
	v_and_b32_e32 v43, 0xffff0000, v43
	v_and_b32_e32 v45, 0xffff0000, v45
	v_or_b32_sdwa v76, v39, v38 dst_sel:DWORD dst_unused:UNUSED_PAD src0_sel:DWORD src1_sel:WORD_1
	v_or_b32_sdwa v77, v41, v40 dst_sel:DWORD dst_unused:UNUSED_PAD src0_sel:DWORD src1_sel:WORD_1
	v_or_b32_sdwa v78, v43, v42 dst_sel:DWORD dst_unused:UNUSED_PAD src0_sel:DWORD src1_sel:WORD_1
	v_or_b32_sdwa v79, v45, v44 dst_sel:DWORD dst_unused:UNUSED_PAD src0_sel:DWORD src1_sel:WORD_1
	global_store_dwordx4 v58, v[76:79], s[56:57]
	s_waitcnt vmcnt(7) lgkmcnt(4)
	v_fmamk_f32 v54, v164, 0x3a800000, v13
	v_rsq_f32_e32 v54, v54
	v_add_u32_e32 v57, 0x80000, v4
	v_mul_f32_e32 v14, v14, v54
	v_mul_f32_e32 v15, v15, v54
	v_mul_f32_e32 v16, v16, v54
	v_mul_f32_e32 v17, v17, v54
	v_mul_f32_e32 v18, v18, v54
	v_mul_f32_e32 v19, v19, v54
	v_mul_f32_e32 v20, v20, v54
	v_mul_f32_e32 v21, v21, v54
	v_max_f32_e32 v14, 0, v14
	v_max_f32_e32 v15, 0, v15
	v_max_f32_e32 v16, 0, v16
	v_max_f32_e32 v17, 0, v17
	v_max_f32_e32 v18, 0, v18
	v_max_f32_e32 v19, 0, v19
	v_max_f32_e32 v20, 0, v20
	v_max_f32_e32 v21, 0, v21
	v_pk_mul_f32 v[14:15], v[14:15], v[14:15]
	v_pk_mul_f32 v[16:17], v[16:17], v[16:17]
	v_pk_mul_f32 v[18:19], v[18:19], v[18:19]
	v_pk_mul_f32 v[20:21], v[20:21], v[20:21]
	v_and_b32_sdwa v46, v14, v59 dst_sel:DWORD dst_unused:UNUSED_PAD src0_sel:WORD_1 src1_sel:DWORD
	v_and_b32_sdwa v47, v15, v59 dst_sel:DWORD dst_unused:UNUSED_PAD src0_sel:WORD_1 src1_sel:DWORD
	v_and_b32_sdwa v48, v16, v59 dst_sel:DWORD dst_unused:UNUSED_PAD src0_sel:WORD_1 src1_sel:DWORD
	v_and_b32_sdwa v49, v17, v59 dst_sel:DWORD dst_unused:UNUSED_PAD src0_sel:WORD_1 src1_sel:DWORD
	v_and_b32_sdwa v50, v18, v59 dst_sel:DWORD dst_unused:UNUSED_PAD src0_sel:WORD_1 src1_sel:DWORD
	v_and_b32_sdwa v51, v19, v59 dst_sel:DWORD dst_unused:UNUSED_PAD src0_sel:WORD_1 src1_sel:DWORD
	v_and_b32_sdwa v52, v20, v59 dst_sel:DWORD dst_unused:UNUSED_PAD src0_sel:WORD_1 src1_sel:DWORD
	v_and_b32_sdwa v53, v21, v59 dst_sel:DWORD dst_unused:UNUSED_PAD src0_sel:WORD_1 src1_sel:DWORD
	v_add3_u32 v14, v14, v46, s24
	v_add3_u32 v15, v15, v47, s24
	v_add3_u32 v16, v16, v48, s24
	v_add3_u32 v17, v17, v49, s24
	v_add3_u32 v18, v18, v50, s24
	v_add3_u32 v19, v19, v51, s24
	v_add3_u32 v20, v20, v52, s24
	v_add3_u32 v21, v21, v53, s24
	v_and_b32_e32 v15, 0xffff0000, v15
	v_and_b32_e32 v17, 0xffff0000, v17
	v_and_b32_e32 v19, 0xffff0000, v19
	v_and_b32_e32 v21, 0xffff0000, v21
	v_or_b32_sdwa v60, v15, v14 dst_sel:DWORD dst_unused:UNUSED_PAD src0_sel:DWORD src1_sel:WORD_1
	v_or_b32_sdwa v61, v17, v16 dst_sel:DWORD dst_unused:UNUSED_PAD src0_sel:DWORD src1_sel:WORD_1
	v_or_b32_sdwa v62, v19, v18 dst_sel:DWORD dst_unused:UNUSED_PAD src0_sel:DWORD src1_sel:WORD_1
	v_or_b32_sdwa v63, v21, v20 dst_sel:DWORD dst_unused:UNUSED_PAD src0_sel:DWORD src1_sel:WORD_1
	global_store_dwordx4 v57, v[60:63], s[56:57]
	v_add_u32_e32 v55, 0xc180, v103
	ds_read2_b32 v[30:31], v55 offset0:0 offset1:1
	ds_read2_b32 v[32:33], v55 offset0:2 offset1:3
	ds_read2_b32 v[34:35], v55 offset0:4 offset1:5
	ds_read2_b32 v[36:37], v55 offset0:6 offset1:7
	v_add_u32_e32 v56, 0xe1c0, v103
	ds_read2_b32 v[38:39], v56 offset0:0 offset1:1
	ds_read2_b32 v[40:41], v56 offset0:2 offset1:3
	ds_read2_b32 v[42:43], v56 offset0:4 offset1:5
	ds_read2_b32 v[44:45], v56 offset0:6 offset1:7
	s_waitcnt vmcnt(7) lgkmcnt(8)
	v_fmamk_f32 v54, v165, 0x3a800000, v13
	v_rsq_f32_e32 v54, v54
	v_add_u32_e32 v58, 0xa0000, v4
	v_mul_f32_e32 v22, v22, v54
	v_mul_f32_e32 v23, v23, v54
	v_mul_f32_e32 v24, v24, v54
	v_mul_f32_e32 v25, v25, v54
	v_mul_f32_e32 v26, v26, v54
	v_mul_f32_e32 v27, v27, v54
	v_mul_f32_e32 v28, v28, v54
	v_mul_f32_e32 v29, v29, v54
	v_max_f32_e32 v22, 0, v22
	v_max_f32_e32 v23, 0, v23
	v_max_f32_e32 v24, 0, v24
	v_max_f32_e32 v25, 0, v25
	v_max_f32_e32 v26, 0, v26
	v_max_f32_e32 v27, 0, v27
	v_max_f32_e32 v28, 0, v28
	v_max_f32_e32 v29, 0, v29
	v_pk_mul_f32 v[22:23], v[22:23], v[22:23]
	v_pk_mul_f32 v[24:25], v[24:25], v[24:25]
	v_pk_mul_f32 v[26:27], v[26:27], v[26:27]
	v_pk_mul_f32 v[28:29], v[28:29], v[28:29]
	v_and_b32_sdwa v46, v22, v59 dst_sel:DWORD dst_unused:UNUSED_PAD src0_sel:WORD_1 src1_sel:DWORD
	v_and_b32_sdwa v47, v23, v59 dst_sel:DWORD dst_unused:UNUSED_PAD src0_sel:WORD_1 src1_sel:DWORD
	v_and_b32_sdwa v48, v24, v59 dst_sel:DWORD dst_unused:UNUSED_PAD src0_sel:WORD_1 src1_sel:DWORD
	v_and_b32_sdwa v49, v25, v59 dst_sel:DWORD dst_unused:UNUSED_PAD src0_sel:WORD_1 src1_sel:DWORD
	v_and_b32_sdwa v50, v26, v59 dst_sel:DWORD dst_unused:UNUSED_PAD src0_sel:WORD_1 src1_sel:DWORD
	v_and_b32_sdwa v51, v27, v59 dst_sel:DWORD dst_unused:UNUSED_PAD src0_sel:WORD_1 src1_sel:DWORD
	v_and_b32_sdwa v52, v28, v59 dst_sel:DWORD dst_unused:UNUSED_PAD src0_sel:WORD_1 src1_sel:DWORD
	v_and_b32_sdwa v53, v29, v59 dst_sel:DWORD dst_unused:UNUSED_PAD src0_sel:WORD_1 src1_sel:DWORD
	v_add3_u32 v22, v22, v46, s24
	v_add3_u32 v23, v23, v47, s24
	v_add3_u32 v24, v24, v48, s24
	v_add3_u32 v25, v25, v49, s24
	v_add3_u32 v26, v26, v50, s24
	v_add3_u32 v27, v27, v51, s24
	v_add3_u32 v28, v28, v52, s24
	v_add3_u32 v29, v29, v53, s24
	v_and_b32_e32 v23, 0xffff0000, v23
	v_and_b32_e32 v25, 0xffff0000, v25
	v_and_b32_e32 v27, 0xffff0000, v27
	v_and_b32_e32 v29, 0xffff0000, v29
	v_or_b32_sdwa v76, v23, v22 dst_sel:DWORD dst_unused:UNUSED_PAD src0_sel:DWORD src1_sel:WORD_1
	v_or_b32_sdwa v77, v25, v24 dst_sel:DWORD dst_unused:UNUSED_PAD src0_sel:DWORD src1_sel:WORD_1
	v_or_b32_sdwa v78, v27, v26 dst_sel:DWORD dst_unused:UNUSED_PAD src0_sel:DWORD src1_sel:WORD_1
	v_or_b32_sdwa v79, v29, v28 dst_sel:DWORD dst_unused:UNUSED_PAD src0_sel:DWORD src1_sel:WORD_1
	global_store_dwordx4 v58, v[76:79], s[56:57]
	s_waitcnt vmcnt(7) lgkmcnt(4)
	v_fmamk_f32 v54, v166, 0x3a800000, v13
	v_rsq_f32_e32 v54, v54
	v_add_u32_e32 v57, 0xc0000, v4
	v_mul_f32_e32 v30, v30, v54
	v_mul_f32_e32 v31, v31, v54
	v_mul_f32_e32 v32, v32, v54
	v_mul_f32_e32 v33, v33, v54
	v_mul_f32_e32 v34, v34, v54
	v_mul_f32_e32 v35, v35, v54
	v_mul_f32_e32 v36, v36, v54
	v_mul_f32_e32 v37, v37, v54
	v_max_f32_e32 v30, 0, v30
	v_max_f32_e32 v31, 0, v31
	v_max_f32_e32 v32, 0, v32
	v_max_f32_e32 v33, 0, v33
	v_max_f32_e32 v34, 0, v34
	v_max_f32_e32 v35, 0, v35
	v_max_f32_e32 v36, 0, v36
	v_max_f32_e32 v37, 0, v37
	v_pk_mul_f32 v[30:31], v[30:31], v[30:31]
	v_pk_mul_f32 v[32:33], v[32:33], v[32:33]
	v_pk_mul_f32 v[34:35], v[34:35], v[34:35]
	v_pk_mul_f32 v[36:37], v[36:37], v[36:37]
	v_and_b32_sdwa v46, v30, v59 dst_sel:DWORD dst_unused:UNUSED_PAD src0_sel:WORD_1 src1_sel:DWORD
	v_and_b32_sdwa v47, v31, v59 dst_sel:DWORD dst_unused:UNUSED_PAD src0_sel:WORD_1 src1_sel:DWORD
	v_and_b32_sdwa v48, v32, v59 dst_sel:DWORD dst_unused:UNUSED_PAD src0_sel:WORD_1 src1_sel:DWORD
	v_and_b32_sdwa v49, v33, v59 dst_sel:DWORD dst_unused:UNUSED_PAD src0_sel:WORD_1 src1_sel:DWORD
	v_and_b32_sdwa v50, v34, v59 dst_sel:DWORD dst_unused:UNUSED_PAD src0_sel:WORD_1 src1_sel:DWORD
	v_and_b32_sdwa v51, v35, v59 dst_sel:DWORD dst_unused:UNUSED_PAD src0_sel:WORD_1 src1_sel:DWORD
	v_and_b32_sdwa v52, v36, v59 dst_sel:DWORD dst_unused:UNUSED_PAD src0_sel:WORD_1 src1_sel:DWORD
	v_and_b32_sdwa v53, v37, v59 dst_sel:DWORD dst_unused:UNUSED_PAD src0_sel:WORD_1 src1_sel:DWORD
	v_add3_u32 v30, v30, v46, s24
	v_add3_u32 v31, v31, v47, s24
	v_add3_u32 v32, v32, v48, s24
	v_add3_u32 v33, v33, v49, s24
	v_add3_u32 v34, v34, v50, s24
	v_add3_u32 v35, v35, v51, s24
	v_add3_u32 v36, v36, v52, s24
	v_add3_u32 v37, v37, v53, s24
	v_and_b32_e32 v31, 0xffff0000, v31
	v_and_b32_e32 v33, 0xffff0000, v33
	v_and_b32_e32 v35, 0xffff0000, v35
	v_and_b32_e32 v37, 0xffff0000, v37
	v_or_b32_sdwa v60, v31, v30 dst_sel:DWORD dst_unused:UNUSED_PAD src0_sel:DWORD src1_sel:WORD_1
	v_or_b32_sdwa v61, v33, v32 dst_sel:DWORD dst_unused:UNUSED_PAD src0_sel:DWORD src1_sel:WORD_1
	v_or_b32_sdwa v62, v35, v34 dst_sel:DWORD dst_unused:UNUSED_PAD src0_sel:DWORD src1_sel:WORD_1
	v_or_b32_sdwa v63, v37, v36 dst_sel:DWORD dst_unused:UNUSED_PAD src0_sel:DWORD src1_sel:WORD_1
	global_store_dwordx4 v57, v[60:63], s[56:57]
	s_waitcnt vmcnt(7) lgkmcnt(0)
	v_fmamk_f32 v54, v167, 0x3a800000, v13
	v_rsq_f32_e32 v54, v54
	v_add_u32_e32 v58, 0xe0000, v4
	v_mul_f32_e32 v38, v38, v54
	v_mul_f32_e32 v39, v39, v54
	v_mul_f32_e32 v40, v40, v54
	v_mul_f32_e32 v41, v41, v54
	v_mul_f32_e32 v42, v42, v54
	v_mul_f32_e32 v43, v43, v54
	v_mul_f32_e32 v44, v44, v54
	v_mul_f32_e32 v45, v45, v54
	v_max_f32_e32 v38, 0, v38
	v_max_f32_e32 v39, 0, v39
	v_max_f32_e32 v40, 0, v40
	v_max_f32_e32 v41, 0, v41
	v_max_f32_e32 v42, 0, v42
	v_max_f32_e32 v43, 0, v43
	v_max_f32_e32 v44, 0, v44
	v_max_f32_e32 v45, 0, v45
	v_pk_mul_f32 v[38:39], v[38:39], v[38:39]
	v_pk_mul_f32 v[40:41], v[40:41], v[40:41]
	v_pk_mul_f32 v[42:43], v[42:43], v[42:43]
	v_pk_mul_f32 v[44:45], v[44:45], v[44:45]
	v_and_b32_sdwa v46, v38, v59 dst_sel:DWORD dst_unused:UNUSED_PAD src0_sel:WORD_1 src1_sel:DWORD
	v_and_b32_sdwa v47, v39, v59 dst_sel:DWORD dst_unused:UNUSED_PAD src0_sel:WORD_1 src1_sel:DWORD
	v_and_b32_sdwa v48, v40, v59 dst_sel:DWORD dst_unused:UNUSED_PAD src0_sel:WORD_1 src1_sel:DWORD
	v_and_b32_sdwa v49, v41, v59 dst_sel:DWORD dst_unused:UNUSED_PAD src0_sel:WORD_1 src1_sel:DWORD
	v_and_b32_sdwa v50, v42, v59 dst_sel:DWORD dst_unused:UNUSED_PAD src0_sel:WORD_1 src1_sel:DWORD
	v_and_b32_sdwa v51, v43, v59 dst_sel:DWORD dst_unused:UNUSED_PAD src0_sel:WORD_1 src1_sel:DWORD
	v_and_b32_sdwa v52, v44, v59 dst_sel:DWORD dst_unused:UNUSED_PAD src0_sel:WORD_1 src1_sel:DWORD
	v_and_b32_sdwa v53, v45, v59 dst_sel:DWORD dst_unused:UNUSED_PAD src0_sel:WORD_1 src1_sel:DWORD
	v_add3_u32 v38, v38, v46, s24
	v_add3_u32 v39, v39, v47, s24
	v_add3_u32 v40, v40, v48, s24
	v_add3_u32 v41, v41, v49, s24
	v_add3_u32 v42, v42, v50, s24
	v_add3_u32 v43, v43, v51, s24
	v_add3_u32 v44, v44, v52, s24
	v_add3_u32 v45, v45, v53, s24
	v_and_b32_e32 v39, 0xffff0000, v39
	v_and_b32_e32 v41, 0xffff0000, v41
	v_and_b32_e32 v43, 0xffff0000, v43
	v_and_b32_e32 v45, 0xffff0000, v45
	v_or_b32_sdwa v76, v39, v38 dst_sel:DWORD dst_unused:UNUSED_PAD src0_sel:DWORD src1_sel:WORD_1
	v_or_b32_sdwa v77, v41, v40 dst_sel:DWORD dst_unused:UNUSED_PAD src0_sel:DWORD src1_sel:WORD_1
	v_or_b32_sdwa v78, v43, v42 dst_sel:DWORD dst_unused:UNUSED_PAD src0_sel:DWORD src1_sel:WORD_1
	v_or_b32_sdwa v79, v45, v44 dst_sel:DWORD dst_unused:UNUSED_PAD src0_sel:DWORD src1_sel:WORD_1
	global_store_dwordx4 v58, v[76:79], s[56:57]
	s_cmpk_lt_u32 s13, 0x400
	s_barrier
	s_cbranch_scc1 .LBB0_338

.LBB0_590:
	s_lshr_b32 s8, s12, 2
	s_and_b32 s10, s16, 56
	s_and_b32 s8, s8, 0x1ffffc0
	s_or_b32 s10, s10, s3
	s_or_b32 s8, s10, s8
	s_lshl_b32 s8, s8, 7
	s_lshl_b64 s[24:25], s[8:9], 11
	v_lshl_add_u64 v[78:79], v[70:71], 0, s[24:25]
	v_add_co_u32_e32 v80, vcc, s18, v78
	s_and_b32 s10, s14, 0xf80
	s_nop 0
	v_addc_co_u32_e32 v81, vcc, 0, v79, vcc
	s_lshl_b32 s26, s10, 11
	s_mov_b32 s27, s9
	v_add_co_u32_e32 v82, vcc, s19, v78
	v_lshl_add_u64 v[76:77], v[72:73], 0, s[26:27]
	s_nop 0
	v_addc_co_u32_e32 v83, vcc, 0, v79, vcc
	v_add_co_u32_e32 v84, vcc, s18, v76
	global_load_dwordx4 v[2:5], v[78:79], off
	global_load_dwordx4 v[6:9], v[80:81], off
	v_addc_co_u32_e32 v85, vcc, 0, v77, vcc
	v_add_co_u32_e32 v86, vcc, s19, v76
	global_load_dwordx4 v[10:13], v[82:83], off
	global_load_dwordx4 v[14:17], v[76:77], off
	v_addc_co_u32_e32 v87, vcc, 0, v77, vcc
	global_load_dwordx4 v[18:21], v[84:85], off
	global_load_dwordx4 v[22:25], v[86:87], off
	v_add_co_u32_e32 v88, vcc, s20, v76
	s_nop 1
	v_addc_co_u32_e32 v89, vcc, 0, v77, vcc
	global_load_dwordx4 v[26:29], v[88:89], off
	v_add_co_u32_e32 v90, vcc, s20, v78
	s_nop 1
	v_addc_co_u32_e32 v91, vcc, 0, v79, vcc
	global_load_dwordx4 v[30:33], v[90:91], off
	global_load_dwordx4 v[148:151], v[76:77], off offset:128
	global_load_dwordx4 v[152:155], v[84:85], off offset:128
	global_load_dwordx4 v[156:159], v[86:87], off offset:128
	global_load_dwordx4 v[160:163], v[88:89], off offset:128
	global_load_dwordx4 v[164:167], v[78:79], off offset:128
	global_load_dwordx4 v[168:171], v[80:81], off offset:128
	global_load_dwordx4 v[172:175], v[82:83], off offset:128
	global_load_dwordx4 v[176:179], v[90:91], off offset:128
	s_waitcnt vmcnt(12)
	ds_write_b128 v1, v[14:17] offset:36864
	s_waitcnt vmcnt(11)
	ds_write_b128 v1, v[18:21] offset:41472
	s_waitcnt vmcnt(10)
	ds_write_b128 v1, v[22:25] offset:46080
	s_waitcnt vmcnt(9)
	ds_write_b128 v1, v[26:29] offset:50688
	ds_write_b128 v1, v[2:5]
	ds_write_b128 v1, v[6:9] offset:4608
	ds_write_b128 v1, v[10:13] offset:9216
	s_waitcnt vmcnt(8)
	ds_write_b128 v1, v[30:33] offset:13824
	s_waitcnt lgkmcnt(0)
	s_barrier
	global_load_dwordx4 v[180:183], v[80:81], off offset:256
	global_load_dwordx4 v[184:187], v[82:83], off offset:256
	global_load_dwordx4 v[188:191], v[78:79], off offset:256
	global_load_dwordx4 v[192:195], v[76:77], off offset:256
	global_load_dwordx4 v[196:199], v[90:91], off offset:256
	global_load_dwordx4 v[200:203], v[84:85], off offset:256
	global_load_dwordx4 v[204:207], v[86:87], off offset:256
	global_load_dwordx4 v[208:211], v[88:89], off offset:256
	ds_read_b128 v[18:21], v66
	ds_read_b128 v[34:37], v67 offset:36864
	ds_read_b128 v[212:215], v66 offset:32
	ds_read_b128 v[216:219], v67 offset:36896
	ds_read_b128 v[50:53], v67 offset:41472
	ds_read_b128 v[220:223], v67 offset:41504
	ds_read_b128 v[54:57], v66 offset:4608
	ds_read_b128 v[224:227], v66 offset:4640
	s_waitcnt lgkmcnt(6)
	v_mfma_f32_32x32x16_bf16 v[2:17], v[18:21], v[34:37], 0
	s_waitcnt lgkmcnt(3)
	v_mfma_f32_32x32x16_bf16 v[18:33], v[18:21], v[50:53], 0
	s_waitcnt lgkmcnt(1)
	v_mfma_f32_32x32x16_bf16 v[34:49], v[54:57], v[34:37], 0
	v_mfma_f32_32x32x16_bf16 v[50:65], v[54:57], v[50:53], 0
	v_mfma_f32_32x32x16_bf16 v[2:17], v[212:215], v[216:219], v[2:17]
	v_mfma_f32_32x32x16_bf16 v[18:33], v[212:215], v[220:223], v[18:33]
	s_waitcnt lgkmcnt(0)
	v_mfma_f32_32x32x16_bf16 v[34:49], v[224:227], v[216:219], v[34:49]
	v_mfma_f32_32x32x16_bf16 v[50:65], v[224:227], v[220:223], v[50:65]
	ds_read_b128 v[212:215], v66 offset:64
	ds_read_b128 v[216:219], v67 offset:36928
	ds_read_b128 v[220:223], v66 offset:96
	ds_read_b128 v[224:227], v67 offset:36960
	ds_read_b128 v[228:231], v67 offset:41536
	ds_read_b128 v[232:235], v67 offset:41568
	s_waitcnt lgkmcnt(4)
	v_mfma_f32_32x32x16_bf16 v[2:17], v[212:215], v[216:219], v[2:17]
	s_waitcnt lgkmcnt(1)
	v_mfma_f32_32x32x16_bf16 v[18:33], v[212:215], v[228:231], v[18:33]
	ds_read_b128 v[212:215], v66 offset:4672
	ds_read_b128 v[236:239], v66 offset:4704
	s_waitcnt vmcnt(11)
	ds_write_b128 v1, v[164:167] offset:18432
	s_waitcnt vmcnt(10)
	ds_write_b128 v1, v[168:171] offset:23040
	s_waitcnt vmcnt(9)
	ds_write_b128 v1, v[172:175] offset:27648
	s_waitcnt vmcnt(8)
	ds_write_b128 v1, v[176:179] offset:32256
	ds_write_b128 v1, v[148:151] offset:55296
	ds_write_b128 v1, v[152:155] offset:59904
	ds_write_b128 v1, v[156:159] offset:64512
	ds_write_b128 v92, v[160:163] offset:32256
	global_load_dwordx4 v[148:151], v[80:81], off offset:384
	global_load_dwordx4 v[152:155], v[82:83], off offset:384
	global_load_dwordx4 v[156:159], v[78:79], off offset:384
	global_load_dwordx4 v[160:163], v[76:77], off offset:384
	global_load_dwordx4 v[164:167], v[90:91], off offset:384
	global_load_dwordx4 v[168:171], v[84:85], off offset:384
	global_load_dwordx4 v[172:175], v[86:87], off offset:384
	global_load_dwordx4 v[176:179], v[88:89], off offset:384
	s_waitcnt lgkmcnt(0)
	s_barrier
	v_mfma_f32_32x32x16_bf16 v[34:49], v[212:215], v[216:219], v[34:49]
	v_mfma_f32_32x32x16_bf16 v[50:65], v[212:215], v[228:231], v[50:65]
	v_mfma_f32_32x32x16_bf16 v[2:17], v[220:223], v[224:227], v[2:17]
	v_mfma_f32_32x32x16_bf16 v[18:33], v[220:223], v[232:235], v[18:33]
	v_mfma_f32_32x32x16_bf16 v[34:49], v[236:239], v[224:227], v[34:49]
	v_mfma_f32_32x32x16_bf16 v[50:65], v[236:239], v[232:235], v[50:65]
	ds_read_b128 v[212:215], v66 offset:18432
	ds_read_b128 v[216:219], v67 offset:55296
	ds_read_b128 v[220:223], v66 offset:18464
	ds_read_b128 v[224:227], v67 offset:55328
	ds_read_b128 v[228:231], v67 offset:59904
	ds_read_b128 v[232:235], v67 offset:59936
	s_waitcnt lgkmcnt(4)
	v_mfma_f32_32x32x16_bf16 v[2:17], v[212:215], v[216:219], v[2:17]
	s_waitcnt lgkmcnt(1)
	v_mfma_f32_32x32x16_bf16 v[18:33], v[212:215], v[228:231], v[18:33]
	ds_read_b128 v[212:215], v66 offset:23040
	ds_read_b128 v[236:239], v66 offset:23072
	s_waitcnt lgkmcnt(1)
	v_mfma_f32_32x32x16_bf16 v[34:49], v[212:215], v[216:219], v[34:49]
	v_mfma_f32_32x32x16_bf16 v[50:65], v[212:215], v[228:231], v[50:65]
	v_mfma_f32_32x32x16_bf16 v[2:17], v[220:223], v[224:227], v[2:17]
	v_mfma_f32_32x32x16_bf16 v[18:33], v[220:223], v[232:235], v[18:33]
	s_waitcnt lgkmcnt(0)
	v_mfma_f32_32x32x16_bf16 v[34:49], v[236:239], v[224:227], v[34:49]
	ds_read_b128 v[212:215], v66 offset:18496
	ds_read_b128 v[216:219], v67 offset:55360
	ds_read_b128 v[220:223], v66 offset:18528
	ds_read_b128 v[224:227], v67 offset:55392
	v_mfma_f32_32x32x16_bf16 v[50:65], v[236:239], v[232:235], v[50:65]
	ds_read_b128 v[228:231], v67 offset:59968
	ds_read_b128 v[232:235], v67 offset:60000
	s_waitcnt lgkmcnt(4)
	v_mfma_f32_32x32x16_bf16 v[2:17], v[212:215], v[216:219], v[2:17]
	s_waitcnt lgkmcnt(1)
	v_mfma_f32_32x32x16_bf16 v[18:33], v[212:215], v[228:231], v[18:33]
	ds_read_b128 v[212:215], v66 offset:23104
	ds_read_b128 v[236:239], v66 offset:23136
	s_waitcnt vmcnt(13)
	ds_write_b128 v1, v[188:191]
	ds_write_b128 v1, v[180:183] offset:4608
	ds_write_b128 v1, v[184:187] offset:9216
	s_waitcnt vmcnt(11)
	ds_write_b128 v1, v[196:199] offset:13824
	ds_write_b128 v1, v[192:195] offset:36864
	s_waitcnt vmcnt(10)
	ds_write_b128 v1, v[200:203] offset:41472
	s_waitcnt vmcnt(9)
	ds_write_b128 v1, v[204:207] offset:46080
	s_waitcnt vmcnt(8)
	ds_write_b128 v1, v[208:211] offset:50688
	global_load_dwordx4 v[180:183], v[80:81], off offset:512
	global_load_dwordx4 v[184:187], v[82:83], off offset:512
	global_load_dwordx4 v[188:191], v[78:79], off offset:512
	global_load_dwordx4 v[192:195], v[76:77], off offset:512
	global_load_dwordx4 v[196:199], v[90:91], off offset:512
	global_load_dwordx4 v[200:203], v[84:85], off offset:512
	global_load_dwordx4 v[204:207], v[86:87], off offset:512
	global_load_dwordx4 v[208:211], v[88:89], off offset:512
	s_waitcnt lgkmcnt(0)
	s_barrier
	v_mfma_f32_32x32x16_bf16 v[34:49], v[212:215], v[216:219], v[34:49]
	v_mfma_f32_32x32x16_bf16 v[50:65], v[212:215], v[228:231], v[50:65]
	v_mfma_f32_32x32x16_bf16 v[2:17], v[220:223], v[224:227], v[2:17]
	v_mfma_f32_32x32x16_bf16 v[18:33], v[220:223], v[232:235], v[18:33]
	v_mfma_f32_32x32x16_bf16 v[34:49], v[236:239], v[224:227], v[34:49]
	v_mfma_f32_32x32x16_bf16 v[50:65], v[236:239], v[232:235], v[50:65]
	ds_read_b128 v[212:215], v66
	ds_read_b128 v[216:219], v67 offset:36864
	ds_read_b128 v[220:223], v66 offset:32
	ds_read_b128 v[224:227], v67 offset:36896
	ds_read_b128 v[228:231], v67 offset:41472
	ds_read_b128 v[232:235], v67 offset:41504
	s_waitcnt lgkmcnt(4)
	v_mfma_f32_32x32x16_bf16 v[2:17], v[212:215], v[216:219], v[2:17]
	s_waitcnt lgkmcnt(1)
	v_mfma_f32_32x32x16_bf16 v[18:33], v[212:215], v[228:231], v[18:33]
	ds_read_b128 v[212:215], v66 offset:4608
	ds_read_b128 v[236:239], v66 offset:4640
	s_waitcnt lgkmcnt(1)
	v_mfma_f32_32x32x16_bf16 v[34:49], v[212:215], v[216:219], v[34:49]
	v_mfma_f32_32x32x16_bf16 v[50:65], v[212:215], v[228:231], v[50:65]
	v_mfma_f32_32x32x16_bf16 v[2:17], v[220:223], v[224:227], v[2:17]
	v_mfma_f32_32x32x16_bf16 v[18:33], v[220:223], v[232:235], v[18:33]
	s_waitcnt lgkmcnt(0)
	v_mfma_f32_32x32x16_bf16 v[34:49], v[236:239], v[224:227], v[34:49]
	ds_read_b128 v[212:215], v66 offset:64
	ds_read_b128 v[216:219], v67 offset:36928
	ds_read_b128 v[220:223], v66 offset:96
	ds_read_b128 v[224:227], v67 offset:36960
	v_mfma_f32_32x32x16_bf16 v[50:65], v[236:239], v[232:235], v[50:65]
	ds_read_b128 v[228:231], v67 offset:41536
	ds_read_b128 v[232:235], v67 offset:41568
	s_waitcnt lgkmcnt(4)
	v_mfma_f32_32x32x16_bf16 v[2:17], v[212:215], v[216:219], v[2:17]
	s_waitcnt lgkmcnt(1)
	v_mfma_f32_32x32x16_bf16 v[18:33], v[212:215], v[228:231], v[18:33]
	ds_read_b128 v[212:215], v66 offset:4672
	ds_read_b128 v[236:239], v66 offset:4704
	s_waitcnt vmcnt(13)
	ds_write_b128 v1, v[156:159] offset:18432
	ds_write_b128 v1, v[148:151] offset:23040
	ds_write_b128 v1, v[152:155] offset:27648
	s_waitcnt vmcnt(11)
	ds_write_b128 v1, v[164:167] offset:32256
	ds_write_b128 v1, v[160:163] offset:55296
	s_waitcnt vmcnt(10)
	ds_write_b128 v1, v[168:171] offset:59904
	s_waitcnt vmcnt(9)
	ds_write_b128 v1, v[172:175] offset:64512
	s_waitcnt vmcnt(8)
	ds_write_b128 v92, v[176:179] offset:32256
	global_load_dwordx4 v[148:151], v[80:81], off offset:640
	global_load_dwordx4 v[152:155], v[82:83], off offset:640
	global_load_dwordx4 v[156:159], v[78:79], off offset:640
	global_load_dwordx4 v[160:163], v[76:77], off offset:640
	global_load_dwordx4 v[164:167], v[90:91], off offset:640
	global_load_dwordx4 v[168:171], v[84:85], off offset:640
	global_load_dwordx4 v[172:175], v[86:87], off offset:640
	global_load_dwordx4 v[176:179], v[88:89], off offset:640
	s_waitcnt lgkmcnt(0)
	s_barrier
	v_mfma_f32_32x32x16_bf16 v[34:49], v[212:215], v[216:219], v[34:49]
	v_mfma_f32_32x32x16_bf16 v[50:65], v[212:215], v[228:231], v[50:65]
	v_mfma_f32_32x32x16_bf16 v[2:17], v[220:223], v[224:227], v[2:17]
	v_mfma_f32_32x32x16_bf16 v[18:33], v[220:223], v[232:235], v[18:33]
	v_mfma_f32_32x32x16_bf16 v[34:49], v[236:239], v[224:227], v[34:49]
	v_mfma_f32_32x32x16_bf16 v[50:65], v[236:239], v[232:235], v[50:65]
	ds_read_b128 v[212:215], v66 offset:18432
	ds_read_b128 v[216:219], v67 offset:55296
	ds_read_b128 v[220:223], v66 offset:18464
	ds_read_b128 v[224:227], v67 offset:55328
	ds_read_b128 v[228:231], v67 offset:59904
	ds_read_b128 v[232:235], v67 offset:59936
	s_waitcnt lgkmcnt(4)
	v_mfma_f32_32x32x16_bf16 v[2:17], v[212:215], v[216:219], v[2:17]
	s_waitcnt lgkmcnt(1)
	v_mfma_f32_32x32x16_bf16 v[18:33], v[212:215], v[228:231], v[18:33]
	ds_read_b128 v[212:215], v66 offset:23040
	ds_read_b128 v[236:239], v66 offset:23072
	s_waitcnt lgkmcnt(1)
	v_mfma_f32_32x32x16_bf16 v[34:49], v[212:215], v[216:219], v[34:49]
	v_mfma_f32_32x32x16_bf16 v[50:65], v[212:215], v[228:231], v[50:65]
	v_mfma_f32_32x32x16_bf16 v[2:17], v[220:223], v[224:227], v[2:17]
	v_mfma_f32_32x32x16_bf16 v[18:33], v[220:223], v[232:235], v[18:33]
	s_waitcnt lgkmcnt(0)
	v_mfma_f32_32x32x16_bf16 v[34:49], v[236:239], v[224:227], v[34:49]
	ds_read_b128 v[212:215], v66 offset:18496
	ds_read_b128 v[216:219], v67 offset:55360
	ds_read_b128 v[220:223], v66 offset:18528
	ds_read_b128 v[224:227], v67 offset:55392
	v_mfma_f32_32x32x16_bf16 v[50:65], v[236:239], v[232:235], v[50:65]
	ds_read_b128 v[228:231], v67 offset:59968
	ds_read_b128 v[232:235], v67 offset:60000
	s_waitcnt lgkmcnt(4)
	v_mfma_f32_32x32x16_bf16 v[2:17], v[212:215], v[216:219], v[2:17]
	s_waitcnt lgkmcnt(1)
	v_mfma_f32_32x32x16_bf16 v[18:33], v[212:215], v[228:231], v[18:33]
	ds_read_b128 v[212:215], v66 offset:23104
	ds_read_b128 v[236:239], v66 offset:23136
	s_waitcnt vmcnt(13)
	ds_write_b128 v1, v[188:191]
	ds_write_b128 v1, v[180:183] offset:4608
	ds_write_b128 v1, v[184:187] offset:9216
	s_waitcnt vmcnt(11)
	ds_write_b128 v1, v[196:199] offset:13824
	ds_write_b128 v1, v[192:195] offset:36864
	s_waitcnt vmcnt(10)
	ds_write_b128 v1, v[200:203] offset:41472
	s_waitcnt vmcnt(9)
	ds_write_b128 v1, v[204:207] offset:46080
	s_waitcnt vmcnt(8)
	ds_write_b128 v1, v[208:211] offset:50688
	global_load_dwordx4 v[180:183], v[80:81], off offset:768
	global_load_dwordx4 v[184:187], v[82:83], off offset:768
	global_load_dwordx4 v[188:191], v[78:79], off offset:768
	global_load_dwordx4 v[192:195], v[76:77], off offset:768
	global_load_dwordx4 v[196:199], v[90:91], off offset:768
	global_load_dwordx4 v[200:203], v[84:85], off offset:768
	global_load_dwordx4 v[204:207], v[86:87], off offset:768
	global_load_dwordx4 v[208:211], v[88:89], off offset:768
	s_waitcnt lgkmcnt(0)
	s_barrier
	v_mfma_f32_32x32x16_bf16 v[34:49], v[212:215], v[216:219], v[34:49]
	v_mfma_f32_32x32x16_bf16 v[50:65], v[212:215], v[228:231], v[50:65]
	v_mfma_f32_32x32x16_bf16 v[2:17], v[220:223], v[224:227], v[2:17]
	v_mfma_f32_32x32x16_bf16 v[18:33], v[220:223], v[232:235], v[18:33]
	v_mfma_f32_32x32x16_bf16 v[34:49], v[236:239], v[224:227], v[34:49]
	v_mfma_f32_32x32x16_bf16 v[50:65], v[236:239], v[232:235], v[50:65]
	ds_read_b128 v[212:215], v66
	ds_read_b128 v[216:219], v67 offset:36864
	ds_read_b128 v[220:223], v66 offset:32
	ds_read_b128 v[224:227], v67 offset:36896
	ds_read_b128 v[228:231], v67 offset:41472
	ds_read_b128 v[232:235], v67 offset:41504
	s_waitcnt lgkmcnt(4)
	v_mfma_f32_32x32x16_bf16 v[2:17], v[212:215], v[216:219], v[2:17]
	s_waitcnt lgkmcnt(1)
	v_mfma_f32_32x32x16_bf16 v[18:33], v[212:215], v[228:231], v[18:33]
	ds_read_b128 v[212:215], v66 offset:4608
	ds_read_b128 v[236:239], v66 offset:4640
	s_waitcnt lgkmcnt(1)
	v_mfma_f32_32x32x16_bf16 v[34:49], v[212:215], v[216:219], v[34:49]
	v_mfma_f32_32x32x16_bf16 v[50:65], v[212:215], v[228:231], v[50:65]
	v_mfma_f32_32x32x16_bf16 v[2:17], v[220:223], v[224:227], v[2:17]
	v_mfma_f32_32x32x16_bf16 v[18:33], v[220:223], v[232:235], v[18:33]
	s_waitcnt lgkmcnt(0)
	v_mfma_f32_32x32x16_bf16 v[34:49], v[236:239], v[224:227], v[34:49]
	ds_read_b128 v[212:215], v66 offset:64
	ds_read_b128 v[216:219], v67 offset:36928
	ds_read_b128 v[220:223], v66 offset:96
	ds_read_b128 v[224:227], v67 offset:36960
	v_mfma_f32_32x32x16_bf16 v[50:65], v[236:239], v[232:235], v[50:65]
	ds_read_b128 v[228:231], v67 offset:41536
	ds_read_b128 v[232:235], v67 offset:41568
	s_waitcnt lgkmcnt(4)
	v_mfma_f32_32x32x16_bf16 v[2:17], v[212:215], v[216:219], v[2:17]
	s_waitcnt lgkmcnt(1)
	v_mfma_f32_32x32x16_bf16 v[18:33], v[212:215], v[228:231], v[18:33]
	ds_read_b128 v[212:215], v66 offset:4672
	ds_read_b128 v[236:239], v66 offset:4704
	s_waitcnt vmcnt(13)
	ds_write_b128 v1, v[156:159] offset:18432
	ds_write_b128 v1, v[148:151] offset:23040
	ds_write_b128 v1, v[152:155] offset:27648
	s_waitcnt vmcnt(11)
	ds_write_b128 v1, v[164:167] offset:32256
	ds_write_b128 v1, v[160:163] offset:55296
	s_waitcnt vmcnt(10)
	ds_write_b128 v1, v[168:171] offset:59904
	s_waitcnt vmcnt(9)
	ds_write_b128 v1, v[172:175] offset:64512
	s_waitcnt vmcnt(8)
	ds_write_b128 v92, v[176:179] offset:32256
	global_load_dwordx4 v[148:151], v[80:81], off offset:896
	global_load_dwordx4 v[152:155], v[82:83], off offset:896
	global_load_dwordx4 v[156:159], v[78:79], off offset:896
	global_load_dwordx4 v[160:163], v[76:77], off offset:896
	global_load_dwordx4 v[164:167], v[90:91], off offset:896
	global_load_dwordx4 v[168:171], v[84:85], off offset:896
	global_load_dwordx4 v[172:175], v[86:87], off offset:896
	global_load_dwordx4 v[176:179], v[88:89], off offset:896
	s_waitcnt lgkmcnt(0)
	s_barrier
	v_mfma_f32_32x32x16_bf16 v[34:49], v[212:215], v[216:219], v[34:49]
	v_mfma_f32_32x32x16_bf16 v[50:65], v[212:215], v[228:231], v[50:65]
	v_mfma_f32_32x32x16_bf16 v[2:17], v[220:223], v[224:227], v[2:17]
	v_mfma_f32_32x32x16_bf16 v[18:33], v[220:223], v[232:235], v[18:33]
	v_mfma_f32_32x32x16_bf16 v[34:49], v[236:239], v[224:227], v[34:49]
	v_mfma_f32_32x32x16_bf16 v[50:65], v[236:239], v[232:235], v[50:65]
	ds_read_b128 v[212:215], v66 offset:18432
	ds_read_b128 v[216:219], v67 offset:55296
	ds_read_b128 v[220:223], v66 offset:18464
	ds_read_b128 v[224:227], v67 offset:55328
	ds_read_b128 v[228:231], v67 offset:59904
	ds_read_b128 v[232:235], v67 offset:59936
	s_waitcnt lgkmcnt(4)
	v_mfma_f32_32x32x16_bf16 v[2:17], v[212:215], v[216:219], v[2:17]
	s_waitcnt lgkmcnt(1)
	v_mfma_f32_32x32x16_bf16 v[18:33], v[212:215], v[228:231], v[18:33]
	ds_read_b128 v[212:215], v66 offset:23040
	ds_read_b128 v[236:239], v66 offset:23072
	s_waitcnt lgkmcnt(1)
	v_mfma_f32_32x32x16_bf16 v[34:49], v[212:215], v[216:219], v[34:49]
	v_mfma_f32_32x32x16_bf16 v[50:65], v[212:215], v[228:231], v[50:65]
	v_mfma_f32_32x32x16_bf16 v[2:17], v[220:223], v[224:227], v[2:17]
	v_mfma_f32_32x32x16_bf16 v[18:33], v[220:223], v[232:235], v[18:33]
	s_waitcnt lgkmcnt(0)
	v_mfma_f32_32x32x16_bf16 v[34:49], v[236:239], v[224:227], v[34:49]
	ds_read_b128 v[212:215], v66 offset:18496
	ds_read_b128 v[216:219], v67 offset:55360
	ds_read_b128 v[220:223], v66 offset:18528
	ds_read_b128 v[224:227], v67 offset:55392
	v_mfma_f32_32x32x16_bf16 v[50:65], v[236:239], v[232:235], v[50:65]
	ds_read_b128 v[228:231], v67 offset:59968
	ds_read_b128 v[232:235], v67 offset:60000
	s_waitcnt lgkmcnt(4)
	v_mfma_f32_32x32x16_bf16 v[2:17], v[212:215], v[216:219], v[2:17]
	s_waitcnt lgkmcnt(1)
	v_mfma_f32_32x32x16_bf16 v[18:33], v[212:215], v[228:231], v[18:33]
	ds_read_b128 v[212:215], v66 offset:23104
	ds_read_b128 v[236:239], v66 offset:23136
	s_waitcnt vmcnt(13)
	ds_write_b128 v1, v[188:191]
	ds_write_b128 v1, v[180:183] offset:4608
	ds_write_b128 v1, v[184:187] offset:9216
	s_waitcnt vmcnt(11)
	ds_write_b128 v1, v[196:199] offset:13824
	ds_write_b128 v1, v[192:195] offset:36864
	s_waitcnt vmcnt(10)
	ds_write_b128 v1, v[200:203] offset:41472
	s_waitcnt vmcnt(9)
	ds_write_b128 v1, v[204:207] offset:46080
	s_waitcnt vmcnt(8)
	ds_write_b128 v1, v[208:211] offset:50688
	global_load_dwordx4 v[180:183], v[80:81], off offset:1024
	global_load_dwordx4 v[184:187], v[82:83], off offset:1024
	global_load_dwordx4 v[188:191], v[78:79], off offset:1024
	global_load_dwordx4 v[192:195], v[76:77], off offset:1024
	global_load_dwordx4 v[196:199], v[90:91], off offset:1024
	global_load_dwordx4 v[200:203], v[84:85], off offset:1024
	global_load_dwordx4 v[204:207], v[86:87], off offset:1024
	global_load_dwordx4 v[208:211], v[88:89], off offset:1024
	s_waitcnt lgkmcnt(0)
	s_barrier
	v_mfma_f32_32x32x16_bf16 v[34:49], v[212:215], v[216:219], v[34:49]
	v_mfma_f32_32x32x16_bf16 v[50:65], v[212:215], v[228:231], v[50:65]
	v_mfma_f32_32x32x16_bf16 v[2:17], v[220:223], v[224:227], v[2:17]
	v_mfma_f32_32x32x16_bf16 v[18:33], v[220:223], v[232:235], v[18:33]
	v_mfma_f32_32x32x16_bf16 v[34:49], v[236:239], v[224:227], v[34:49]
	v_mfma_f32_32x32x16_bf16 v[50:65], v[236:239], v[232:235], v[50:65]
	ds_read_b128 v[212:215], v66
	ds_read_b128 v[216:219], v67 offset:36864
	ds_read_b128 v[220:223], v66 offset:32
	ds_read_b128 v[224:227], v67 offset:36896
	ds_read_b128 v[228:231], v67 offset:41472
	ds_read_b128 v[232:235], v67 offset:41504
	s_waitcnt lgkmcnt(4)
	v_mfma_f32_32x32x16_bf16 v[2:17], v[212:215], v[216:219], v[2:17]
	s_waitcnt lgkmcnt(1)
	v_mfma_f32_32x32x16_bf16 v[18:33], v[212:215], v[228:231], v[18:33]
	ds_read_b128 v[212:215], v66 offset:4608
	ds_read_b128 v[236:239], v66 offset:4640
	s_waitcnt lgkmcnt(1)
	v_mfma_f32_32x32x16_bf16 v[34:49], v[212:215], v[216:219], v[34:49]
	v_mfma_f32_32x32x16_bf16 v[50:65], v[212:215], v[228:231], v[50:65]
	v_mfma_f32_32x32x16_bf16 v[2:17], v[220:223], v[224:227], v[2:17]
	v_mfma_f32_32x32x16_bf16 v[18:33], v[220:223], v[232:235], v[18:33]
	s_waitcnt lgkmcnt(0)
	v_mfma_f32_32x32x16_bf16 v[34:49], v[236:239], v[224:227], v[34:49]
	ds_read_b128 v[212:215], v66 offset:64
	ds_read_b128 v[216:219], v67 offset:36928
	ds_read_b128 v[220:223], v66 offset:96
	ds_read_b128 v[224:227], v67 offset:36960
	v_mfma_f32_32x32x16_bf16 v[50:65], v[236:239], v[232:235], v[50:65]
	ds_read_b128 v[228:231], v67 offset:41536
	ds_read_b128 v[232:235], v67 offset:41568
	s_waitcnt lgkmcnt(4)
	v_mfma_f32_32x32x16_bf16 v[2:17], v[212:215], v[216:219], v[2:17]
	s_waitcnt lgkmcnt(1)
	v_mfma_f32_32x32x16_bf16 v[18:33], v[212:215], v[228:231], v[18:33]
	ds_read_b128 v[212:215], v66 offset:4672
	ds_read_b128 v[236:239], v66 offset:4704
	s_waitcnt vmcnt(13)
	ds_write_b128 v1, v[156:159] offset:18432
	ds_write_b128 v1, v[148:151] offset:23040
	ds_write_b128 v1, v[152:155] offset:27648
	s_waitcnt vmcnt(11)
	ds_write_b128 v1, v[164:167] offset:32256
	ds_write_b128 v1, v[160:163] offset:55296
	s_waitcnt vmcnt(10)
	ds_write_b128 v1, v[168:171] offset:59904
	s_waitcnt vmcnt(9)
	ds_write_b128 v1, v[172:175] offset:64512
	s_waitcnt vmcnt(8)
	ds_write_b128 v92, v[176:179] offset:32256
	global_load_dwordx4 v[148:151], v[80:81], off offset:1152
	global_load_dwordx4 v[152:155], v[82:83], off offset:1152
	global_load_dwordx4 v[156:159], v[78:79], off offset:1152
	global_load_dwordx4 v[160:163], v[76:77], off offset:1152
	global_load_dwordx4 v[164:167], v[90:91], off offset:1152
	global_load_dwordx4 v[168:171], v[84:85], off offset:1152
	global_load_dwordx4 v[172:175], v[86:87], off offset:1152
	global_load_dwordx4 v[176:179], v[88:89], off offset:1152
	s_waitcnt lgkmcnt(0)
	s_barrier
	v_mfma_f32_32x32x16_bf16 v[34:49], v[212:215], v[216:219], v[34:49]
	v_mfma_f32_32x32x16_bf16 v[50:65], v[212:215], v[228:231], v[50:65]
	v_mfma_f32_32x32x16_bf16 v[2:17], v[220:223], v[224:227], v[2:17]
	v_mfma_f32_32x32x16_bf16 v[18:33], v[220:223], v[232:235], v[18:33]
	v_mfma_f32_32x32x16_bf16 v[34:49], v[236:239], v[224:227], v[34:49]
	v_mfma_f32_32x32x16_bf16 v[50:65], v[236:239], v[232:235], v[50:65]
	ds_read_b128 v[212:215], v66 offset:18432
	ds_read_b128 v[216:219], v67 offset:55296
	ds_read_b128 v[220:223], v66 offset:18464
	ds_read_b128 v[224:227], v67 offset:55328
	ds_read_b128 v[228:231], v67 offset:59904
	ds_read_b128 v[232:235], v67 offset:59936
	s_waitcnt lgkmcnt(4)
	v_mfma_f32_32x32x16_bf16 v[2:17], v[212:215], v[216:219], v[2:17]
	s_waitcnt lgkmcnt(1)
	v_mfma_f32_32x32x16_bf16 v[18:33], v[212:215], v[228:231], v[18:33]
	ds_read_b128 v[212:215], v66 offset:23040
	ds_read_b128 v[236:239], v66 offset:23072
	s_waitcnt lgkmcnt(1)
	v_mfma_f32_32x32x16_bf16 v[34:49], v[212:215], v[216:219], v[34:49]
	v_mfma_f32_32x32x16_bf16 v[50:65], v[212:215], v[228:231], v[50:65]
	v_mfma_f32_32x32x16_bf16 v[2:17], v[220:223], v[224:227], v[2:17]
	v_mfma_f32_32x32x16_bf16 v[18:33], v[220:223], v[232:235], v[18:33]
	s_waitcnt lgkmcnt(0)
	v_mfma_f32_32x32x16_bf16 v[34:49], v[236:239], v[224:227], v[34:49]
	ds_read_b128 v[212:215], v66 offset:18496
	ds_read_b128 v[216:219], v67 offset:55360
	ds_read_b128 v[220:223], v66 offset:18528
	ds_read_b128 v[224:227], v67 offset:55392
	v_mfma_f32_32x32x16_bf16 v[50:65], v[236:239], v[232:235], v[50:65]
	ds_read_b128 v[228:231], v67 offset:59968
	ds_read_b128 v[232:235], v67 offset:60000
	s_waitcnt lgkmcnt(4)
	v_mfma_f32_32x32x16_bf16 v[2:17], v[212:215], v[216:219], v[2:17]
	s_waitcnt lgkmcnt(1)
	v_mfma_f32_32x32x16_bf16 v[18:33], v[212:215], v[228:231], v[18:33]
	ds_read_b128 v[212:215], v66 offset:23104
	ds_read_b128 v[236:239], v66 offset:23136
	s_waitcnt vmcnt(13)
	ds_write_b128 v1, v[188:191]
	ds_write_b128 v1, v[180:183] offset:4608
	ds_write_b128 v1, v[184:187] offset:9216
	s_waitcnt vmcnt(11)
	ds_write_b128 v1, v[196:199] offset:13824
	ds_write_b128 v1, v[192:195] offset:36864
	s_waitcnt vmcnt(10)
	ds_write_b128 v1, v[200:203] offset:41472
	s_waitcnt vmcnt(9)
	ds_write_b128 v1, v[204:207] offset:46080
	s_waitcnt vmcnt(8)
	ds_write_b128 v1, v[208:211] offset:50688
	global_load_dwordx4 v[180:183], v[80:81], off offset:1280
	global_load_dwordx4 v[184:187], v[82:83], off offset:1280
	global_load_dwordx4 v[188:191], v[78:79], off offset:1280
	global_load_dwordx4 v[192:195], v[76:77], off offset:1280
	global_load_dwordx4 v[196:199], v[90:91], off offset:1280
	global_load_dwordx4 v[200:203], v[84:85], off offset:1280
	global_load_dwordx4 v[204:207], v[86:87], off offset:1280
	global_load_dwordx4 v[208:211], v[88:89], off offset:1280
	s_waitcnt lgkmcnt(0)
	s_barrier
	v_mfma_f32_32x32x16_bf16 v[34:49], v[212:215], v[216:219], v[34:49]
	v_mfma_f32_32x32x16_bf16 v[50:65], v[212:215], v[228:231], v[50:65]
	v_mfma_f32_32x32x16_bf16 v[2:17], v[220:223], v[224:227], v[2:17]
	v_mfma_f32_32x32x16_bf16 v[18:33], v[220:223], v[232:235], v[18:33]
	v_mfma_f32_32x32x16_bf16 v[34:49], v[236:239], v[224:227], v[34:49]
	v_mfma_f32_32x32x16_bf16 v[50:65], v[236:239], v[232:235], v[50:65]
	ds_read_b128 v[212:215], v66
	ds_read_b128 v[216:219], v67 offset:36864
	ds_read_b128 v[220:223], v66 offset:32
	ds_read_b128 v[224:227], v67 offset:36896
	ds_read_b128 v[228:231], v67 offset:41472
	ds_read_b128 v[232:235], v67 offset:41504
	s_waitcnt lgkmcnt(4)
	v_mfma_f32_32x32x16_bf16 v[2:17], v[212:215], v[216:219], v[2:17]
	s_waitcnt lgkmcnt(1)
	v_mfma_f32_32x32x16_bf16 v[18:33], v[212:215], v[228:231], v[18:33]
	ds_read_b128 v[212:215], v66 offset:4608
	ds_read_b128 v[236:239], v66 offset:4640
	s_waitcnt lgkmcnt(1)
	v_mfma_f32_32x32x16_bf16 v[34:49], v[212:215], v[216:219], v[34:49]
	v_mfma_f32_32x32x16_bf16 v[50:65], v[212:215], v[228:231], v[50:65]
	v_mfma_f32_32x32x16_bf16 v[2:17], v[220:223], v[224:227], v[2:17]
	v_mfma_f32_32x32x16_bf16 v[18:33], v[220:223], v[232:235], v[18:33]
	s_waitcnt lgkmcnt(0)
	v_mfma_f32_32x32x16_bf16 v[34:49], v[236:239], v[224:227], v[34:49]
	ds_read_b128 v[212:215], v66 offset:64
	ds_read_b128 v[216:219], v67 offset:36928
	ds_read_b128 v[220:223], v66 offset:96
	ds_read_b128 v[224:227], v67 offset:36960
	v_mfma_f32_32x32x16_bf16 v[50:65], v[236:239], v[232:235], v[50:65]
	ds_read_b128 v[228:231], v67 offset:41536
	ds_read_b128 v[232:235], v67 offset:41568
	s_waitcnt lgkmcnt(4)
	v_mfma_f32_32x32x16_bf16 v[2:17], v[212:215], v[216:219], v[2:17]
	s_waitcnt lgkmcnt(1)
	v_mfma_f32_32x32x16_bf16 v[18:33], v[212:215], v[228:231], v[18:33]
	ds_read_b128 v[212:215], v66 offset:4672
	ds_read_b128 v[236:239], v66 offset:4704
	s_waitcnt vmcnt(13)
	ds_write_b128 v1, v[156:159] offset:18432
	ds_write_b128 v1, v[148:151] offset:23040
	ds_write_b128 v1, v[152:155] offset:27648
	s_waitcnt vmcnt(11)
	ds_write_b128 v1, v[164:167] offset:32256
	ds_write_b128 v1, v[160:163] offset:55296
	s_waitcnt vmcnt(10)
	ds_write_b128 v1, v[168:171] offset:59904
	s_waitcnt vmcnt(9)
	ds_write_b128 v1, v[172:175] offset:64512
	s_waitcnt vmcnt(8)
	ds_write_b128 v92, v[176:179] offset:32256
	global_load_dwordx4 v[148:151], v[80:81], off offset:1408
	global_load_dwordx4 v[152:155], v[82:83], off offset:1408
	global_load_dwordx4 v[156:159], v[78:79], off offset:1408
	global_load_dwordx4 v[160:163], v[76:77], off offset:1408
	global_load_dwordx4 v[164:167], v[90:91], off offset:1408
	global_load_dwordx4 v[168:171], v[84:85], off offset:1408
	global_load_dwordx4 v[172:175], v[86:87], off offset:1408
	global_load_dwordx4 v[176:179], v[88:89], off offset:1408
	s_waitcnt lgkmcnt(0)
	s_barrier
	v_mfma_f32_32x32x16_bf16 v[34:49], v[212:215], v[216:219], v[34:49]
	v_mfma_f32_32x32x16_bf16 v[50:65], v[212:215], v[228:231], v[50:65]
	v_mfma_f32_32x32x16_bf16 v[2:17], v[220:223], v[224:227], v[2:17]
	v_mfma_f32_32x32x16_bf16 v[18:33], v[220:223], v[232:235], v[18:33]
	v_mfma_f32_32x32x16_bf16 v[34:49], v[236:239], v[224:227], v[34:49]
	v_mfma_f32_32x32x16_bf16 v[50:65], v[236:239], v[232:235], v[50:65]
	ds_read_b128 v[212:215], v66 offset:18432
	ds_read_b128 v[216:219], v67 offset:55296
	ds_read_b128 v[220:223], v66 offset:18464
	ds_read_b128 v[224:227], v67 offset:55328
	ds_read_b128 v[228:231], v67 offset:59904
	ds_read_b128 v[232:235], v67 offset:59936
	s_waitcnt lgkmcnt(4)
	v_mfma_f32_32x32x16_bf16 v[2:17], v[212:215], v[216:219], v[2:17]
	s_waitcnt lgkmcnt(1)
	v_mfma_f32_32x32x16_bf16 v[18:33], v[212:215], v[228:231], v[18:33]
	ds_read_b128 v[212:215], v66 offset:23040
	ds_read_b128 v[236:239], v66 offset:23072
	s_waitcnt lgkmcnt(1)
	v_mfma_f32_32x32x16_bf16 v[34:49], v[212:215], v[216:219], v[34:49]
	v_mfma_f32_32x32x16_bf16 v[50:65], v[212:215], v[228:231], v[50:65]
	v_mfma_f32_32x32x16_bf16 v[2:17], v[220:223], v[224:227], v[2:17]
	v_mfma_f32_32x32x16_bf16 v[18:33], v[220:223], v[232:235], v[18:33]
	s_waitcnt lgkmcnt(0)
	v_mfma_f32_32x32x16_bf16 v[34:49], v[236:239], v[224:227], v[34:49]
	ds_read_b128 v[212:215], v66 offset:18496
	ds_read_b128 v[216:219], v67 offset:55360
	ds_read_b128 v[220:223], v66 offset:18528
	ds_read_b128 v[224:227], v67 offset:55392
	v_mfma_f32_32x32x16_bf16 v[50:65], v[236:239], v[232:235], v[50:65]
	ds_read_b128 v[228:231], v67 offset:59968
	ds_read_b128 v[232:235], v67 offset:60000
	s_waitcnt lgkmcnt(4)
	v_mfma_f32_32x32x16_bf16 v[2:17], v[212:215], v[216:219], v[2:17]
	s_waitcnt lgkmcnt(1)
	v_mfma_f32_32x32x16_bf16 v[18:33], v[212:215], v[228:231], v[18:33]
	ds_read_b128 v[212:215], v66 offset:23104
	ds_read_b128 v[236:239], v66 offset:23136
	s_waitcnt vmcnt(13)
	ds_write_b128 v1, v[188:191]
	ds_write_b128 v1, v[180:183] offset:4608
	ds_write_b128 v1, v[184:187] offset:9216
	s_waitcnt vmcnt(11)
	ds_write_b128 v1, v[196:199] offset:13824
	ds_write_b128 v1, v[192:195] offset:36864
	s_waitcnt vmcnt(10)
	ds_write_b128 v1, v[200:203] offset:41472
	s_waitcnt vmcnt(9)
	ds_write_b128 v1, v[204:207] offset:46080
	s_waitcnt vmcnt(8)
	ds_write_b128 v1, v[208:211] offset:50688
	global_load_dwordx4 v[180:183], v[80:81], off offset:1536
	global_load_dwordx4 v[184:187], v[82:83], off offset:1536
	global_load_dwordx4 v[188:191], v[78:79], off offset:1536
	global_load_dwordx4 v[192:195], v[76:77], off offset:1536
	global_load_dwordx4 v[196:199], v[90:91], off offset:1536
	global_load_dwordx4 v[200:203], v[84:85], off offset:1536
	global_load_dwordx4 v[204:207], v[86:87], off offset:1536
	global_load_dwordx4 v[208:211], v[88:89], off offset:1536
	s_waitcnt lgkmcnt(0)
	s_barrier
	v_mfma_f32_32x32x16_bf16 v[34:49], v[212:215], v[216:219], v[34:49]
	v_mfma_f32_32x32x16_bf16 v[50:65], v[212:215], v[228:231], v[50:65]
	v_mfma_f32_32x32x16_bf16 v[2:17], v[220:223], v[224:227], v[2:17]
	v_mfma_f32_32x32x16_bf16 v[18:33], v[220:223], v[232:235], v[18:33]
	v_mfma_f32_32x32x16_bf16 v[34:49], v[236:239], v[224:227], v[34:49]
	v_mfma_f32_32x32x16_bf16 v[50:65], v[236:239], v[232:235], v[50:65]
	ds_read_b128 v[212:215], v66
	ds_read_b128 v[216:219], v67 offset:36864
	ds_read_b128 v[220:223], v66 offset:32
	ds_read_b128 v[224:227], v67 offset:36896
	ds_read_b128 v[228:231], v67 offset:41472
	ds_read_b128 v[232:235], v67 offset:41504
	s_waitcnt lgkmcnt(4)
	v_mfma_f32_32x32x16_bf16 v[2:17], v[212:215], v[216:219], v[2:17]
	s_waitcnt lgkmcnt(1)
	v_mfma_f32_32x32x16_bf16 v[18:33], v[212:215], v[228:231], v[18:33]
	ds_read_b128 v[212:215], v66 offset:4608
	ds_read_b128 v[236:239], v66 offset:4640
	s_waitcnt lgkmcnt(1)
	v_mfma_f32_32x32x16_bf16 v[34:49], v[212:215], v[216:219], v[34:49]
	v_mfma_f32_32x32x16_bf16 v[50:65], v[212:215], v[228:231], v[50:65]
	v_mfma_f32_32x32x16_bf16 v[2:17], v[220:223], v[224:227], v[2:17]
	v_mfma_f32_32x32x16_bf16 v[18:33], v[220:223], v[232:235], v[18:33]
	s_waitcnt lgkmcnt(0)
	v_mfma_f32_32x32x16_bf16 v[34:49], v[236:239], v[224:227], v[34:49]
	ds_read_b128 v[212:215], v66 offset:64
	ds_read_b128 v[216:219], v67 offset:36928
	ds_read_b128 v[220:223], v66 offset:96
	ds_read_b128 v[224:227], v67 offset:36960
	v_mfma_f32_32x32x16_bf16 v[50:65], v[236:239], v[232:235], v[50:65]
	ds_read_b128 v[228:231], v67 offset:41536
	ds_read_b128 v[232:235], v67 offset:41568
	s_waitcnt lgkmcnt(4)
	v_mfma_f32_32x32x16_bf16 v[2:17], v[212:215], v[216:219], v[2:17]
	s_waitcnt lgkmcnt(1)
	v_mfma_f32_32x32x16_bf16 v[18:33], v[212:215], v[228:231], v[18:33]
	ds_read_b128 v[212:215], v66 offset:4672
	ds_read_b128 v[236:239], v66 offset:4704
	s_waitcnt vmcnt(13)
	ds_write_b128 v1, v[156:159] offset:18432
	ds_write_b128 v1, v[148:151] offset:23040
	ds_write_b128 v1, v[152:155] offset:27648
	s_waitcnt vmcnt(11)
	ds_write_b128 v1, v[164:167] offset:32256
	ds_write_b128 v1, v[160:163] offset:55296
	s_waitcnt vmcnt(10)
	ds_write_b128 v1, v[168:171] offset:59904
	s_waitcnt vmcnt(9)
	ds_write_b128 v1, v[172:175] offset:64512
	s_waitcnt vmcnt(8)
	ds_write_b128 v92, v[176:179] offset:32256
	global_load_dwordx4 v[148:151], v[80:81], off offset:1664
	global_load_dwordx4 v[152:155], v[82:83], off offset:1664
	global_load_dwordx4 v[156:159], v[78:79], off offset:1664
	global_load_dwordx4 v[160:163], v[76:77], off offset:1664
	global_load_dwordx4 v[164:167], v[90:91], off offset:1664
	global_load_dwordx4 v[168:171], v[84:85], off offset:1664
	global_load_dwordx4 v[172:175], v[86:87], off offset:1664
	global_load_dwordx4 v[176:179], v[88:89], off offset:1664
	s_waitcnt lgkmcnt(0)
	s_barrier
	v_mfma_f32_32x32x16_bf16 v[34:49], v[212:215], v[216:219], v[34:49]
	v_mfma_f32_32x32x16_bf16 v[50:65], v[212:215], v[228:231], v[50:65]
	v_mfma_f32_32x32x16_bf16 v[2:17], v[220:223], v[224:227], v[2:17]
	v_mfma_f32_32x32x16_bf16 v[18:33], v[220:223], v[232:235], v[18:33]
	v_mfma_f32_32x32x16_bf16 v[34:49], v[236:239], v[224:227], v[34:49]
	v_mfma_f32_32x32x16_bf16 v[50:65], v[236:239], v[232:235], v[50:65]
	ds_read_b128 v[212:215], v66 offset:18432
	ds_read_b128 v[216:219], v67 offset:55296
	ds_read_b128 v[220:223], v66 offset:18464
	ds_read_b128 v[224:227], v67 offset:55328
	ds_read_b128 v[228:231], v67 offset:59904
	ds_read_b128 v[232:235], v67 offset:59936
	s_waitcnt lgkmcnt(4)
	v_mfma_f32_32x32x16_bf16 v[2:17], v[212:215], v[216:219], v[2:17]
	s_waitcnt lgkmcnt(1)
	v_mfma_f32_32x32x16_bf16 v[18:33], v[212:215], v[228:231], v[18:33]
	ds_read_b128 v[212:215], v66 offset:23040
	ds_read_b128 v[236:239], v66 offset:23072
	s_waitcnt lgkmcnt(1)
	v_mfma_f32_32x32x16_bf16 v[34:49], v[212:215], v[216:219], v[34:49]
	v_mfma_f32_32x32x16_bf16 v[50:65], v[212:215], v[228:231], v[50:65]
	v_mfma_f32_32x32x16_bf16 v[2:17], v[220:223], v[224:227], v[2:17]
	v_mfma_f32_32x32x16_bf16 v[18:33], v[220:223], v[232:235], v[18:33]
	s_waitcnt lgkmcnt(0)
	v_mfma_f32_32x32x16_bf16 v[34:49], v[236:239], v[224:227], v[34:49]
	ds_read_b128 v[212:215], v66 offset:18496
	ds_read_b128 v[216:219], v67 offset:55360
	ds_read_b128 v[220:223], v66 offset:18528
	ds_read_b128 v[224:227], v67 offset:55392
	v_mfma_f32_32x32x16_bf16 v[50:65], v[236:239], v[232:235], v[50:65]
	ds_read_b128 v[228:231], v67 offset:59968
	ds_read_b128 v[232:235], v67 offset:60000
	s_waitcnt lgkmcnt(4)
	v_mfma_f32_32x32x16_bf16 v[2:17], v[212:215], v[216:219], v[2:17]
	s_waitcnt lgkmcnt(1)
	v_mfma_f32_32x32x16_bf16 v[18:33], v[212:215], v[228:231], v[18:33]
	ds_read_b128 v[212:215], v66 offset:23104
	ds_read_b128 v[236:239], v66 offset:23136
	s_waitcnt vmcnt(13)
	ds_write_b128 v1, v[188:191]
	ds_write_b128 v1, v[180:183] offset:4608
	ds_write_b128 v1, v[184:187] offset:9216
	s_waitcnt vmcnt(11)
	ds_write_b128 v1, v[196:199] offset:13824
	ds_write_b128 v1, v[192:195] offset:36864
	s_waitcnt vmcnt(10)
	ds_write_b128 v1, v[200:203] offset:41472
	s_waitcnt vmcnt(9)
	ds_write_b128 v1, v[204:207] offset:46080
	s_waitcnt vmcnt(8)
	ds_write_b128 v1, v[208:211] offset:50688
	global_load_dwordx4 v[180:183], v[80:81], off offset:1792
	global_load_dwordx4 v[184:187], v[82:83], off offset:1792
	global_load_dwordx4 v[188:191], v[78:79], off offset:1792
	global_load_dwordx4 v[192:195], v[76:77], off offset:1792
	global_load_dwordx4 v[196:199], v[90:91], off offset:1792
	global_load_dwordx4 v[200:203], v[84:85], off offset:1792
	global_load_dwordx4 v[204:207], v[86:87], off offset:1792
	global_load_dwordx4 v[208:211], v[88:89], off offset:1792
	s_waitcnt lgkmcnt(0)
	s_barrier
	v_mfma_f32_32x32x16_bf16 v[34:49], v[212:215], v[216:219], v[34:49]
	v_mfma_f32_32x32x16_bf16 v[50:65], v[212:215], v[228:231], v[50:65]
	v_mfma_f32_32x32x16_bf16 v[2:17], v[220:223], v[224:227], v[2:17]
	v_mfma_f32_32x32x16_bf16 v[18:33], v[220:223], v[232:235], v[18:33]
	v_mfma_f32_32x32x16_bf16 v[34:49], v[236:239], v[224:227], v[34:49]
	v_mfma_f32_32x32x16_bf16 v[50:65], v[236:239], v[232:235], v[50:65]
	ds_read_b128 v[212:215], v66
	ds_read_b128 v[216:219], v67 offset:36864
	ds_read_b128 v[220:223], v66 offset:32
	ds_read_b128 v[224:227], v67 offset:36896
	ds_read_b128 v[228:231], v67 offset:41472
	ds_read_b128 v[232:235], v67 offset:41504
	s_waitcnt lgkmcnt(4)
	v_mfma_f32_32x32x16_bf16 v[2:17], v[212:215], v[216:219], v[2:17]
	s_waitcnt lgkmcnt(1)
	v_mfma_f32_32x32x16_bf16 v[18:33], v[212:215], v[228:231], v[18:33]
	ds_read_b128 v[212:215], v66 offset:4608
	ds_read_b128 v[236:239], v66 offset:4640
	s_waitcnt lgkmcnt(1)
	v_mfma_f32_32x32x16_bf16 v[34:49], v[212:215], v[216:219], v[34:49]
	v_mfma_f32_32x32x16_bf16 v[50:65], v[212:215], v[228:231], v[50:65]
	v_mfma_f32_32x32x16_bf16 v[2:17], v[220:223], v[224:227], v[2:17]
	v_mfma_f32_32x32x16_bf16 v[18:33], v[220:223], v[232:235], v[18:33]
	s_waitcnt lgkmcnt(0)
	v_mfma_f32_32x32x16_bf16 v[34:49], v[236:239], v[224:227], v[34:49]
	ds_read_b128 v[212:215], v66 offset:64
	ds_read_b128 v[216:219], v67 offset:36928
	ds_read_b128 v[220:223], v66 offset:96
	ds_read_b128 v[224:227], v67 offset:36960
	v_mfma_f32_32x32x16_bf16 v[50:65], v[236:239], v[232:235], v[50:65]
	ds_read_b128 v[228:231], v67 offset:41536
	ds_read_b128 v[232:235], v67 offset:41568
	s_waitcnt lgkmcnt(4)
	v_mfma_f32_32x32x16_bf16 v[2:17], v[212:215], v[216:219], v[2:17]
	s_waitcnt lgkmcnt(1)
	v_mfma_f32_32x32x16_bf16 v[18:33], v[212:215], v[228:231], v[18:33]
	ds_read_b128 v[212:215], v66 offset:4672
	ds_read_b128 v[236:239], v66 offset:4704
	s_waitcnt vmcnt(13)
	ds_write_b128 v1, v[156:159] offset:18432
	ds_write_b128 v1, v[148:151] offset:23040
	ds_write_b128 v1, v[152:155] offset:27648
	s_waitcnt vmcnt(11)
	ds_write_b128 v1, v[164:167] offset:32256
	ds_write_b128 v1, v[160:163] offset:55296
	s_waitcnt vmcnt(10)
	ds_write_b128 v1, v[168:171] offset:59904
	s_waitcnt vmcnt(9)
	ds_write_b128 v1, v[172:175] offset:64512
	s_waitcnt vmcnt(8)
	ds_write_b128 v92, v[176:179] offset:32256
	s_waitcnt lgkmcnt(0)
	s_barrier
	global_load_dwordx4 v[148:151], v[80:81], off offset:1920
	s_nop 0
	global_load_dwordx4 v[80:83], v[82:83], off offset:1920
	s_nop 0
	global_load_dwordx4 v[152:155], v[78:79], off offset:1920
	s_nop 0
	global_load_dwordx4 v[76:79], v[76:77], off offset:1920
	s_nop 0
	global_load_dwordx4 v[156:159], v[90:91], off offset:1920
	global_load_dwordx4 v[160:163], v[84:85], off offset:1920
	s_nop 0
	global_load_dwordx4 v[84:87], v[86:87], off offset:1920
	s_nop 0
	global_load_dwordx4 v[88:91], v[88:89], off offset:1920
	v_mfma_f32_32x32x16_bf16 v[34:49], v[212:215], v[216:219], v[34:49]
	v_mfma_f32_32x32x16_bf16 v[50:65], v[212:215], v[228:231], v[50:65]
	v_mfma_f32_32x32x16_bf16 v[2:17], v[220:223], v[224:227], v[2:17]
	v_mfma_f32_32x32x16_bf16 v[18:33], v[220:223], v[232:235], v[18:33]
	v_mfma_f32_32x32x16_bf16 v[34:49], v[236:239], v[224:227], v[34:49]
	v_mfma_f32_32x32x16_bf16 v[50:65], v[236:239], v[232:235], v[50:65]
	ds_read_b128 v[164:167], v66 offset:18432
	ds_read_b128 v[168:171], v67 offset:55296
	ds_read_b128 v[172:175], v66 offset:18464
	ds_read_b128 v[176:179], v67 offset:55328
	ds_read_b128 v[212:215], v67 offset:59904
	ds_read_b128 v[216:219], v67 offset:59936
	s_waitcnt lgkmcnt(4)
	v_mfma_f32_32x32x16_bf16 v[2:17], v[164:167], v[168:171], v[2:17]
	s_waitcnt lgkmcnt(1)
	v_mfma_f32_32x32x16_bf16 v[18:33], v[164:167], v[212:215], v[18:33]
	ds_read_b128 v[164:167], v66 offset:23040
	ds_read_b128 v[220:223], v66 offset:23072
	s_waitcnt lgkmcnt(1)
	v_mfma_f32_32x32x16_bf16 v[34:49], v[164:167], v[168:171], v[34:49]
	v_mfma_f32_32x32x16_bf16 v[50:65], v[164:167], v[212:215], v[50:65]
	v_mfma_f32_32x32x16_bf16 v[2:17], v[172:175], v[176:179], v[2:17]
	v_mfma_f32_32x32x16_bf16 v[18:33], v[172:175], v[216:219], v[18:33]
	s_waitcnt lgkmcnt(0)
	v_mfma_f32_32x32x16_bf16 v[34:49], v[220:223], v[176:179], v[34:49]
	ds_read_b128 v[164:167], v66 offset:18496
	ds_read_b128 v[168:171], v67 offset:55360
	ds_read_b128 v[172:175], v66 offset:18528
	ds_read_b128 v[176:179], v67 offset:55392
	v_mfma_f32_32x32x16_bf16 v[50:65], v[220:223], v[216:219], v[50:65]
	ds_read_b128 v[212:215], v67 offset:59968
	ds_read_b128 v[216:219], v67 offset:60000
	s_waitcnt lgkmcnt(4)
	v_mfma_f32_32x32x16_bf16 v[2:17], v[164:167], v[168:171], v[2:17]
	s_waitcnt lgkmcnt(1)
	v_mfma_f32_32x32x16_bf16 v[18:33], v[164:167], v[212:215], v[18:33]
	ds_read_b128 v[164:167], v66 offset:23104
	ds_read_b128 v[220:223], v66 offset:23136
	s_waitcnt vmcnt(13)
	ds_write_b128 v1, v[188:191]
	ds_write_b128 v1, v[180:183] offset:4608
	ds_write_b128 v1, v[184:187] offset:9216
	s_waitcnt vmcnt(11)
	ds_write_b128 v1, v[196:199] offset:13824
	ds_write_b128 v1, v[192:195] offset:36864
	s_waitcnt vmcnt(10)
	ds_write_b128 v1, v[200:203] offset:41472
	s_waitcnt vmcnt(9)
	ds_write_b128 v1, v[204:207] offset:46080
	s_waitcnt vmcnt(8)
	ds_write_b128 v1, v[208:211] offset:50688
	s_waitcnt lgkmcnt(0)
	s_barrier
	v_mfma_f32_32x32x16_bf16 v[34:49], v[164:167], v[168:171], v[34:49]
	v_mfma_f32_32x32x16_bf16 v[50:65], v[164:167], v[212:215], v[50:65]
	v_mfma_f32_32x32x16_bf16 v[2:17], v[172:175], v[176:179], v[2:17]
	v_mfma_f32_32x32x16_bf16 v[18:33], v[172:175], v[216:219], v[18:33]
	v_mfma_f32_32x32x16_bf16 v[34:49], v[220:223], v[176:179], v[34:49]
	v_mfma_f32_32x32x16_bf16 v[50:65], v[220:223], v[216:219], v[50:65]
	ds_read_b128 v[164:167], v66
	ds_read_b128 v[168:171], v67 offset:36864
	ds_read_b128 v[172:175], v66 offset:32
	ds_read_b128 v[176:179], v67 offset:36896
	ds_read_b128 v[180:183], v67 offset:41472
	ds_read_b128 v[184:187], v67 offset:41504
	s_waitcnt lgkmcnt(4)
	v_mfma_f32_32x32x16_bf16 v[2:17], v[164:167], v[168:171], v[2:17]
	s_waitcnt lgkmcnt(1)
	v_mfma_f32_32x32x16_bf16 v[18:33], v[164:167], v[180:183], v[18:33]
	ds_read_b128 v[164:167], v66 offset:4608
	ds_read_b128 v[188:191], v66 offset:4640
	s_waitcnt lgkmcnt(1)
	v_mfma_f32_32x32x16_bf16 v[34:49], v[164:167], v[168:171], v[34:49]
	v_mfma_f32_32x32x16_bf16 v[50:65], v[164:167], v[180:183], v[50:65]
	v_mfma_f32_32x32x16_bf16 v[2:17], v[172:175], v[176:179], v[2:17]
	v_mfma_f32_32x32x16_bf16 v[18:33], v[172:175], v[184:187], v[18:33]
	s_waitcnt lgkmcnt(0)
	v_mfma_f32_32x32x16_bf16 v[34:49], v[188:191], v[176:179], v[34:49]
	ds_read_b128 v[164:167], v66 offset:64
	ds_read_b128 v[168:171], v67 offset:36928
	ds_read_b128 v[172:175], v66 offset:96
	ds_read_b128 v[176:179], v67 offset:36960
	v_mfma_f32_32x32x16_bf16 v[50:65], v[188:191], v[184:187], v[50:65]
	ds_read_b128 v[180:183], v67 offset:41536
	ds_read_b128 v[184:187], v67 offset:41568
	s_waitcnt lgkmcnt(4)
	v_mfma_f32_32x32x16_bf16 v[2:17], v[164:167], v[168:171], v[2:17]
	s_waitcnt lgkmcnt(1)
	v_mfma_f32_32x32x16_bf16 v[18:33], v[164:167], v[180:183], v[18:33]
	ds_read_b128 v[164:167], v66 offset:4672
	ds_read_b128 v[188:191], v66 offset:4704
	s_waitcnt vmcnt(5)
	ds_write_b128 v1, v[152:155] offset:18432
	ds_write_b128 v1, v[148:151] offset:23040
	ds_write_b128 v1, v[80:83] offset:27648
	s_waitcnt vmcnt(3)
	ds_write_b128 v1, v[156:159] offset:32256
	ds_write_b128 v1, v[76:79] offset:55296
	s_waitcnt vmcnt(2)
	ds_write_b128 v1, v[160:163] offset:59904
	s_waitcnt vmcnt(1)
	ds_write_b128 v1, v[84:87] offset:64512
	s_waitcnt vmcnt(0)
	ds_write_b128 v92, v[88:91] offset:32256
	s_waitcnt lgkmcnt(0)
	s_barrier
	v_mfma_f32_32x32x16_bf16 v[34:49], v[164:167], v[168:171], v[34:49]
	v_mfma_f32_32x32x16_bf16 v[50:65], v[164:167], v[180:183], v[50:65]
	v_mfma_f32_32x32x16_bf16 v[2:17], v[172:175], v[176:179], v[2:17]
	v_mfma_f32_32x32x16_bf16 v[18:33], v[172:175], v[184:187], v[18:33]
	v_mfma_f32_32x32x16_bf16 v[34:49], v[188:191], v[176:179], v[34:49]
	v_mfma_f32_32x32x16_bf16 v[50:65], v[188:191], v[184:187], v[50:65]
	ds_read_b128 v[76:79], v66 offset:18432
	ds_read_b128 v[80:83], v67 offset:55296
	ds_read_b128 v[84:87], v66 offset:18464
	ds_read_b128 v[88:91], v67 offset:55328
	ds_read_b128 v[148:151], v67 offset:59904
	ds_read_b128 v[152:155], v67 offset:59936
	v_or_b32_e32 v68, s8, v94
	s_waitcnt lgkmcnt(4)
	v_mfma_f32_32x32x16_bf16 v[2:17], v[76:79], v[80:83], v[2:17]
	s_lshl_b32 s10, s10, 1
	s_mov_b32 s11, s9
	s_add_i32 s12, s12, s13
	s_add_i32 s14, s14, s15
	s_add_i32 s16, s16, s17
	s_cmpk_lt_u32 s12, 0x400
	s_waitcnt lgkmcnt(1)
	v_mfma_f32_32x32x16_bf16 v[18:33], v[76:79], v[148:151], v[18:33]
	ds_read_b128 v[76:79], v66 offset:23040
	ds_read_b128 v[156:159], v66 offset:23072
	s_waitcnt lgkmcnt(1)
	v_mfma_f32_32x32x16_bf16 v[34:49], v[76:79], v[80:83], v[34:49]
	v_mfma_f32_32x32x16_bf16 v[50:65], v[76:79], v[148:151], v[50:65]
	v_mfma_f32_32x32x16_bf16 v[2:17], v[84:87], v[88:91], v[2:17]
	v_mfma_f32_32x32x16_bf16 v[18:33], v[84:87], v[152:155], v[18:33]
	s_waitcnt lgkmcnt(0)
	v_mfma_f32_32x32x16_bf16 v[34:49], v[156:159], v[88:91], v[34:49]
	ds_read_b128 v[76:79], v66 offset:18496
	ds_read_b128 v[80:83], v67 offset:55360
	ds_read_b128 v[84:87], v66 offset:18528
	ds_read_b128 v[88:91], v67 offset:55392
	v_mfma_f32_32x32x16_bf16 v[50:65], v[156:159], v[152:155], v[50:65]
	ds_read_b128 v[148:151], v67 offset:59968
	ds_read_b128 v[152:155], v67 offset:60000
	s_waitcnt lgkmcnt(4)
	v_mfma_f32_32x32x16_bf16 v[2:17], v[76:79], v[80:83], v[2:17]
	s_waitcnt lgkmcnt(1)
	v_mfma_f32_32x32x16_bf16 v[18:33], v[76:79], v[148:151], v[18:33]
	ds_read_b128 v[76:79], v66 offset:23104
	ds_read_b128 v[156:159], v66 offset:23136
	s_waitcnt lgkmcnt(0)
	s_barrier
	v_lshlrev_b32_e32 v168, 2, v68
	global_load_dword v160, v168, s[6:7]
	global_load_dword v161, v168, s[6:7] offset:64
	global_load_dword v162, v168, s[6:7] offset:128
	global_load_dword v163, v168, s[6:7] offset:192
	global_load_dword v164, v168, s[6:7] offset:256
	global_load_dword v165, v168, s[6:7] offset:320
	global_load_dword v166, v168, s[6:7] offset:384
	global_load_dword v167, v168, s[6:7] offset:448
	v_mfma_f32_32x32x16_bf16 v[34:49], v[76:79], v[80:83], v[34:49]
	v_mfma_f32_32x32x16_bf16 v[50:65], v[76:79], v[148:151], v[50:65]
	v_mfma_f32_32x32x16_bf16 v[2:17], v[84:87], v[88:91], v[2:17]
	v_mfma_f32_32x32x16_bf16 v[18:33], v[84:87], v[152:155], v[18:33]
	v_mfma_f32_32x32x16_bf16 v[34:49], v[156:159], v[88:91], v[34:49]
	s_nop 10
	ds_write2_b32 v93, v2, v18 offset1:32
	v_mfma_f32_32x32x16_bf16 v[50:65], v[156:159], v[152:155], v[50:65]
	s_nop 11
	ds_write2_b32 v132, v34, v50 offset0:32 offset1:64
	ds_write2_b32 v93, v3, v19 offset0:129 offset1:161
	ds_write2_b32 v132, v35, v51 offset0:161 offset1:193
	ds_write2_b32 v133, v4, v20 offset0:2 offset1:34
	ds_write2_b32 v134, v36, v52 offset0:34 offset1:66
	ds_write2_b32 v133, v5, v21 offset0:131 offset1:163
	ds_write2_b32 v134, v37, v53 offset0:163 offset1:195
	ds_write2_b32 v135, v6, v22 offset0:8 offset1:40
	ds_write2_b32 v136, v38, v54 offset0:40 offset1:72
	ds_write2_b32 v135, v7, v23 offset0:137 offset1:169
	ds_write2_b32 v136, v39, v55 offset0:169 offset1:201
	ds_write2_b32 v137, v8, v24 offset0:10 offset1:42
	ds_write2_b32 v138, v40, v56 offset0:42 offset1:74
	ds_write2_b32 v137, v9, v25 offset0:139 offset1:171
	ds_write2_b32 v138, v41, v57 offset0:171 offset1:203
	ds_write2_b32 v139, v10, v26 offset0:16 offset1:48
	ds_write2_b32 v140, v42, v58 offset0:48 offset1:80
	ds_write2_b32 v139, v11, v27 offset0:145 offset1:177
	ds_write2_b32 v140, v43, v59 offset0:177 offset1:209
	ds_write2_b32 v141, v12, v28 offset0:18 offset1:50
	ds_write2_b32 v142, v44, v60 offset0:50 offset1:82
	ds_write2_b32 v141, v13, v29 offset0:147 offset1:179
	ds_write2_b32 v142, v45, v61 offset0:179 offset1:211
	ds_write2_b32 v143, v14, v30 offset0:24 offset1:56
	ds_write2_b32 v144, v46, v62 offset0:56 offset1:88
	ds_write2_b32 v143, v15, v31 offset0:153 offset1:185
	ds_write2_b32 v144, v47, v63 offset0:185 offset1:217
	ds_write2_b32 v145, v16, v32 offset0:26 offset1:58
	ds_write2_b32 v146, v48, v64 offset0:58 offset1:90
	ds_write2_b32 v145, v17, v33 offset0:155 offset1:187
	ds_write2_b32 v146, v49, v65 offset0:187 offset1:219
	v_lshl_add_u64 v[2:3], v[68:69], 2, s[6:7]
	s_waitcnt lgkmcnt(0)
	s_barrier
	v_mov_b32_e32 v2, v68
	v_lshlrev_b32_e32 v3, 2, v2
	v_lshlrev_b32_e32 v4, 13, v2
	v_add3_u32 v4, v4, v74, s10
	s_movk_i32 s24, 0x7fff
	v_mov_b32_e32 v59, 1
	v_mov_b32_e32 v13, 0x358637bd
	ds_read2_b32 v[14:15], v103 offset0:0 offset1:1
	ds_read2_b32 v[16:17], v103 offset0:2 offset1:3
	ds_read2_b32 v[18:19], v103 offset0:4 offset1:5
	ds_read2_b32 v[20:21], v103 offset0:6 offset1:7
	v_add_u32_e32 v56, 0x2040, v103
	ds_read2_b32 v[22:23], v56 offset0:0 offset1:1
	ds_read2_b32 v[24:25], v56 offset0:2 offset1:3
	ds_read2_b32 v[26:27], v56 offset0:4 offset1:5
	ds_read2_b32 v[28:29], v56 offset0:6 offset1:7
	s_waitcnt vmcnt(7) lgkmcnt(4)
	v_fmamk_f32 v54, v160, 0x3a800000, v13
	v_rsq_f32_e32 v54, v54
	s_nop 0
	v_mul_f32_e32 v14, v14, v54
	v_mul_f32_e32 v15, v15, v54
	v_mul_f32_e32 v16, v16, v54
	v_mul_f32_e32 v17, v17, v54
	v_mul_f32_e32 v18, v18, v54
	v_mul_f32_e32 v19, v19, v54
	v_mul_f32_e32 v20, v20, v54
	v_mul_f32_e32 v21, v21, v54
	v_max_f32_e32 v14, 0, v14
	v_max_f32_e32 v15, 0, v15
	v_max_f32_e32 v16, 0, v16
	v_max_f32_e32 v17, 0, v17
	v_max_f32_e32 v18, 0, v18
	v_max_f32_e32 v19, 0, v19
	v_max_f32_e32 v20, 0, v20
	v_max_f32_e32 v21, 0, v21
	v_pk_mul_f32 v[14:15], v[14:15], v[14:15]
	v_pk_mul_f32 v[16:17], v[16:17], v[16:17]
	v_pk_mul_f32 v[18:19], v[18:19], v[18:19]
	v_pk_mul_f32 v[20:21], v[20:21], v[20:21]
	v_and_b32_sdwa v46, v14, v59 dst_sel:DWORD dst_unused:UNUSED_PAD src0_sel:WORD_1 src1_sel:DWORD
	v_and_b32_sdwa v47, v15, v59 dst_sel:DWORD dst_unused:UNUSED_PAD src0_sel:WORD_1 src1_sel:DWORD
	v_and_b32_sdwa v48, v16, v59 dst_sel:DWORD dst_unused:UNUSED_PAD src0_sel:WORD_1 src1_sel:DWORD
	v_and_b32_sdwa v49, v17, v59 dst_sel:DWORD dst_unused:UNUSED_PAD src0_sel:WORD_1 src1_sel:DWORD
	v_and_b32_sdwa v50, v18, v59 dst_sel:DWORD dst_unused:UNUSED_PAD src0_sel:WORD_1 src1_sel:DWORD
	v_and_b32_sdwa v51, v19, v59 dst_sel:DWORD dst_unused:UNUSED_PAD src0_sel:WORD_1 src1_sel:DWORD
	v_and_b32_sdwa v52, v20, v59 dst_sel:DWORD dst_unused:UNUSED_PAD src0_sel:WORD_1 src1_sel:DWORD
	v_and_b32_sdwa v53, v21, v59 dst_sel:DWORD dst_unused:UNUSED_PAD src0_sel:WORD_1 src1_sel:DWORD
	v_add3_u32 v14, v14, v46, s24
	v_add3_u32 v15, v15, v47, s24
	v_add3_u32 v16, v16, v48, s24
	v_add3_u32 v17, v17, v49, s24
	v_add3_u32 v18, v18, v50, s24
	v_add3_u32 v19, v19, v51, s24
	v_add3_u32 v20, v20, v52, s24
	v_add3_u32 v21, v21, v53, s24
	v_and_b32_e32 v15, 0xffff0000, v15
	v_and_b32_e32 v17, 0xffff0000, v17
	v_and_b32_e32 v19, 0xffff0000, v19
	v_and_b32_e32 v21, 0xffff0000, v21
	v_or_b32_sdwa v60, v15, v14 dst_sel:DWORD dst_unused:UNUSED_PAD src0_sel:DWORD src1_sel:WORD_1
	v_or_b32_sdwa v61, v17, v16 dst_sel:DWORD dst_unused:UNUSED_PAD src0_sel:DWORD src1_sel:WORD_1
	v_or_b32_sdwa v62, v19, v18 dst_sel:DWORD dst_unused:UNUSED_PAD src0_sel:DWORD src1_sel:WORD_1
	v_or_b32_sdwa v63, v21, v20 dst_sel:DWORD dst_unused:UNUSED_PAD src0_sel:DWORD src1_sel:WORD_1
	global_store_dwordx4 v4, v[60:63], s[56:57]
	v_add_u32_e32 v55, 0x4080, v103
	ds_read2_b32 v[30:31], v55 offset0:0 offset1:1
	ds_read2_b32 v[32:33], v55 offset0:2 offset1:3
	ds_read2_b32 v[34:35], v55 offset0:4 offset1:5
	ds_read2_b32 v[36:37], v55 offset0:6 offset1:7
	v_add_u32_e32 v56, 0x60c0, v103
	ds_read2_b32 v[38:39], v56 offset0:0 offset1:1
	ds_read2_b32 v[40:41], v56 offset0:2 offset1:3
	ds_read2_b32 v[42:43], v56 offset0:4 offset1:5
	ds_read2_b32 v[44:45], v56 offset0:6 offset1:7
	s_waitcnt vmcnt(7) lgkmcnt(8)
	v_fmamk_f32 v54, v161, 0x3a800000, v13
	v_rsq_f32_e32 v54, v54
	v_add_u32_e32 v58, 0x20000, v4
	v_mul_f32_e32 v22, v22, v54
	v_mul_f32_e32 v23, v23, v54
	v_mul_f32_e32 v24, v24, v54
	v_mul_f32_e32 v25, v25, v54
	v_mul_f32_e32 v26, v26, v54
	v_mul_f32_e32 v27, v27, v54
	v_mul_f32_e32 v28, v28, v54
	v_mul_f32_e32 v29, v29, v54
	v_max_f32_e32 v22, 0, v22
	v_max_f32_e32 v23, 0, v23
	v_max_f32_e32 v24, 0, v24
	v_max_f32_e32 v25, 0, v25
	v_max_f32_e32 v26, 0, v26
	v_max_f32_e32 v27, 0, v27
	v_max_f32_e32 v28, 0, v28
	v_max_f32_e32 v29, 0, v29
	v_pk_mul_f32 v[22:23], v[22:23], v[22:23]
	v_pk_mul_f32 v[24:25], v[24:25], v[24:25]
	v_pk_mul_f32 v[26:27], v[26:27], v[26:27]
	v_pk_mul_f32 v[28:29], v[28:29], v[28:29]
	v_and_b32_sdwa v46, v22, v59 dst_sel:DWORD dst_unused:UNUSED_PAD src0_sel:WORD_1 src1_sel:DWORD
	v_and_b32_sdwa v47, v23, v59 dst_sel:DWORD dst_unused:UNUSED_PAD src0_sel:WORD_1 src1_sel:DWORD
	v_and_b32_sdwa v48, v24, v59 dst_sel:DWORD dst_unused:UNUSED_PAD src0_sel:WORD_1 src1_sel:DWORD
	v_and_b32_sdwa v49, v25, v59 dst_sel:DWORD dst_unused:UNUSED_PAD src0_sel:WORD_1 src1_sel:DWORD
	v_and_b32_sdwa v50, v26, v59 dst_sel:DWORD dst_unused:UNUSED_PAD src0_sel:WORD_1 src1_sel:DWORD
	v_and_b32_sdwa v51, v27, v59 dst_sel:DWORD dst_unused:UNUSED_PAD src0_sel:WORD_1 src1_sel:DWORD
	v_and_b32_sdwa v52, v28, v59 dst_sel:DWORD dst_unused:UNUSED_PAD src0_sel:WORD_1 src1_sel:DWORD
	v_and_b32_sdwa v53, v29, v59 dst_sel:DWORD dst_unused:UNUSED_PAD src0_sel:WORD_1 src1_sel:DWORD
	v_add3_u32 v22, v22, v46, s24
	v_add3_u32 v23, v23, v47, s24
	v_add3_u32 v24, v24, v48, s24
	v_add3_u32 v25, v25, v49, s24
	v_add3_u32 v26, v26, v50, s24
	v_add3_u32 v27, v27, v51, s24
	v_add3_u32 v28, v28, v52, s24
	v_add3_u32 v29, v29, v53, s24
	v_and_b32_e32 v23, 0xffff0000, v23
	v_and_b32_e32 v25, 0xffff0000, v25
	v_and_b32_e32 v27, 0xffff0000, v27
	v_and_b32_e32 v29, 0xffff0000, v29
	v_or_b32_sdwa v76, v23, v22 dst_sel:DWORD dst_unused:UNUSED_PAD src0_sel:DWORD src1_sel:WORD_1
	v_or_b32_sdwa v77, v25, v24 dst_sel:DWORD dst_unused:UNUSED_PAD src0_sel:DWORD src1_sel:WORD_1
	v_or_b32_sdwa v78, v27, v26 dst_sel:DWORD dst_unused:UNUSED_PAD src0_sel:DWORD src1_sel:WORD_1
	v_or_b32_sdwa v79, v29, v28 dst_sel:DWORD dst_unused:UNUSED_PAD src0_sel:DWORD src1_sel:WORD_1
	global_store_dwordx4 v58, v[76:79], s[56:57]
	s_waitcnt vmcnt(7) lgkmcnt(4)
	v_fmamk_f32 v54, v162, 0x3a800000, v13
	v_rsq_f32_e32 v54, v54
	v_add_u32_e32 v57, 0x40000, v4
	v_mul_f32_e32 v30, v30, v54
	v_mul_f32_e32 v31, v31, v54
	v_mul_f32_e32 v32, v32, v54
	v_mul_f32_e32 v33, v33, v54
	v_mul_f32_e32 v34, v34, v54
	v_mul_f32_e32 v35, v35, v54
	v_mul_f32_e32 v36, v36, v54
	v_mul_f32_e32 v37, v37, v54
	v_max_f32_e32 v30, 0, v30
	v_max_f32_e32 v31, 0, v31
	v_max_f32_e32 v32, 0, v32
	v_max_f32_e32 v33, 0, v33
	v_max_f32_e32 v34, 0, v34
	v_max_f32_e32 v35, 0, v35
	v_max_f32_e32 v36, 0, v36
	v_max_f32_e32 v37, 0, v37
	v_pk_mul_f32 v[30:31], v[30:31], v[30:31]
	v_pk_mul_f32 v[32:33], v[32:33], v[32:33]
	v_pk_mul_f32 v[34:35], v[34:35], v[34:35]
	v_pk_mul_f32 v[36:37], v[36:37], v[36:37]
	v_and_b32_sdwa v46, v30, v59 dst_sel:DWORD dst_unused:UNUSED_PAD src0_sel:WORD_1 src1_sel:DWORD
	v_and_b32_sdwa v47, v31, v59 dst_sel:DWORD dst_unused:UNUSED_PAD src0_sel:WORD_1 src1_sel:DWORD
	v_and_b32_sdwa v48, v32, v59 dst_sel:DWORD dst_unused:UNUSED_PAD src0_sel:WORD_1 src1_sel:DWORD
	v_and_b32_sdwa v49, v33, v59 dst_sel:DWORD dst_unused:UNUSED_PAD src0_sel:WORD_1 src1_sel:DWORD
	v_and_b32_sdwa v50, v34, v59 dst_sel:DWORD dst_unused:UNUSED_PAD src0_sel:WORD_1 src1_sel:DWORD
	v_and_b32_sdwa v51, v35, v59 dst_sel:DWORD dst_unused:UNUSED_PAD src0_sel:WORD_1 src1_sel:DWORD
	v_and_b32_sdwa v52, v36, v59 dst_sel:DWORD dst_unused:UNUSED_PAD src0_sel:WORD_1 src1_sel:DWORD
	v_and_b32_sdwa v53, v37, v59 dst_sel:DWORD dst_unused:UNUSED_PAD src0_sel:WORD_1 src1_sel:DWORD
	v_add3_u32 v30, v30, v46, s24
	v_add3_u32 v31, v31, v47, s24
	v_add3_u32 v32, v32, v48, s24
	v_add3_u32 v33, v33, v49, s24
	v_add3_u32 v34, v34, v50, s24
	v_add3_u32 v35, v35, v51, s24
	v_add3_u32 v36, v36, v52, s24
	v_add3_u32 v37, v37, v53, s24
	v_and_b32_e32 v31, 0xffff0000, v31
	v_and_b32_e32 v33, 0xffff0000, v33
	v_and_b32_e32 v35, 0xffff0000, v35
	v_and_b32_e32 v37, 0xffff0000, v37
	v_or_b32_sdwa v60, v31, v30 dst_sel:DWORD dst_unused:UNUSED_PAD src0_sel:DWORD src1_sel:WORD_1
	v_or_b32_sdwa v61, v33, v32 dst_sel:DWORD dst_unused:UNUSED_PAD src0_sel:DWORD src1_sel:WORD_1
	v_or_b32_sdwa v62, v35, v34 dst_sel:DWORD dst_unused:UNUSED_PAD src0_sel:DWORD src1_sel:WORD_1
	v_or_b32_sdwa v63, v37, v36 dst_sel:DWORD dst_unused:UNUSED_PAD src0_sel:DWORD src1_sel:WORD_1
	global_store_dwordx4 v57, v[60:63], s[56:57]
	v_add_u32_e32 v55, 0x8100, v103
	ds_read2_b32 v[14:15], v55 offset0:0 offset1:1
	ds_read2_b32 v[16:17], v55 offset0:2 offset1:3
	ds_read2_b32 v[18:19], v55 offset0:4 offset1:5
	ds_read2_b32 v[20:21], v55 offset0:6 offset1:7
	v_add_u32_e32 v56, 0xa140, v103
	ds_read2_b32 v[22:23], v56 offset0:0 offset1:1
	ds_read2_b32 v[24:25], v56 offset0:2 offset1:3
	ds_read2_b32 v[26:27], v56 offset0:4 offset1:5
	ds_read2_b32 v[28:29], v56 offset0:6 offset1:7
	s_waitcnt vmcnt(7) lgkmcnt(8)
	v_fmamk_f32 v54, v163, 0x3a800000, v13
	v_rsq_f32_e32 v54, v54
	v_add_u32_e32 v58, 0x60000, v4
	v_mul_f32_e32 v38, v38, v54
	v_mul_f32_e32 v39, v39, v54
	v_mul_f32_e32 v40, v40, v54
	v_mul_f32_e32 v41, v41, v54
	v_mul_f32_e32 v42, v42, v54
	v_mul_f32_e32 v43, v43, v54
	v_mul_f32_e32 v44, v44, v54
	v_mul_f32_e32 v45, v45, v54
	v_max_f32_e32 v38, 0, v38
	v_max_f32_e32 v39, 0, v39
	v_max_f32_e32 v40, 0, v40
	v_max_f32_e32 v41, 0, v41
	v_max_f32_e32 v42, 0, v42
	v_max_f32_e32 v43, 0, v43
	v_max_f32_e32 v44, 0, v44
	v_max_f32_e32 v45, 0, v45
	v_pk_mul_f32 v[38:39], v[38:39], v[38:39]
	v_pk_mul_f32 v[40:41], v[40:41], v[40:41]
	v_pk_mul_f32 v[42:43], v[42:43], v[42:43]
	v_pk_mul_f32 v[44:45], v[44:45], v[44:45]
	v_and_b32_sdwa v46, v38, v59 dst_sel:DWORD dst_unused:UNUSED_PAD src0_sel:WORD_1 src1_sel:DWORD
	v_and_b32_sdwa v47, v39, v59 dst_sel:DWORD dst_unused:UNUSED_PAD src0_sel:WORD_1 src1_sel:DWORD
	v_and_b32_sdwa v48, v40, v59 dst_sel:DWORD dst_unused:UNUSED_PAD src0_sel:WORD_1 src1_sel:DWORD
	v_and_b32_sdwa v49, v41, v59 dst_sel:DWORD dst_unused:UNUSED_PAD src0_sel:WORD_1 src1_sel:DWORD
	v_and_b32_sdwa v50, v42, v59 dst_sel:DWORD dst_unused:UNUSED_PAD src0_sel:WORD_1 src1_sel:DWORD
	v_and_b32_sdwa v51, v43, v59 dst_sel:DWORD dst_unused:UNUSED_PAD src0_sel:WORD_1 src1_sel:DWORD
	v_and_b32_sdwa v52, v44, v59 dst_sel:DWORD dst_unused:UNUSED_PAD src0_sel:WORD_1 src1_sel:DWORD
	v_and_b32_sdwa v53, v45, v59 dst_sel:DWORD dst_unused:UNUSED_PAD src0_sel:WORD_1 src1_sel:DWORD
	v_add3_u32 v38, v38, v46, s24
	v_add3_u32 v39, v39, v47, s24
	v_add3_u32 v40, v40, v48, s24
	v_add3_u32 v41, v41, v49, s24
	v_add3_u32 v42, v42, v50, s24
	v_add3_u32 v43, v43, v51, s24
	v_add3_u32 v44, v44, v52, s24
	v_add3_u32 v45, v45, v53, s24
	v_and_b32_e32 v39, 0xffff0000, v39
	v_and_b32_e32 v41, 0xffff0000, v41
	v_and_b32_e32 v43, 0xffff0000, v43
	v_and_b32_e32 v45, 0xffff0000, v45
	v_or_b32_sdwa v76, v39, v38 dst_sel:DWORD dst_unused:UNUSED_PAD src0_sel:DWORD src1_sel:WORD_1
	v_or_b32_sdwa v77, v41, v40 dst_sel:DWORD dst_unused:UNUSED_PAD src0_sel:DWORD src1_sel:WORD_1
	v_or_b32_sdwa v78, v43, v42 dst_sel:DWORD dst_unused:UNUSED_PAD src0_sel:DWORD src1_sel:WORD_1
	v_or_b32_sdwa v79, v45, v44 dst_sel:DWORD dst_unused:UNUSED_PAD src0_sel:DWORD src1_sel:WORD_1
	global_store_dwordx4 v58, v[76:79], s[56:57]
	s_waitcnt vmcnt(7) lgkmcnt(4)
	v_fmamk_f32 v54, v164, 0x3a800000, v13
	v_rsq_f32_e32 v54, v54
	v_add_u32_e32 v57, 0x80000, v4
	v_mul_f32_e32 v14, v14, v54
	v_mul_f32_e32 v15, v15, v54
	v_mul_f32_e32 v16, v16, v54
	v_mul_f32_e32 v17, v17, v54
	v_mul_f32_e32 v18, v18, v54
	v_mul_f32_e32 v19, v19, v54
	v_mul_f32_e32 v20, v20, v54
	v_mul_f32_e32 v21, v21, v54
	v_max_f32_e32 v14, 0, v14
	v_max_f32_e32 v15, 0, v15
	v_max_f32_e32 v16, 0, v16
	v_max_f32_e32 v17, 0, v17
	v_max_f32_e32 v18, 0, v18
	v_max_f32_e32 v19, 0, v19
	v_max_f32_e32 v20, 0, v20
	v_max_f32_e32 v21, 0, v21
	v_pk_mul_f32 v[14:15], v[14:15], v[14:15]
	v_pk_mul_f32 v[16:17], v[16:17], v[16:17]
	v_pk_mul_f32 v[18:19], v[18:19], v[18:19]
	v_pk_mul_f32 v[20:21], v[20:21], v[20:21]
	v_and_b32_sdwa v46, v14, v59 dst_sel:DWORD dst_unused:UNUSED_PAD src0_sel:WORD_1 src1_sel:DWORD
	v_and_b32_sdwa v47, v15, v59 dst_sel:DWORD dst_unused:UNUSED_PAD src0_sel:WORD_1 src1_sel:DWORD
	v_and_b32_sdwa v48, v16, v59 dst_sel:DWORD dst_unused:UNUSED_PAD src0_sel:WORD_1 src1_sel:DWORD
	v_and_b32_sdwa v49, v17, v59 dst_sel:DWORD dst_unused:UNUSED_PAD src0_sel:WORD_1 src1_sel:DWORD
	v_and_b32_sdwa v50, v18, v59 dst_sel:DWORD dst_unused:UNUSED_PAD src0_sel:WORD_1 src1_sel:DWORD
	v_and_b32_sdwa v51, v19, v59 dst_sel:DWORD dst_unused:UNUSED_PAD src0_sel:WORD_1 src1_sel:DWORD
	v_and_b32_sdwa v52, v20, v59 dst_sel:DWORD dst_unused:UNUSED_PAD src0_sel:WORD_1 src1_sel:DWORD
	v_and_b32_sdwa v53, v21, v59 dst_sel:DWORD dst_unused:UNUSED_PAD src0_sel:WORD_1 src1_sel:DWORD
	v_add3_u32 v14, v14, v46, s24
	v_add3_u32 v15, v15, v47, s24
	v_add3_u32 v16, v16, v48, s24
	v_add3_u32 v17, v17, v49, s24
	v_add3_u32 v18, v18, v50, s24
	v_add3_u32 v19, v19, v51, s24
	v_add3_u32 v20, v20, v52, s24
	v_add3_u32 v21, v21, v53, s24
	v_and_b32_e32 v15, 0xffff0000, v15
	v_and_b32_e32 v17, 0xffff0000, v17
	v_and_b32_e32 v19, 0xffff0000, v19
	v_and_b32_e32 v21, 0xffff0000, v21
	v_or_b32_sdwa v60, v15, v14 dst_sel:DWORD dst_unused:UNUSED_PAD src0_sel:DWORD src1_sel:WORD_1
	v_or_b32_sdwa v61, v17, v16 dst_sel:DWORD dst_unused:UNUSED_PAD src0_sel:DWORD src1_sel:WORD_1
	v_or_b32_sdwa v62, v19, v18 dst_sel:DWORD dst_unused:UNUSED_PAD src0_sel:DWORD src1_sel:WORD_1
	v_or_b32_sdwa v63, v21, v20 dst_sel:DWORD dst_unused:UNUSED_PAD src0_sel:DWORD src1_sel:WORD_1
	global_store_dwordx4 v57, v[60:63], s[56:57]
	v_add_u32_e32 v55, 0xc180, v103
	ds_read2_b32 v[30:31], v55 offset0:0 offset1:1
	ds_read2_b32 v[32:33], v55 offset0:2 offset1:3
	ds_read2_b32 v[34:35], v55 offset0:4 offset1:5
	ds_read2_b32 v[36:37], v55 offset0:6 offset1:7
	v_add_u32_e32 v56, 0xe1c0, v103
	ds_read2_b32 v[38:39], v56 offset0:0 offset1:1
	ds_read2_b32 v[40:41], v56 offset0:2 offset1:3
	ds_read2_b32 v[42:43], v56 offset0:4 offset1:5
	ds_read2_b32 v[44:45], v56 offset0:6 offset1:7
	s_waitcnt vmcnt(7) lgkmcnt(8)
	v_fmamk_f32 v54, v165, 0x3a800000, v13
	v_rsq_f32_e32 v54, v54
	v_add_u32_e32 v58, 0xa0000, v4
	v_mul_f32_e32 v22, v22, v54
	v_mul_f32_e32 v23, v23, v54
	v_mul_f32_e32 v24, v24, v54
	v_mul_f32_e32 v25, v25, v54
	v_mul_f32_e32 v26, v26, v54
	v_mul_f32_e32 v27, v27, v54
	v_mul_f32_e32 v28, v28, v54
	v_mul_f32_e32 v29, v29, v54
	v_max_f32_e32 v22, 0, v22
	v_max_f32_e32 v23, 0, v23
	v_max_f32_e32 v24, 0, v24
	v_max_f32_e32 v25, 0, v25
	v_max_f32_e32 v26, 0, v26
	v_max_f32_e32 v27, 0, v27
	v_max_f32_e32 v28, 0, v28
	v_max_f32_e32 v29, 0, v29
	v_pk_mul_f32 v[22:23], v[22:23], v[22:23]
	v_pk_mul_f32 v[24:25], v[24:25], v[24:25]
	v_pk_mul_f32 v[26:27], v[26:27], v[26:27]
	v_pk_mul_f32 v[28:29], v[28:29], v[28:29]
	v_and_b32_sdwa v46, v22, v59 dst_sel:DWORD dst_unused:UNUSED_PAD src0_sel:WORD_1 src1_sel:DWORD
	v_and_b32_sdwa v47, v23, v59 dst_sel:DWORD dst_unused:UNUSED_PAD src0_sel:WORD_1 src1_sel:DWORD
	v_and_b32_sdwa v48, v24, v59 dst_sel:DWORD dst_unused:UNUSED_PAD src0_sel:WORD_1 src1_sel:DWORD
	v_and_b32_sdwa v49, v25, v59 dst_sel:DWORD dst_unused:UNUSED_PAD src0_sel:WORD_1 src1_sel:DWORD
	v_and_b32_sdwa v50, v26, v59 dst_sel:DWORD dst_unused:UNUSED_PAD src0_sel:WORD_1 src1_sel:DWORD
	v_and_b32_sdwa v51, v27, v59 dst_sel:DWORD dst_unused:UNUSED_PAD src0_sel:WORD_1 src1_sel:DWORD
	v_and_b32_sdwa v52, v28, v59 dst_sel:DWORD dst_unused:UNUSED_PAD src0_sel:WORD_1 src1_sel:DWORD
	v_and_b32_sdwa v53, v29, v59 dst_sel:DWORD dst_unused:UNUSED_PAD src0_sel:WORD_1 src1_sel:DWORD
	v_add3_u32 v22, v22, v46, s24
	v_add3_u32 v23, v23, v47, s24
	v_add3_u32 v24, v24, v48, s24
	v_add3_u32 v25, v25, v49, s24
	v_add3_u32 v26, v26, v50, s24
	v_add3_u32 v27, v27, v51, s24
	v_add3_u32 v28, v28, v52, s24
	v_add3_u32 v29, v29, v53, s24
	v_and_b32_e32 v23, 0xffff0000, v23
	v_and_b32_e32 v25, 0xffff0000, v25
	v_and_b32_e32 v27, 0xffff0000, v27
	v_and_b32_e32 v29, 0xffff0000, v29
	v_or_b32_sdwa v76, v23, v22 dst_sel:DWORD dst_unused:UNUSED_PAD src0_sel:DWORD src1_sel:WORD_1
	v_or_b32_sdwa v77, v25, v24 dst_sel:DWORD dst_unused:UNUSED_PAD src0_sel:DWORD src1_sel:WORD_1
	v_or_b32_sdwa v78, v27, v26 dst_sel:DWORD dst_unused:UNUSED_PAD src0_sel:DWORD src1_sel:WORD_1
	v_or_b32_sdwa v79, v29, v28 dst_sel:DWORD dst_unused:UNUSED_PAD src0_sel:DWORD src1_sel:WORD_1
	global_store_dwordx4 v58, v[76:79], s[56:57]
	s_waitcnt vmcnt(7) lgkmcnt(4)
	v_fmamk_f32 v54, v166, 0x3a800000, v13
	v_rsq_f32_e32 v54, v54
	v_add_u32_e32 v57, 0xc0000, v4
	v_mul_f32_e32 v30, v30, v54
	v_mul_f32_e32 v31, v31, v54
	v_mul_f32_e32 v32, v32, v54
	v_mul_f32_e32 v33, v33, v54
	v_mul_f32_e32 v34, v34, v54
	v_mul_f32_e32 v35, v35, v54
	v_mul_f32_e32 v36, v36, v54
	v_mul_f32_e32 v37, v37, v54
	v_max_f32_e32 v30, 0, v30
	v_max_f32_e32 v31, 0, v31
	v_max_f32_e32 v32, 0, v32
	v_max_f32_e32 v33, 0, v33
	v_max_f32_e32 v34, 0, v34
	v_max_f32_e32 v35, 0, v35
	v_max_f32_e32 v36, 0, v36
	v_max_f32_e32 v37, 0, v37
	v_pk_mul_f32 v[30:31], v[30:31], v[30:31]
	v_pk_mul_f32 v[32:33], v[32:33], v[32:33]
	v_pk_mul_f32 v[34:35], v[34:35], v[34:35]
	v_pk_mul_f32 v[36:37], v[36:37], v[36:37]
	v_and_b32_sdwa v46, v30, v59 dst_sel:DWORD dst_unused:UNUSED_PAD src0_sel:WORD_1 src1_sel:DWORD
	v_and_b32_sdwa v47, v31, v59 dst_sel:DWORD dst_unused:UNUSED_PAD src0_sel:WORD_1 src1_sel:DWORD
	v_and_b32_sdwa v48, v32, v59 dst_sel:DWORD dst_unused:UNUSED_PAD src0_sel:WORD_1 src1_sel:DWORD
	v_and_b32_sdwa v49, v33, v59 dst_sel:DWORD dst_unused:UNUSED_PAD src0_sel:WORD_1 src1_sel:DWORD
	v_and_b32_sdwa v50, v34, v59 dst_sel:DWORD dst_unused:UNUSED_PAD src0_sel:WORD_1 src1_sel:DWORD
	v_and_b32_sdwa v51, v35, v59 dst_sel:DWORD dst_unused:UNUSED_PAD src0_sel:WORD_1 src1_sel:DWORD
	v_and_b32_sdwa v52, v36, v59 dst_sel:DWORD dst_unused:UNUSED_PAD src0_sel:WORD_1 src1_sel:DWORD
	v_and_b32_sdwa v53, v37, v59 dst_sel:DWORD dst_unused:UNUSED_PAD src0_sel:WORD_1 src1_sel:DWORD
	v_add3_u32 v30, v30, v46, s24
	v_add3_u32 v31, v31, v47, s24
	v_add3_u32 v32, v32, v48, s24
	v_add3_u32 v33, v33, v49, s24
	v_add3_u32 v34, v34, v50, s24
	v_add3_u32 v35, v35, v51, s24
	v_add3_u32 v36, v36, v52, s24
	v_add3_u32 v37, v37, v53, s24
	v_and_b32_e32 v31, 0xffff0000, v31
	v_and_b32_e32 v33, 0xffff0000, v33
	v_and_b32_e32 v35, 0xffff0000, v35
	v_and_b32_e32 v37, 0xffff0000, v37
	v_or_b32_sdwa v60, v31, v30 dst_sel:DWORD dst_unused:UNUSED_PAD src0_sel:DWORD src1_sel:WORD_1
	v_or_b32_sdwa v61, v33, v32 dst_sel:DWORD dst_unused:UNUSED_PAD src0_sel:DWORD src1_sel:WORD_1
	v_or_b32_sdwa v62, v35, v34 dst_sel:DWORD dst_unused:UNUSED_PAD src0_sel:DWORD src1_sel:WORD_1
	v_or_b32_sdwa v63, v37, v36 dst_sel:DWORD dst_unused:UNUSED_PAD src0_sel:DWORD src1_sel:WORD_1
	global_store_dwordx4 v57, v[60:63], s[56:57]
	s_waitcnt vmcnt(7) lgkmcnt(0)
	v_fmamk_f32 v54, v167, 0x3a800000, v13
	v_rsq_f32_e32 v54, v54
	v_add_u32_e32 v58, 0xe0000, v4
	v_mul_f32_e32 v38, v38, v54
	v_mul_f32_e32 v39, v39, v54
	v_mul_f32_e32 v40, v40, v54
	v_mul_f32_e32 v41, v41, v54
	v_mul_f32_e32 v42, v42, v54
	v_mul_f32_e32 v43, v43, v54
	v_mul_f32_e32 v44, v44, v54
	v_mul_f32_e32 v45, v45, v54
	v_max_f32_e32 v38, 0, v38
	v_max_f32_e32 v39, 0, v39
	v_max_f32_e32 v40, 0, v40
	v_max_f32_e32 v41, 0, v41
	v_max_f32_e32 v42, 0, v42
	v_max_f32_e32 v43, 0, v43
	v_max_f32_e32 v44, 0, v44
	v_max_f32_e32 v45, 0, v45
	v_pk_mul_f32 v[38:39], v[38:39], v[38:39]
	v_pk_mul_f32 v[40:41], v[40:41], v[40:41]
	v_pk_mul_f32 v[42:43], v[42:43], v[42:43]
	v_pk_mul_f32 v[44:45], v[44:45], v[44:45]
	v_and_b32_sdwa v46, v38, v59 dst_sel:DWORD dst_unused:UNUSED_PAD src0_sel:WORD_1 src1_sel:DWORD
	v_and_b32_sdwa v47, v39, v59 dst_sel:DWORD dst_unused:UNUSED_PAD src0_sel:WORD_1 src1_sel:DWORD
	v_and_b32_sdwa v48, v40, v59 dst_sel:DWORD dst_unused:UNUSED_PAD src0_sel:WORD_1 src1_sel:DWORD
	v_and_b32_sdwa v49, v41, v59 dst_sel:DWORD dst_unused:UNUSED_PAD src0_sel:WORD_1 src1_sel:DWORD
	v_and_b32_sdwa v50, v42, v59 dst_sel:DWORD dst_unused:UNUSED_PAD src0_sel:WORD_1 src1_sel:DWORD
	v_and_b32_sdwa v51, v43, v59 dst_sel:DWORD dst_unused:UNUSED_PAD src0_sel:WORD_1 src1_sel:DWORD
	v_and_b32_sdwa v52, v44, v59 dst_sel:DWORD dst_unused:UNUSED_PAD src0_sel:WORD_1 src1_sel:DWORD
	v_and_b32_sdwa v53, v45, v59 dst_sel:DWORD dst_unused:UNUSED_PAD src0_sel:WORD_1 src1_sel:DWORD
	v_add3_u32 v38, v38, v46, s24
	v_add3_u32 v39, v39, v47, s24
	v_add3_u32 v40, v40, v48, s24
	v_add3_u32 v41, v41, v49, s24
	v_add3_u32 v42, v42, v50, s24
	v_add3_u32 v43, v43, v51, s24
	v_add3_u32 v44, v44, v52, s24
	v_add3_u32 v45, v45, v53, s24
	v_and_b32_e32 v39, 0xffff0000, v39
	v_and_b32_e32 v41, 0xffff0000, v41
	v_and_b32_e32 v43, 0xffff0000, v43
	v_and_b32_e32 v45, 0xffff0000, v45
	v_or_b32_sdwa v76, v39, v38 dst_sel:DWORD dst_unused:UNUSED_PAD src0_sel:DWORD src1_sel:WORD_1
	v_or_b32_sdwa v77, v41, v40 dst_sel:DWORD dst_unused:UNUSED_PAD src0_sel:DWORD src1_sel:WORD_1
	v_or_b32_sdwa v78, v43, v42 dst_sel:DWORD dst_unused:UNUSED_PAD src0_sel:DWORD src1_sel:WORD_1
	v_or_b32_sdwa v79, v45, v44 dst_sel:DWORD dst_unused:UNUSED_PAD src0_sel:DWORD src1_sel:WORD_1
	global_store_dwordx4 v58, v[76:79], s[56:57]
	s_cmpk_lt_u32 s12, 0x400
	s_barrier
	s_cbranch_scc1 .LBB0_590
